# removed all s_setprio flips in the 8 GEMM K-loops
# speedup vs baseline: 1.0049x; 1.0049x over previous
;     __device__ bool next(int i, Unit& u) const { if (i != 0) return false; return so.next(round, u); }
;     __device__ __forceinline__ bool next(int i, Unit& u) const { if (i > 0 || !on) return false; u.pm = pm; u.pn = 0; return true; }
; #define PG8_STAGE(bufoff, gbase, voff) do { _Pragma("unroll") for (int _i = 0; _i < 2; ++_i) \
;         __builtin_amdgcn_global_load_lds((const unsigned*)((const char*)(gbase) + (voff)[_i]), (PG8_LAS unsigned*)(lds + (bufoff) + ldsw + _i * 8192), 16, 0, 0); } while (0)
; #define PG8_LDA(dst, b, h) do { _Pragma("unroll") for (int m = 0; m < 4; ++m) _Pragma("unroll") for (int k = 0; k < 2; ++k) dst[m][k] = *(const PG8_LAS bf16x8*)(lds + PG8_SA(b, h) + aoff + m * 2048 + k * 1024); } while (0)
; #define PG8_WAIT_V(n) asm volatile("s_waitcnt vmcnt(" #n ")" ::: "memory")
; #define PG8_WAIT_L(n) asm volatile("s_waitcnt lgkmcnt(" #n ")" ::: "memory")
; template <class Epi, class Sched, bool ALIGN_EPI = false, bool SP2 = false, bool MIDHOOK = false>
; __device__ __forceinline__ void gemm_phase(PG8_LAS unsigned char* lds, const Gemm g, const Sched& S, const Epi& E) {
;     ...
;         const bool has_next = S.next(ui + 1, nxt);
;         const char* nA = has_next ? (const char*)g.A + (size_t)nxt.pm * tstep : cA; const char* nB = has_next ? (const char*)g.Bt + (size_t)nxt.pn * tstep : cB;
;         for (int t = 0; t < nt; t += 2) {
;             if constexpr (MIDHOOK) { if (t == nt / 2) E.mid(acc, cur, wr, wc, fr, fq); }
;             const bool last = (t == nt - 2);
;             const char* a1 = cA + (size_t)(t + 1) * kstep;
;             const char* a2 = last ? nA : cA + (size_t)(t + 2) * kstep; const char* b2 = last ? nB : cB + (size_t)(t + 2) * kstep;
;             const char* a3 = a2 + kstep; const char* b3 = b2 + kstep;
;             if (last && has_next) S.a_ready(nxt);
;             if constexpr (SP2) {
;             PG8_LDB(B0, 0, 0); PG8_LDB(B1, 0, 1); PG8_SCHED; PG8_LDA(At, 0, 0); PG8_STAGE(PG8_SA(1, 1), a1 + hstep, voffA);
;             PG8_WAIT_V(8); PG8_WAIT_L(0); PG8_BAR; PG8_MMA(0, 0, At, B0); PG8_MMA(0, 1, At, B1); PG8_BAR; PG8_SCHED;
;             PG8_LDA(At, 0, 1); PG8_STAGE(PG8_SB(0, 0), b2, voffB); PG8_STAGE(PG8_SB(0, 1), b2 + hstep, voffB); PG8_STAGE(PG8_SA(0, 0), a2, voffA);
;             PG8_WAIT_V(8); PG8_WAIT_L(0); PG8_BAR; PG8_MMA(1, 0, At, B0); PG8_MMA(1, 1, At, B1); PG8_BAR; PG8_SCHED;
.LBB0_191:
	ds_read_b128 v[128:131], v180
	s_waitcnt vmcnt(0)
	ds_read_b128 v[132:135], v180 offset:1024
	ds_read_b128 v[136:139], v180 offset:2048
	ds_read_b128 v[168:171], v180 offset:3072
	ds_read_b128 v[172:175], v181
	ds_read_b128 v[184:187], v181 offset:1024
	ds_read_b128 v[188:191], v181 offset:2048
	ds_read_b128 v[192:195], v181 offset:3072
	s_add_u32 s8, s6, 0xfffc0080
	s_addc_u32 s9, s7, -1
	s_cmp_eq_u32 s65, 12
	s_cselect_b32 s49, s5, s9
	s_cselect_b32 s48, s41, s8
	s_cselect_b32 s9, s39, s64
	s_cselect_b32 s8, s62, s63
	v_lshl_add_u64 v[230:231], s[6:7], 0, v[156:157]
	s_add_i32 m0, s47, 0xc000
	ds_read_b128 v[196:199], v182
	ds_read_b128 v[200:203], v182 offset:1024
	ds_read_b128 v[204:207], v182 offset:2048
	ds_read_b128 v[208:211], v182 offset:3072
	ds_read_b128 v[212:215], v182 offset:4096
	ds_read_b128 v[216:219], v182 offset:5120
	ds_read_b128 v[222:225], v182 offset:6144
	ds_read_b128 v[226:229], v182 offset:7168
	global_load_lds_dwordx4 v[230:231], off
	v_lshl_add_u64 v[230:231], s[6:7], 0, v[158:159]
	s_add_i32 m0, s47, 0xe000
	s_nop 0
	global_load_lds_dwordx4 v[230:231], off
	s_waitcnt vmcnt(8)
	s_waitcnt lgkmcnt(0)
	s_barrier
	s_waitcnt lgkmcnt(0)
	v_mfma_f32_16x16x32_bf16 v[124:127], v[128:131], v[196:199], v[124:127]
	v_mfma_f32_16x16x32_bf16 v[116:119], v[136:139], v[196:199], v[116:119]
	v_mfma_f32_16x16x32_bf16 v[108:111], v[128:131], v[204:207], v[108:111]
	v_mfma_f32_16x16x32_bf16 v[100:103], v[136:139], v[204:207], v[100:103]
	v_mfma_f32_16x16x32_bf16 v[92:95], v[128:131], v[212:215], v[92:95]
	v_mfma_f32_16x16x32_bf16 v[84:87], v[136:139], v[212:215], v[84:87]
	v_mfma_f32_16x16x32_bf16 v[76:79], v[128:131], v[222:225], v[76:79]
	v_mfma_f32_16x16x32_bf16 v[68:71], v[136:139], v[222:225], v[68:71]
	v_mfma_f32_16x16x32_bf16 v[124:127], v[132:135], v[200:203], v[124:127]
	v_mfma_f32_16x16x32_bf16 v[116:119], v[168:171], v[200:203], v[116:119]
	v_mfma_f32_16x16x32_bf16 v[108:111], v[132:135], v[208:211], v[108:111]
	v_mfma_f32_16x16x32_bf16 v[100:103], v[168:171], v[208:211], v[100:103]
	v_mfma_f32_16x16x32_bf16 v[92:95], v[132:135], v[216:219], v[92:95]
	v_mfma_f32_16x16x32_bf16 v[84:87], v[168:171], v[216:219], v[84:87]
	v_mfma_f32_16x16x32_bf16 v[76:79], v[132:135], v[226:229], v[76:79]
	v_mfma_f32_16x16x32_bf16 v[68:71], v[168:171], v[226:229], v[68:71]
	v_mfma_f32_16x16x32_bf16 v[120:123], v[172:175], v[196:199], v[120:123]
	v_mfma_f32_16x16x32_bf16 v[112:115], v[188:191], v[196:199], v[112:115]
	v_mfma_f32_16x16x32_bf16 v[104:107], v[172:175], v[204:207], v[104:107]
	v_mfma_f32_16x16x32_bf16 v[96:99], v[188:191], v[204:207], v[96:99]
	v_mfma_f32_16x16x32_bf16 v[88:91], v[172:175], v[212:215], v[88:91]
	v_mfma_f32_16x16x32_bf16 v[80:83], v[188:191], v[212:215], v[80:83]
	v_mfma_f32_16x16x32_bf16 v[72:75], v[172:175], v[222:225], v[72:75]
	v_mfma_f32_16x16x32_bf16 v[64:67], v[188:191], v[222:225], v[64:67]
	v_mfma_f32_16x16x32_bf16 v[120:123], v[184:187], v[200:203], v[120:123]
	v_mfma_f32_16x16x32_bf16 v[112:115], v[192:195], v[200:203], v[112:115]
	v_mfma_f32_16x16x32_bf16 v[104:107], v[184:187], v[208:211], v[104:107]
	v_mfma_f32_16x16x32_bf16 v[96:99], v[192:195], v[208:211], v[96:99]
	v_mfma_f32_16x16x32_bf16 v[88:91], v[184:187], v[216:219], v[88:91]
	v_mfma_f32_16x16x32_bf16 v[80:83], v[192:195], v[216:219], v[80:83]
	v_mfma_f32_16x16x32_bf16 v[72:75], v[184:187], v[226:229], v[72:75]
	v_mfma_f32_16x16x32_bf16 v[64:67], v[192:195], v[226:229], v[64:67]
	s_barrier
	s_add_i32 s66, s58, s3
	v_lshl_add_u64 v[230:231], s[8:9], 0, v[142:143]
	s_mov_b32 m0, s66
	ds_read_b128 v[196:199], v182 offset:16384
	ds_read_b128 v[200:203], v182 offset:17408
	ds_read_b128 v[204:207], v182 offset:18432
	ds_read_b128 v[208:211], v182 offset:19456
	ds_read_b128 v[212:215], v182 offset:20480
	ds_read_b128 v[216:219], v182 offset:21504
	ds_read_b128 v[222:225], v182 offset:22528
	ds_read_b128 v[226:229], v182 offset:23552
	global_load_lds_dwordx4 v[230:231], off
	s_add_i32 m0, s66, 0x2000
	s_add_u32 s66, s8, 0x40000
	v_lshl_add_u64 v[232:233], s[8:9], 0, v[146:147]
	s_addc_u32 s67, s9, 0
	s_add_i32 s68, s59, s3
	global_load_lds_dwordx4 v[232:233], off
	v_lshl_add_u64 v[234:235], s[66:67], 0, v[142:143]
	s_mov_b32 m0, s68
	v_lshl_add_u64 v[236:237], s[48:49], 0, v[144:145]
	global_load_lds_dwordx4 v[234:235], off
	v_lshl_add_u64 v[234:235], s[66:67], 0, v[146:147]
	s_add_i32 m0, s68, 0x2000
	s_nop 0
	global_load_lds_dwordx4 v[234:235], off
	v_lshl_add_u64 v[234:235], s[48:49], 0, v[140:141]
	s_mov_b32 m0, s47
	s_nop 0
	global_load_lds_dwordx4 v[234:235], off
	s_mov_b32 m0, s50
	s_nop 0
	global_load_lds_dwordx4 v[236:237], off
	s_waitcnt vmcnt(8)
	s_waitcnt lgkmcnt(0)
	s_barrier
; #define PG8_STAGE(bufoff, gbase, voff) do { _Pragma("unroll") for (int _i = 0; _i < 2; ++_i) \
;         __builtin_amdgcn_global_load_lds((const unsigned*)((const char*)(gbase) + (voff)[_i]), (PG8_LAS unsigned*)(lds + (bufoff) + ldsw + _i * 8192), 16, 0, 0); } while (0)
; #define PG8_LDA(dst, b, h) do { _Pragma("unroll") for (int m = 0; m < 4; ++m) _Pragma("unroll") for (int k = 0; k < 2; ++k) dst[m][k] = *(const PG8_LAS bf16x8*)(lds + PG8_SA(b, h) + aoff + m * 2048 + k * 1024); } while (0)
; #define PG8_LDB(dst, b, h) do { _Pragma("unroll") for (int n = 0; n < 2; ++n) _Pragma("unroll") for (int k = 0; k < 2; ++k) dst[n][k] = *(const PG8_LAS bf16x8*)(lds + PG8_SB(b, h) + boff + n * 2048 + k * 1024); } while (0)
; #define PG8_MMA(ai, bj, At, Bt) do { __builtin_amdgcn_s_setprio(1); _Pragma("unroll") for (int m = 0; m < 4; ++m) _Pragma("unroll") for (int n = 0; n < 2; ++n) _Pragma("unroll") for (int k = 0; k < 2; ++k) \
;         acc[ai][bj][m][n] = __builtin_amdgcn_mfma_f32_16x16x32_bf16(Bt[n][k], At[m][k], acc[ai][bj][m][n], 0, 0, 0); __builtin_amdgcn_s_setprio(0); } while (0)
; #define PG8_WAIT_V(n) asm volatile("s_waitcnt vmcnt(" #n ")" ::: "memory")
; #define PG8_WAIT_L(n) asm volatile("s_waitcnt lgkmcnt(" #n ")" ::: "memory")
; template <class Epi, class Sched, bool ALIGN_EPI = false, bool SP2 = false, bool MIDHOOK = false>
; __device__ __forceinline__ void gemm_phase(PG8_LAS unsigned char* lds, const Gemm g, const Sched& S, const Epi& E) {
;     ...
;             PG8_WAIT_V(8); PG8_WAIT_L(0); PG8_BAR; PG8_MMA(0, 0, At, B0); PG8_MMA(0, 1, At, B1); PG8_BAR; PG8_SCHED;
;             PG8_LDA(At, 0, 1); PG8_STAGE(PG8_SB(0, 0), b2, voffB); PG8_STAGE(PG8_SB(0, 1), b2 + hstep, voffB); PG8_STAGE(PG8_SA(0, 0), a2, voffA);
;             PG8_WAIT_V(8); PG8_WAIT_L(0); PG8_BAR; PG8_MMA(1, 0, At, B0); PG8_MMA(1, 1, At, B1); PG8_BAR; PG8_SCHED;
;             PG8_LDB(B0, 1, 0); PG8_LDB(B1, 1, 1); PG8_SCHED; PG8_LDA(At, 1, 0); PG8_STAGE(PG8_SA(0, 1), a2 + hstep, voffA);
;             PG8_WAIT_V(8); PG8_WAIT_L(0); PG8_BAR; PG8_MMA(0, 0, At, B0); PG8_MMA(0, 1, At, B1); PG8_BAR; PG8_SCHED;
;             PG8_LDA(At, 1, 1); PG8_STAGE(PG8_SB(1, 0), b3, voffB); PG8_STAGE(PG8_SB(1, 1), b3 + hstep, voffB); PG8_STAGE(PG8_SA(1, 0), a3, voffA);
;             PG8_WAIT_V(8); PG8_WAIT_L(0); PG8_BAR; PG8_MMA(1, 0, At, B0); PG8_MMA(1, 1, At, B1); PG8_BAR; PG8_SCHED;
	s_waitcnt lgkmcnt(0)
	v_mfma_f32_16x16x32_bf16 v[60:63], v[128:131], v[196:199], v[60:63]
	v_mfma_f32_16x16x32_bf16 v[52:55], v[136:139], v[196:199], v[52:55]
	v_mfma_f32_16x16x32_bf16 v[44:47], v[128:131], v[204:207], v[44:47]
	v_mfma_f32_16x16x32_bf16 v[36:39], v[136:139], v[204:207], v[36:39]
	v_mfma_f32_16x16x32_bf16 v[28:31], v[128:131], v[212:215], v[28:31]
	v_mfma_f32_16x16x32_bf16 v[20:23], v[136:139], v[212:215], v[20:23]
	v_mfma_f32_16x16x32_bf16 v[12:15], v[128:131], v[222:225], v[12:15]
	v_mfma_f32_16x16x32_bf16 v[4:7], v[136:139], v[222:225], v[4:7]
	v_mfma_f32_16x16x32_bf16 v[60:63], v[132:135], v[200:203], v[60:63]
	v_mfma_f32_16x16x32_bf16 v[52:55], v[168:171], v[200:203], v[52:55]
	v_mfma_f32_16x16x32_bf16 v[44:47], v[132:135], v[208:211], v[44:47]
	v_mfma_f32_16x16x32_bf16 v[36:39], v[168:171], v[208:211], v[36:39]
	v_mfma_f32_16x16x32_bf16 v[28:31], v[132:135], v[216:219], v[28:31]
	v_mfma_f32_16x16x32_bf16 v[20:23], v[168:171], v[216:219], v[20:23]
	v_mfma_f32_16x16x32_bf16 v[12:15], v[132:135], v[226:229], v[12:15]
	v_mfma_f32_16x16x32_bf16 v[4:7], v[168:171], v[226:229], v[4:7]
	v_mfma_f32_16x16x32_bf16 v[56:59], v[172:175], v[196:199], v[56:59]
	v_mfma_f32_16x16x32_bf16 v[48:51], v[188:191], v[196:199], v[48:51]
	v_mfma_f32_16x16x32_bf16 v[40:43], v[172:175], v[204:207], v[40:43]
	v_mfma_f32_16x16x32_bf16 v[32:35], v[188:191], v[204:207], v[32:35]
	v_mfma_f32_16x16x32_bf16 v[24:27], v[172:175], v[212:215], v[24:27]
	v_mfma_f32_16x16x32_bf16 v[16:19], v[188:191], v[212:215], v[16:19]
	v_mfma_f32_16x16x32_bf16 v[8:11], v[172:175], v[222:225], v[8:11]
	v_mfma_f32_16x16x32_bf16 v[0:3], v[188:191], v[222:225], v[0:3]
	v_mfma_f32_16x16x32_bf16 v[56:59], v[184:187], v[200:203], v[56:59]
	v_mfma_f32_16x16x32_bf16 v[48:51], v[192:195], v[200:203], v[48:51]
	v_mfma_f32_16x16x32_bf16 v[40:43], v[184:187], v[208:211], v[40:43]
	v_mfma_f32_16x16x32_bf16 v[32:35], v[192:195], v[208:211], v[32:35]
	v_mfma_f32_16x16x32_bf16 v[24:27], v[184:187], v[216:219], v[24:27]
	v_mfma_f32_16x16x32_bf16 v[16:19], v[192:195], v[216:219], v[16:19]
	v_mfma_f32_16x16x32_bf16 v[8:11], v[184:187], v[226:229], v[8:11]
	v_mfma_f32_16x16x32_bf16 v[0:3], v[192:195], v[226:229], v[0:3]
	s_barrier
	s_add_i32 s66, 0, 0x18000
	v_add_u32_e32 v148, s66, v177
	s_add_i32 s67, 0, 0x1c000
	ds_read_b128 v[128:131], v148
	ds_read_b128 v[132:135], v148 offset:1024
	ds_read_b128 v[136:139], v148 offset:2048
	ds_read_b128 v[168:171], v148 offset:3072
	v_add_u32_e32 v148, s67, v177
	ds_read_b128 v[172:175], v148
	ds_read_b128 v[184:187], v148 offset:1024
	ds_read_b128 v[188:191], v148 offset:2048
	ds_read_b128 v[192:195], v148 offset:3072
	s_add_u32 s48, s48, 0x40000
	s_addc_u32 s49, s49, 0
	s_mov_b32 m0, s51
	v_lshl_add_u64 v[238:239], s[48:49], 0, v[140:141]
	ds_read_b128 v[196:199], v182 offset:32768
	ds_read_b128 v[200:203], v182 offset:33792
	ds_read_b128 v[204:207], v182 offset:34816
	ds_read_b128 v[208:211], v182 offset:35840
	ds_read_b128 v[212:215], v182 offset:36864
	ds_read_b128 v[216:219], v182 offset:37888
	ds_read_b128 v[222:225], v182 offset:38912
	ds_read_b128 v[226:229], v182 offset:39936
	global_load_lds_dwordx4 v[238:239], off
	v_lshl_add_u64 v[238:239], s[48:49], 0, v[144:145]
	s_mov_b32 m0, s52
	s_nop 0
	global_load_lds_dwordx4 v[238:239], off
	s_waitcnt vmcnt(8)
	s_waitcnt lgkmcnt(0)
	s_barrier
	s_waitcnt lgkmcnt(0)
	v_mfma_f32_16x16x32_bf16 v[124:127], v[128:131], v[196:199], v[124:127]
	v_mfma_f32_16x16x32_bf16 v[116:119], v[136:139], v[196:199], v[116:119]
	v_mfma_f32_16x16x32_bf16 v[108:111], v[128:131], v[204:207], v[108:111]
	v_mfma_f32_16x16x32_bf16 v[100:103], v[136:139], v[204:207], v[100:103]
	v_mfma_f32_16x16x32_bf16 v[92:95], v[128:131], v[212:215], v[92:95]
	v_mfma_f32_16x16x32_bf16 v[84:87], v[136:139], v[212:215], v[84:87]
	v_mfma_f32_16x16x32_bf16 v[76:79], v[128:131], v[222:225], v[76:79]
	v_mfma_f32_16x16x32_bf16 v[68:71], v[136:139], v[222:225], v[68:71]
	v_mfma_f32_16x16x32_bf16 v[124:127], v[132:135], v[200:203], v[124:127]
	v_mfma_f32_16x16x32_bf16 v[116:119], v[168:171], v[200:203], v[116:119]
	v_mfma_f32_16x16x32_bf16 v[108:111], v[132:135], v[208:211], v[108:111]
	v_mfma_f32_16x16x32_bf16 v[100:103], v[168:171], v[208:211], v[100:103]
	v_mfma_f32_16x16x32_bf16 v[92:95], v[132:135], v[216:219], v[92:95]
	v_mfma_f32_16x16x32_bf16 v[84:87], v[168:171], v[216:219], v[84:87]
	v_mfma_f32_16x16x32_bf16 v[76:79], v[132:135], v[226:229], v[76:79]
	v_mfma_f32_16x16x32_bf16 v[68:71], v[168:171], v[226:229], v[68:71]
	v_mfma_f32_16x16x32_bf16 v[120:123], v[172:175], v[196:199], v[120:123]
	v_mfma_f32_16x16x32_bf16 v[112:115], v[188:191], v[196:199], v[112:115]
	v_mfma_f32_16x16x32_bf16 v[104:107], v[172:175], v[204:207], v[104:107]
	v_mfma_f32_16x16x32_bf16 v[96:99], v[188:191], v[204:207], v[96:99]
	v_mfma_f32_16x16x32_bf16 v[88:91], v[172:175], v[212:215], v[88:91]
	v_mfma_f32_16x16x32_bf16 v[80:83], v[188:191], v[212:215], v[80:83]
	v_mfma_f32_16x16x32_bf16 v[72:75], v[172:175], v[222:225], v[72:75]
	v_mfma_f32_16x16x32_bf16 v[64:67], v[188:191], v[222:225], v[64:67]
	v_mfma_f32_16x16x32_bf16 v[120:123], v[184:187], v[200:203], v[120:123]
	v_mfma_f32_16x16x32_bf16 v[112:115], v[192:195], v[200:203], v[112:115]
	v_mfma_f32_16x16x32_bf16 v[104:107], v[184:187], v[208:211], v[104:107]
	v_mfma_f32_16x16x32_bf16 v[96:99], v[192:195], v[208:211], v[96:99]
	v_mfma_f32_16x16x32_bf16 v[88:91], v[184:187], v[216:219], v[88:91]
	v_mfma_f32_16x16x32_bf16 v[80:83], v[192:195], v[216:219], v[80:83]
	v_mfma_f32_16x16x32_bf16 v[72:75], v[184:187], v[226:229], v[72:75]
	v_mfma_f32_16x16x32_bf16 v[64:67], v[192:195], v[226:229], v[64:67]
	s_barrier
; #define PG8_STAGE(bufoff, gbase, voff) do { _Pragma("unroll") for (int _i = 0; _i < 2; ++_i) \
;         __builtin_amdgcn_global_load_lds((const unsigned*)((const char*)(gbase) + (voff)[_i]), (PG8_LAS unsigned*)(lds + (bufoff) + ldsw + _i * 8192), 16, 0, 0); } while (0)
; #define PG8_LDA(dst, b, h) do { _Pragma("unroll") for (int m = 0; m < 4; ++m) _Pragma("unroll") for (int k = 0; k < 2; ++k) dst[m][k] = *(const PG8_LAS bf16x8*)(lds + PG8_SA(b, h) + aoff + m * 2048 + k * 1024); } while (0)
; #define PG8_MMA(ai, bj, At, Bt) do { __builtin_amdgcn_s_setprio(1); _Pragma("unroll") for (int m = 0; m < 4; ++m) _Pragma("unroll") for (int n = 0; n < 2; ++n) _Pragma("unroll") for (int k = 0; k < 2; ++k) \
;         acc[ai][bj][m][n] = __builtin_amdgcn_mfma_f32_16x16x32_bf16(Bt[n][k], At[m][k], acc[ai][bj][m][n], 0, 0, 0); __builtin_amdgcn_s_setprio(0); } while (0)
; #define PG8_WAIT_V(n) asm volatile("s_waitcnt vmcnt(" #n ")" ::: "memory")
; #define PG8_WAIT_L(n) asm volatile("s_waitcnt lgkmcnt(" #n ")" ::: "memory")
; #define PG8_BAR __builtin_amdgcn_s_barrier()
; #define PG8_SCHED __builtin_amdgcn_sched_barrier(0)
; template <class Epi, class Sched, bool ALIGN_EPI = false, bool SP2 = false, bool MIDHOOK = false>
; __device__ __forceinline__ void gemm_phase(PG8_LAS unsigned char* lds, const Gemm g, const Sched& S, const Epi& E) {
;     ...
;             PG8_LDA(At, 1, 1); PG8_STAGE(PG8_SB(1, 0), b3, voffB); PG8_STAGE(PG8_SB(1, 1), b3 + hstep, voffB); PG8_STAGE(PG8_SA(1, 0), a3, voffA);
;             PG8_WAIT_V(8); PG8_WAIT_L(0); PG8_BAR; PG8_MMA(1, 0, At, B0); PG8_MMA(1, 1, At, B1); PG8_BAR; PG8_SCHED;
;     ...
;         if constexpr (ALIGN_EPI) { if (wr == 0) PG8_BAR; }
;         if constexpr (!Epi::AFTER_DRAIN) { E(acc, cur, wr, wc, fr, fq); S.done(cur); }
;         if (!has_next) break;
	s_add_i32 s48, s66, s3
	v_lshl_add_u64 v[230:231], v[230:231], 0, s[34:35]
	s_mov_b32 m0, s48
	ds_read_b128 v[196:199], v182 offset:49152
	ds_read_b128 v[200:203], v182 offset:50176
	ds_read_b128 v[204:207], v182 offset:51200
	ds_read_b128 v[208:211], v182 offset:52224
	ds_read_b128 v[212:215], v182 offset:53248
	ds_read_b128 v[216:219], v182 offset:54272
	ds_read_b128 v[222:225], v182 offset:55296
	ds_read_b128 v[226:229], v182 offset:56320
	global_load_lds_dwordx4 v[230:231], off
	s_add_i32 m0, s48, 0x2000
	s_add_u32 s8, s8, 0x40080
	v_lshl_add_u64 v[230:231], v[232:233], 0, s[34:35]
	s_addc_u32 s9, s9, 0
	s_add_i32 s48, s67, s3
	global_load_lds_dwordx4 v[230:231], off
	v_lshl_add_u64 v[230:231], s[8:9], 0, v[142:143]
	s_mov_b32 m0, s48
	s_nop 0
	global_load_lds_dwordx4 v[230:231], off
	v_lshl_add_u64 v[230:231], s[8:9], 0, v[146:147]
	s_add_i32 m0, s48, 0x2000
	s_nop 0
	global_load_lds_dwordx4 v[230:231], off
	v_lshl_add_u64 v[230:231], v[234:235], 0, s[34:35]
	s_mov_b32 m0, s54
	s_nop 0
	global_load_lds_dwordx4 v[230:231], off
	v_lshl_add_u64 v[230:231], v[236:237], 0, s[34:35]
	s_mov_b32 m0, s55
	s_nop 0
	global_load_lds_dwordx4 v[230:231], off
	s_waitcnt vmcnt(8)
	s_waitcnt lgkmcnt(0)
	s_barrier
	s_waitcnt lgkmcnt(0)
	v_mfma_f32_16x16x32_bf16 v[60:63], v[128:131], v[196:199], v[60:63]
	v_mfma_f32_16x16x32_bf16 v[52:55], v[136:139], v[196:199], v[52:55]
	v_mfma_f32_16x16x32_bf16 v[44:47], v[128:131], v[204:207], v[44:47]
	v_mfma_f32_16x16x32_bf16 v[36:39], v[136:139], v[204:207], v[36:39]
	v_mfma_f32_16x16x32_bf16 v[28:31], v[128:131], v[212:215], v[28:31]
	v_mfma_f32_16x16x32_bf16 v[20:23], v[136:139], v[212:215], v[20:23]
	v_mfma_f32_16x16x32_bf16 v[12:15], v[128:131], v[222:225], v[12:15]
	v_mfma_f32_16x16x32_bf16 v[4:7], v[136:139], v[222:225], v[4:7]
	v_mfma_f32_16x16x32_bf16 v[60:63], v[132:135], v[200:203], v[60:63]
	v_mfma_f32_16x16x32_bf16 v[52:55], v[168:171], v[200:203], v[52:55]
	v_mfma_f32_16x16x32_bf16 v[44:47], v[132:135], v[208:211], v[44:47]
	v_mfma_f32_16x16x32_bf16 v[36:39], v[168:171], v[208:211], v[36:39]
	v_mfma_f32_16x16x32_bf16 v[28:31], v[132:135], v[216:219], v[28:31]
	v_mfma_f32_16x16x32_bf16 v[20:23], v[168:171], v[216:219], v[20:23]
	v_mfma_f32_16x16x32_bf16 v[12:15], v[132:135], v[226:229], v[12:15]
	v_mfma_f32_16x16x32_bf16 v[4:7], v[168:171], v[226:229], v[4:7]
	v_mfma_f32_16x16x32_bf16 v[56:59], v[172:175], v[196:199], v[56:59]
	v_mfma_f32_16x16x32_bf16 v[48:51], v[188:191], v[196:199], v[48:51]
	v_mfma_f32_16x16x32_bf16 v[40:43], v[172:175], v[204:207], v[40:43]
	v_mfma_f32_16x16x32_bf16 v[32:35], v[188:191], v[204:207], v[32:35]
	v_mfma_f32_16x16x32_bf16 v[24:27], v[172:175], v[212:215], v[24:27]
	v_mfma_f32_16x16x32_bf16 v[16:19], v[188:191], v[212:215], v[16:19]
	v_mfma_f32_16x16x32_bf16 v[8:11], v[172:175], v[222:225], v[8:11]
	v_mfma_f32_16x16x32_bf16 v[0:3], v[188:191], v[222:225], v[0:3]
	v_mfma_f32_16x16x32_bf16 v[56:59], v[184:187], v[200:203], v[56:59]
	v_mfma_f32_16x16x32_bf16 v[48:51], v[192:195], v[200:203], v[48:51]
	v_mfma_f32_16x16x32_bf16 v[40:43], v[184:187], v[208:211], v[40:43]
	v_mfma_f32_16x16x32_bf16 v[32:35], v[192:195], v[208:211], v[32:35]
	v_mfma_f32_16x16x32_bf16 v[24:27], v[184:187], v[216:219], v[24:27]
	v_mfma_f32_16x16x32_bf16 v[16:19], v[192:195], v[216:219], v[16:19]
	v_mfma_f32_16x16x32_bf16 v[8:11], v[184:187], v[226:229], v[8:11]
	v_mfma_f32_16x16x32_bf16 v[0:3], v[192:195], v[226:229], v[0:3]
	s_barrier
	s_add_i32 s65, s65, 2
	s_add_u32 s6, s6, 0x100
	s_addc_u32 s7, s7, 0
	s_add_u32 s63, s63, 0x100
	s_addc_u32 s64, s64, 0
	s_cmp_gt_u32 s65, 13
	s_cbranch_scc0 .LBB0_191
	s_and_b64 vcc, exec, s[36:37]
	s_cbranch_vccz .LBB0_194
	s_barrier

; #define PG8_STAGE(bufoff, gbase, voff) do { _Pragma("unroll") for (int _i = 0; _i < 2; ++_i) \
;         __builtin_amdgcn_global_load_lds((const unsigned*)((const char*)(gbase) + (voff)[_i]), (PG8_LAS unsigned*)(lds + (bufoff) + ldsw + _i * 8192), 16, 0, 0); } while (0)
; #define PG8_LDA(dst, b, h) do { _Pragma("unroll") for (int m = 0; m < 4; ++m) _Pragma("unroll") for (int k = 0; k < 2; ++k) dst[m][k] = *(const PG8_LAS bf16x8*)(lds + PG8_SA(b, h) + aoff + m * 2048 + k * 1024); } while (0)
; #define PG8_LDB(dst, b, h) do { _Pragma("unroll") for (int n = 0; n < 2; ++n) _Pragma("unroll") for (int k = 0; k < 2; ++k) dst[n][k] = *(const PG8_LAS bf16x8*)(lds + PG8_SB(b, h) + boff + n * 2048 + k * 1024); } while (0)
; #define PG8_WAIT_V(n) asm volatile("s_waitcnt vmcnt(" #n ")" ::: "memory")
; #define PG8_WAIT_L(n) asm volatile("s_waitcnt lgkmcnt(" #n ")" ::: "memory")
; template <class Epi, class Sched, bool ALIGN_EPI = false, bool SP2 = false, bool MIDHOOK = false>
; __device__ __forceinline__ void gemm_phase(PG8_LAS unsigned char* lds, const Gemm g, const Sched& S, const Epi& E) {
;     ...
;         for (int t = 0; t < nt; t += 2) {
;             if constexpr (MIDHOOK) { if (t == nt / 2) E.mid(acc, cur, wr, wc, fr, fq); }
;             const bool last = (t == nt - 2);
;             const char* a1 = cA + (size_t)(t + 1) * kstep;
;             const char* a2 = last ? nA : cA + (size_t)(t + 2) * kstep; const char* b2 = last ? nB : cB + (size_t)(t + 2) * kstep;
;             const char* a3 = a2 + kstep; const char* b3 = b2 + kstep;
;             if (last && has_next) S.a_ready(nxt);
;             if constexpr (SP2) {
;             PG8_LDB(B0, 0, 0); PG8_LDB(B1, 0, 1); PG8_SCHED; PG8_LDA(At, 0, 0); PG8_STAGE(PG8_SA(1, 1), a1 + hstep, voffA);
;             PG8_WAIT_V(8); PG8_WAIT_L(0); PG8_BAR; PG8_MMA(0, 0, At, B0); PG8_MMA(0, 1, At, B1); PG8_BAR; PG8_SCHED;
;             PG8_LDA(At, 0, 1); PG8_STAGE(PG8_SB(0, 0), b2, voffB); PG8_STAGE(PG8_SB(0, 1), b2 + hstep, voffB); PG8_STAGE(PG8_SA(0, 0), a2, voffA);
;             PG8_WAIT_V(8); PG8_WAIT_L(0); PG8_BAR; PG8_MMA(1, 0, At, B0); PG8_MMA(1, 1, At, B1); PG8_BAR; PG8_SCHED;
;             PG8_LDB(B0, 1, 0); PG8_LDB(B1, 1, 1); PG8_SCHED; PG8_LDA(At, 1, 0); PG8_STAGE(PG8_SA(0, 1), a2 + hstep, voffA);
;             PG8_WAIT_V(8); PG8_WAIT_L(0); PG8_BAR; PG8_MMA(0, 0, At, B0); PG8_MMA(0, 1, At, B1); PG8_BAR; PG8_SCHED;
.LBB0_374:
	s_add_u32 s30, s24, s28
	s_addc_u32 s31, s25, s29
	s_add_u32 s30, s30, 0x17000100
	ds_read_b128 v[82:85], v78
	ds_read_b128 v[86:89], v78 offset:1024
	ds_read_b128 v[90:93], v78 offset:2048
	ds_read_b128 v[94:97], v78 offset:3072
	s_addc_u32 s31, s31, 0
	s_add_u32 s34, s46, s28
	s_addc_u32 s35, s47, s29
	s_add_u32 s55, s34, 0xb00100
	s_addc_u32 s56, s35, 0
	s_cmpk_eq_i32 s28, 0x300
	s_cselect_b32 s35, s7, s31
	s_cselect_b32 s34, s6, s30
	s_cselect_b32 s31, s5, s56
	s_cselect_b32 s30, s4, s55
	s_mov_b32 m0, s49
	v_lshl_add_u64 v[130:131], v[72:73], 0, s[28:29]
	ds_read_b128 v[98:101], v79
	ds_read_b128 v[102:105], v79 offset:1024
	ds_read_b128 v[106:109], v79 offset:2048
	ds_read_b128 v[110:113], v79 offset:3072
	ds_read_b128 v[114:117], v79 offset:4096
	ds_read_b128 v[118:121], v79 offset:5120
	ds_read_b128 v[122:125], v79 offset:6144
	ds_read_b128 v[126:129], v79 offset:7168
	global_load_lds_dwordx4 v[130:131], off
	v_lshl_add_u64 v[130:131], v[74:75], 0, s[28:29]
	s_mov_b32 m0, s50
	s_nop 0
	global_load_lds_dwordx4 v[130:131], off
	s_waitcnt vmcnt(8)
	s_waitcnt lgkmcnt(0)
	s_barrier
	s_waitcnt lgkmcnt(0)
	v_mfma_f32_16x16x32_bf16 v[60:63], v[82:85], v[98:101], v[60:63]
	v_mfma_f32_16x16x32_bf16 v[56:59], v[90:93], v[98:101], v[56:59]
	v_mfma_f32_16x16x32_bf16 v[52:55], v[82:85], v[106:109], v[52:55]
	v_mfma_f32_16x16x32_bf16 v[48:51], v[90:93], v[106:109], v[48:51]
	v_mfma_f32_16x16x32_bf16 v[44:47], v[82:85], v[114:117], v[44:47]
	v_mfma_f32_16x16x32_bf16 v[40:43], v[90:93], v[114:117], v[40:43]
	v_mfma_f32_16x16x32_bf16 v[36:39], v[82:85], v[122:125], v[36:39]
	v_mfma_f32_16x16x32_bf16 v[32:35], v[90:93], v[122:125], v[32:35]
	v_mfma_f32_16x16x32_bf16 v[60:63], v[86:89], v[102:105], v[60:63]
	v_mfma_f32_16x16x32_bf16 v[56:59], v[94:97], v[102:105], v[56:59]
	v_mfma_f32_16x16x32_bf16 v[52:55], v[86:89], v[110:113], v[52:55]
	v_mfma_f32_16x16x32_bf16 v[48:51], v[94:97], v[110:113], v[48:51]
	v_mfma_f32_16x16x32_bf16 v[44:47], v[86:89], v[118:121], v[44:47]
	v_mfma_f32_16x16x32_bf16 v[40:43], v[94:97], v[118:121], v[40:43]
	v_mfma_f32_16x16x32_bf16 v[36:39], v[86:89], v[126:129], v[36:39]
	v_mfma_f32_16x16x32_bf16 v[32:35], v[94:97], v[126:129], v[32:35]
	s_barrier
	s_mov_b32 m0, s51
	v_lshl_add_u64 v[130:131], s[30:31], 0, v[68:69]
	s_add_u32 s56, s30, 0x40000
	ds_read_b128 v[98:101], v79 offset:16384
	ds_read_b128 v[102:105], v79 offset:17408
	ds_read_b128 v[106:109], v79 offset:18432
	ds_read_b128 v[110:113], v79 offset:19456
	ds_read_b128 v[114:117], v79 offset:20480
	ds_read_b128 v[118:121], v79 offset:21504
	ds_read_b128 v[122:125], v79 offset:22528
	ds_read_b128 v[126:129], v79 offset:23552
	global_load_lds_dwordx4 v[130:131], off
	v_lshl_add_u64 v[132:133], s[30:31], 0, v[64:65]
	s_mov_b32 m0, s52
	s_addc_u32 s57, s31, 0
	global_load_lds_dwordx4 v[132:133], off
	v_lshl_add_u64 v[134:135], s[56:57], 0, v[68:69]
	s_mov_b32 m0, s36
	v_lshl_add_u64 v[136:137], s[34:35], 0, v[66:67]
	global_load_lds_dwordx4 v[134:135], off
	v_lshl_add_u64 v[134:135], s[56:57], 0, v[64:65]
	s_mov_b32 m0, s37
	s_nop 0
	global_load_lds_dwordx4 v[134:135], off
	v_lshl_add_u64 v[134:135], s[34:35], 0, v[70:71]
	s_mov_b32 m0, s1
	s_nop 0
	global_load_lds_dwordx4 v[134:135], off
	s_mov_b32 m0, s38
	s_nop 0
	global_load_lds_dwordx4 v[136:137], off
	s_waitcnt vmcnt(8)
	s_waitcnt lgkmcnt(0)
	s_barrier
	s_waitcnt lgkmcnt(0)
	v_mfma_f32_16x16x32_bf16 v[28:31], v[82:85], v[98:101], v[28:31]
	v_mfma_f32_16x16x32_bf16 v[24:27], v[90:93], v[98:101], v[24:27]
	v_mfma_f32_16x16x32_bf16 v[20:23], v[82:85], v[106:109], v[20:23]
	v_mfma_f32_16x16x32_bf16 v[16:19], v[90:93], v[106:109], v[16:19]
	v_mfma_f32_16x16x32_bf16 v[12:15], v[82:85], v[114:117], v[12:15]
	v_mfma_f32_16x16x32_bf16 v[8:11], v[90:93], v[114:117], v[8:11]
	v_mfma_f32_16x16x32_bf16 v[4:7], v[82:85], v[122:125], v[4:7]
	v_mfma_f32_16x16x32_bf16 v[0:3], v[90:93], v[122:125], v[0:3]
	v_mfma_f32_16x16x32_bf16 v[28:31], v[86:89], v[102:105], v[28:31]
	v_mfma_f32_16x16x32_bf16 v[24:27], v[94:97], v[102:105], v[24:27]
	v_mfma_f32_16x16x32_bf16 v[20:23], v[86:89], v[110:113], v[20:23]
	v_mfma_f32_16x16x32_bf16 v[16:19], v[94:97], v[110:113], v[16:19]
	v_mfma_f32_16x16x32_bf16 v[12:15], v[86:89], v[118:121], v[12:15]
	v_mfma_f32_16x16x32_bf16 v[8:11], v[94:97], v[118:121], v[8:11]
	v_mfma_f32_16x16x32_bf16 v[4:7], v[86:89], v[126:129], v[4:7]
	v_mfma_f32_16x16x32_bf16 v[0:3], v[94:97], v[126:129], v[0:3]
	s_barrier
; #define PG8_STAGE(bufoff, gbase, voff) do { _Pragma("unroll") for (int _i = 0; _i < 2; ++_i) \
;         __builtin_amdgcn_global_load_lds((const unsigned*)((const char*)(gbase) + (voff)[_i]), (PG8_LAS unsigned*)(lds + (bufoff) + ldsw + _i * 8192), 16, 0, 0); } while (0)
; #define PG8_LDA(dst, b, h) do { _Pragma("unroll") for (int m = 0; m < 4; ++m) _Pragma("unroll") for (int k = 0; k < 2; ++k) dst[m][k] = *(const PG8_LAS bf16x8*)(lds + PG8_SA(b, h) + aoff + m * 2048 + k * 1024); } while (0)
; #define PG8_LDB(dst, b, h) do { _Pragma("unroll") for (int n = 0; n < 2; ++n) _Pragma("unroll") for (int k = 0; k < 2; ++k) dst[n][k] = *(const PG8_LAS bf16x8*)(lds + PG8_SB(b, h) + boff + n * 2048 + k * 1024); } while (0)
; #define PG8_MMA(ai, bj, At, Bt) do { __builtin_amdgcn_s_setprio(1); _Pragma("unroll") for (int m = 0; m < 4; ++m) _Pragma("unroll") for (int n = 0; n < 2; ++n) _Pragma("unroll") for (int k = 0; k < 2; ++k) \
;         acc[ai][bj][m][n] = __builtin_amdgcn_mfma_f32_16x16x32_bf16(Bt[n][k], At[m][k], acc[ai][bj][m][n], 0, 0, 0); __builtin_amdgcn_s_setprio(0); } while (0)
; #define PG8_WAIT_V(n) asm volatile("s_waitcnt vmcnt(" #n ")" ::: "memory")
; #define PG8_WAIT_L(n) asm volatile("s_waitcnt lgkmcnt(" #n ")" ::: "memory")
; #define PG8_BAR __builtin_amdgcn_s_barrier()
; #define PG8_SCHED __builtin_amdgcn_sched_barrier(0)
; template <class Epi, class Sched, bool ALIGN_EPI = false, bool SP2 = false, bool MIDHOOK = false>
; __device__ __forceinline__ void gemm_phase(PG8_LAS unsigned char* lds, const Gemm g, const Sched& S, const Epi& E) {
;     ...
;             PG8_LDB(B0, 1, 0); PG8_LDB(B1, 1, 1); PG8_SCHED; PG8_LDA(At, 1, 0); PG8_STAGE(PG8_SA(0, 1), a2 + hstep, voffA);
;             PG8_WAIT_V(8); PG8_WAIT_L(0); PG8_BAR; PG8_MMA(0, 0, At, B0); PG8_MMA(0, 1, At, B1); PG8_BAR; PG8_SCHED;
;             PG8_LDA(At, 1, 1); PG8_STAGE(PG8_SB(1, 0), b3, voffB); PG8_STAGE(PG8_SB(1, 1), b3 + hstep, voffB); PG8_STAGE(PG8_SA(1, 0), a3, voffA);
;             PG8_WAIT_V(8); PG8_WAIT_L(0); PG8_BAR; PG8_MMA(1, 0, At, B0); PG8_MMA(1, 1, At, B1); PG8_BAR; PG8_SCHED;
;     ...
;         if constexpr (ALIGN_EPI) { if (wr == 0) PG8_BAR; }
	ds_read_b128 v[82:85], v80
	ds_read_b128 v[86:89], v80 offset:1024
	ds_read_b128 v[90:93], v80 offset:2048
	ds_read_b128 v[94:97], v80 offset:3072
	s_add_u32 s34, s34, 0x40000
	s_addc_u32 s35, s35, 0
	s_mov_b32 m0, s40
	v_lshl_add_u64 v[138:139], s[34:35], 0, v[70:71]
	ds_read_b128 v[98:101], v79 offset:32768
	ds_read_b128 v[102:105], v79 offset:33792
	ds_read_b128 v[106:109], v79 offset:34816
	ds_read_b128 v[110:113], v79 offset:35840
	ds_read_b128 v[114:117], v79 offset:36864
	ds_read_b128 v[118:121], v79 offset:37888
	ds_read_b128 v[122:125], v79 offset:38912
	ds_read_b128 v[126:129], v79 offset:39936
	global_load_lds_dwordx4 v[138:139], off
	v_lshl_add_u64 v[138:139], s[34:35], 0, v[66:67]
	s_mov_b32 m0, s41
	s_nop 0
	global_load_lds_dwordx4 v[138:139], off
	s_waitcnt vmcnt(8)
	s_waitcnt lgkmcnt(0)
	s_barrier
	s_waitcnt lgkmcnt(0)
	v_mfma_f32_16x16x32_bf16 v[60:63], v[82:85], v[98:101], v[60:63]
	v_mfma_f32_16x16x32_bf16 v[56:59], v[90:93], v[98:101], v[56:59]
	v_mfma_f32_16x16x32_bf16 v[52:55], v[82:85], v[106:109], v[52:55]
	v_mfma_f32_16x16x32_bf16 v[48:51], v[90:93], v[106:109], v[48:51]
	v_mfma_f32_16x16x32_bf16 v[44:47], v[82:85], v[114:117], v[44:47]
	v_mfma_f32_16x16x32_bf16 v[40:43], v[90:93], v[114:117], v[40:43]
	v_mfma_f32_16x16x32_bf16 v[36:39], v[82:85], v[122:125], v[36:39]
	v_mfma_f32_16x16x32_bf16 v[32:35], v[90:93], v[122:125], v[32:35]
	v_mfma_f32_16x16x32_bf16 v[60:63], v[86:89], v[102:105], v[60:63]
	v_mfma_f32_16x16x32_bf16 v[56:59], v[94:97], v[102:105], v[56:59]
	v_mfma_f32_16x16x32_bf16 v[52:55], v[86:89], v[110:113], v[52:55]
	v_mfma_f32_16x16x32_bf16 v[48:51], v[94:97], v[110:113], v[48:51]
	v_mfma_f32_16x16x32_bf16 v[44:47], v[86:89], v[118:121], v[44:47]
	v_mfma_f32_16x16x32_bf16 v[40:43], v[94:97], v[118:121], v[40:43]
	v_mfma_f32_16x16x32_bf16 v[36:39], v[86:89], v[126:129], v[36:39]
	v_mfma_f32_16x16x32_bf16 v[32:35], v[94:97], v[126:129], v[32:35]
	s_barrier
	s_mov_b32 m0, s53
	v_lshl_add_u64 v[130:131], v[130:131], 0, s[8:9]
	s_add_u32 s30, s30, 0x40080
	ds_read_b128 v[98:101], v79 offset:49152
	ds_read_b128 v[102:105], v79 offset:50176
	ds_read_b128 v[106:109], v79 offset:51200
	ds_read_b128 v[110:113], v79 offset:52224
	ds_read_b128 v[114:117], v79 offset:53248
	ds_read_b128 v[118:121], v79 offset:54272
	ds_read_b128 v[122:125], v79 offset:55296
	ds_read_b128 v[126:129], v79 offset:56320
	global_load_lds_dwordx4 v[130:131], off
	v_lshl_add_u64 v[130:131], v[132:133], 0, s[8:9]
	s_mov_b32 m0, s54
	s_addc_u32 s31, s31, 0
	global_load_lds_dwordx4 v[130:131], off
	v_lshl_add_u64 v[130:131], s[30:31], 0, v[68:69]
	s_mov_b32 m0, s44
	s_nop 0
	global_load_lds_dwordx4 v[130:131], off
	v_lshl_add_u64 v[130:131], s[30:31], 0, v[64:65]
	s_mov_b32 m0, s45
	s_nop 0
	global_load_lds_dwordx4 v[130:131], off
	v_lshl_add_u64 v[130:131], v[134:135], 0, s[8:9]
	s_mov_b32 m0, s42
	s_nop 0
	global_load_lds_dwordx4 v[130:131], off
	v_lshl_add_u64 v[130:131], v[136:137], 0, s[8:9]
	s_mov_b32 m0, s43
	s_nop 0
	global_load_lds_dwordx4 v[130:131], off
	s_waitcnt vmcnt(8)
	s_waitcnt lgkmcnt(0)
	s_barrier
	s_waitcnt lgkmcnt(0)
	v_mfma_f32_16x16x32_bf16 v[28:31], v[82:85], v[98:101], v[28:31]
	v_mfma_f32_16x16x32_bf16 v[24:27], v[90:93], v[98:101], v[24:27]
	v_mfma_f32_16x16x32_bf16 v[20:23], v[82:85], v[106:109], v[20:23]
	v_mfma_f32_16x16x32_bf16 v[16:19], v[90:93], v[106:109], v[16:19]
	v_mfma_f32_16x16x32_bf16 v[12:15], v[82:85], v[114:117], v[12:15]
	v_mfma_f32_16x16x32_bf16 v[8:11], v[90:93], v[114:117], v[8:11]
	v_mfma_f32_16x16x32_bf16 v[4:7], v[82:85], v[122:125], v[4:7]
	v_mfma_f32_16x16x32_bf16 v[0:3], v[90:93], v[122:125], v[0:3]
	v_mfma_f32_16x16x32_bf16 v[28:31], v[86:89], v[102:105], v[28:31]
	v_mfma_f32_16x16x32_bf16 v[24:27], v[94:97], v[102:105], v[24:27]
	v_mfma_f32_16x16x32_bf16 v[20:23], v[86:89], v[110:113], v[20:23]
	v_mfma_f32_16x16x32_bf16 v[16:19], v[94:97], v[110:113], v[16:19]
	v_mfma_f32_16x16x32_bf16 v[12:15], v[86:89], v[118:121], v[12:15]
	v_mfma_f32_16x16x32_bf16 v[8:11], v[94:97], v[118:121], v[8:11]
	v_mfma_f32_16x16x32_bf16 v[4:7], v[86:89], v[126:129], v[4:7]
	v_mfma_f32_16x16x32_bf16 v[0:3], v[94:97], v[126:129], v[0:3]
	s_barrier
	s_add_i32 s48, s48, 2
	s_add_u32 s28, s28, 0x100
	s_addc_u32 s29, s29, 0
	s_cmp_gt_u32 s48, 5
	s_cbranch_scc0 .LBB0_374
	s_cmp_lt_u32 s84, 4
	s_cbranch_scc0 .LBB0_377
	s_barrier

; #define PG8_STAGE(bufoff, gbase, voff) do { _Pragma("unroll") for (int _i = 0; _i < 2; ++_i) \
;         __builtin_amdgcn_global_load_lds((const unsigned*)((const char*)(gbase) + (voff)[_i]), (PG8_LAS unsigned*)(lds + (bufoff) + ldsw + _i * 8192), 16, 0, 0); } while (0)
; #define PG8_LDA(dst, b, h) do { _Pragma("unroll") for (int m = 0; m < 4; ++m) _Pragma("unroll") for (int k = 0; k < 2; ++k) dst[m][k] = *(const PG8_LAS bf16x8*)(lds + PG8_SA(b, h) + aoff + m * 2048 + k * 1024); } while (0)
; #define PG8_LDB(dst, b, h) do { _Pragma("unroll") for (int n = 0; n < 2; ++n) _Pragma("unroll") for (int k = 0; k < 2; ++k) dst[n][k] = *(const PG8_LAS bf16x8*)(lds + PG8_SB(b, h) + boff + n * 2048 + k * 1024); } while (0)
; #define PG8_MMA(ai, bj, At, Bt) do { __builtin_amdgcn_s_setprio(1); _Pragma("unroll") for (int m = 0; m < 4; ++m) _Pragma("unroll") for (int n = 0; n < 2; ++n) _Pragma("unroll") for (int k = 0; k < 2; ++k) \
;         acc[ai][bj][m][n] = __builtin_amdgcn_mfma_f32_16x16x32_bf16(Bt[n][k], At[m][k], acc[ai][bj][m][n], 0, 0, 0); __builtin_amdgcn_s_setprio(0); } while (0)
; template <class Epi, class Sched, bool ALIGN_EPI = false, bool SP2 = false, bool MIDHOOK = false>
; __device__ __forceinline__ void gemm_phase(PG8_LAS unsigned char* lds, const Gemm g, const Sched& S, const Epi& E) {
;     ...
;         for (int t = 0; t < nt; t += 2) {
;             if constexpr (MIDHOOK) { if (t == nt / 2) E.mid(acc, cur, wr, wc, fr, fq); }
;             const bool last = (t == nt - 2);
;             const char* a1 = cA + (size_t)(t + 1) * kstep;
;             const char* a2 = last ? nA : cA + (size_t)(t + 2) * kstep; const char* b2 = last ? nB : cB + (size_t)(t + 2) * kstep;
;             const char* a3 = a2 + kstep; const char* b3 = b2 + kstep;
;             if (last && has_next) S.a_ready(nxt);
;             if constexpr (SP2) {
;             PG8_LDB(B0, 0, 0); PG8_LDB(B1, 0, 1); PG8_SCHED; PG8_LDA(At, 0, 0); PG8_STAGE(PG8_SA(1, 1), a1 + hstep, voffA);
;             PG8_WAIT_V(8); PG8_WAIT_L(0); PG8_BAR; PG8_MMA(0, 0, At, B0); PG8_MMA(0, 1, At, B1); PG8_BAR; PG8_SCHED;
;             PG8_LDA(At, 0, 1); PG8_STAGE(PG8_SB(0, 0), b2, voffB); PG8_STAGE(PG8_SB(0, 1), b2 + hstep, voffB); PG8_STAGE(PG8_SA(0, 0), a2, voffA);
;             PG8_WAIT_V(8); PG8_WAIT_L(0); PG8_BAR; PG8_MMA(1, 0, At, B0); PG8_MMA(1, 1, At, B1); PG8_BAR; PG8_SCHED;
.LBB0_3841:
	v_add_u32_e32 v1, s44, v224
	ds_read_b128 v[132:135], v1
	ds_read_b128 v[136:139], v1 offset:1024
	ds_read_b128 v[140:143], v1 offset:2048
	ds_read_b128 v[144:147], v1 offset:3072
	v_add_u32_e32 v1, s45, v224
	s_add_u32 s28, s24, s26
	ds_read_b128 v[148:151], v1
	ds_read_b128 v[152:155], v1 offset:1024
	ds_read_b128 v[156:159], v1 offset:2048
	ds_read_b128 v[160:163], v1 offset:3072
	s_addc_u32 s29, s25, s27
	s_add_u32 s28, s28, 0x100
	s_addc_u32 s29, s29, 0
	s_add_u32 s51, s48, s26
	s_addc_u32 s52, s49, s27
	s_cmpk_eq_i32 s26, 0x700
	s_cselect_b32 s31, s19, s29
	s_cselect_b32 s30, s46, s28
	s_cselect_b32 s29, s17, s52
	s_cselect_b32 s28, s47, s51
	v_lshl_add_u64 v[2:3], v[208:209], 0, s[26:27]
	s_add_i32 m0, s35, 0xc000
	ds_read_b128 v[164:167], v226
	ds_read_b128 v[168:171], v226 offset:1024
	ds_read_b128 v[172:175], v226 offset:2048
	ds_read_b128 v[176:179], v226 offset:3072
	ds_read_b128 v[180:183], v226 offset:4096
	ds_read_b128 v[184:187], v226 offset:5120
	ds_read_b128 v[212:215], v226 offset:6144
	ds_read_b128 v[216:219], v226 offset:7168
	global_load_lds_dwordx4 v[2:3], off
	v_lshl_add_u64 v[2:3], v[210:211], 0, s[26:27]
	s_add_i32 m0, s35, 0xe000
	s_nop 0
	global_load_lds_dwordx4 v[2:3], off
	s_waitcnt vmcnt(8)
	s_waitcnt lgkmcnt(0)
	s_barrier
	s_waitcnt lgkmcnt(0)
	v_mfma_f32_16x16x32_bf16 v[128:131], v[132:135], v[164:167], v[128:131]
	v_mfma_f32_16x16x32_bf16 v[124:127], v[140:143], v[164:167], v[124:127]
	v_mfma_f32_16x16x32_bf16 v[112:115], v[132:135], v[172:175], v[112:115]
	v_mfma_f32_16x16x32_bf16 v[108:111], v[140:143], v[172:175], v[108:111]
	v_mfma_f32_16x16x32_bf16 v[96:99], v[132:135], v[180:183], v[96:99]
	v_mfma_f32_16x16x32_bf16 v[92:95], v[140:143], v[180:183], v[92:95]
	v_mfma_f32_16x16x32_bf16 v[80:83], v[132:135], v[212:215], v[80:83]
	v_mfma_f32_16x16x32_bf16 v[76:79], v[140:143], v[212:215], v[76:79]
	v_mfma_f32_16x16x32_bf16 v[128:131], v[136:139], v[168:171], v[128:131]
	v_mfma_f32_16x16x32_bf16 v[124:127], v[144:147], v[168:171], v[124:127]
	v_mfma_f32_16x16x32_bf16 v[112:115], v[136:139], v[176:179], v[112:115]
	v_mfma_f32_16x16x32_bf16 v[108:111], v[144:147], v[176:179], v[108:111]
	v_mfma_f32_16x16x32_bf16 v[96:99], v[136:139], v[184:187], v[96:99]
	v_mfma_f32_16x16x32_bf16 v[92:95], v[144:147], v[184:187], v[92:95]
	v_mfma_f32_16x16x32_bf16 v[80:83], v[136:139], v[216:219], v[80:83]
	v_mfma_f32_16x16x32_bf16 v[76:79], v[144:147], v[216:219], v[76:79]
	v_mfma_f32_16x16x32_bf16 v[120:123], v[148:151], v[164:167], v[120:123]
	v_mfma_f32_16x16x32_bf16 v[116:119], v[156:159], v[164:167], v[116:119]
	v_mfma_f32_16x16x32_bf16 v[104:107], v[148:151], v[172:175], v[104:107]
	v_mfma_f32_16x16x32_bf16 v[100:103], v[156:159], v[172:175], v[100:103]
	v_mfma_f32_16x16x32_bf16 v[88:91], v[148:151], v[180:183], v[88:91]
	v_mfma_f32_16x16x32_bf16 v[84:87], v[156:159], v[180:183], v[84:87]
	v_mfma_f32_16x16x32_bf16 v[72:75], v[148:151], v[212:215], v[72:75]
	v_mfma_f32_16x16x32_bf16 v[68:71], v[156:159], v[212:215], v[68:71]
	v_mfma_f32_16x16x32_bf16 v[120:123], v[152:155], v[168:171], v[120:123]
	v_mfma_f32_16x16x32_bf16 v[116:119], v[160:163], v[168:171], v[116:119]
	v_mfma_f32_16x16x32_bf16 v[104:107], v[152:155], v[176:179], v[104:107]
	v_mfma_f32_16x16x32_bf16 v[100:103], v[160:163], v[176:179], v[100:103]
	v_mfma_f32_16x16x32_bf16 v[88:91], v[152:155], v[184:187], v[88:91]
	v_mfma_f32_16x16x32_bf16 v[84:87], v[160:163], v[184:187], v[84:87]
	v_mfma_f32_16x16x32_bf16 v[72:75], v[152:155], v[216:219], v[72:75]
	v_mfma_f32_16x16x32_bf16 v[68:71], v[160:163], v[216:219], v[68:71]
	s_barrier
	s_add_i32 s51, s44, s34
	v_lshl_add_u64 v[228:229], s[28:29], 0, v[190:191]
	s_mov_b32 m0, s51
	ds_read_b128 v[164:167], v226 offset:16384
	ds_read_b128 v[168:171], v226 offset:17408
	ds_read_b128 v[172:175], v226 offset:18432
	ds_read_b128 v[176:179], v226 offset:19456
	ds_read_b128 v[180:183], v226 offset:20480
	ds_read_b128 v[184:187], v226 offset:21504
	ds_read_b128 v[212:215], v226 offset:22528
	ds_read_b128 v[216:219], v226 offset:23552
	global_load_lds_dwordx4 v[228:229], off
	s_add_i32 m0, s51, 0x2000
	s_add_u32 s52, s28, 0x40000
	v_lshl_add_u64 v[230:231], s[28:29], 0, v[194:195]
	s_addc_u32 s53, s29, 0
	s_add_i32 s51, s45, s34
	global_load_lds_dwordx4 v[230:231], off
	v_lshl_add_u64 v[2:3], s[52:53], 0, v[190:191]
	s_mov_b32 m0, s51
	v_lshl_add_u64 v[232:233], s[30:31], 0, v[188:189]
	global_load_lds_dwordx4 v[2:3], off
	v_lshl_add_u64 v[2:3], s[52:53], 0, v[194:195]
	s_add_i32 m0, s51, 0x2000
	v_lshl_add_u64 v[234:235], s[30:31], 0, v[192:193]
	global_load_lds_dwordx4 v[2:3], off
	s_mov_b32 m0, s35
	s_nop 0
	global_load_lds_dwordx4 v[232:233], off
	s_mov_b32 m0, s36
	s_nop 0
	global_load_lds_dwordx4 v[234:235], off
	s_waitcnt vmcnt(8)
	s_waitcnt lgkmcnt(0)
	s_barrier
; #define PG8_STAGE(bufoff, gbase, voff) do { _Pragma("unroll") for (int _i = 0; _i < 2; ++_i) \
;         __builtin_amdgcn_global_load_lds((const unsigned*)((const char*)(gbase) + (voff)[_i]), (PG8_LAS unsigned*)(lds + (bufoff) + ldsw + _i * 8192), 16, 0, 0); } while (0)
; #define PG8_LDA(dst, b, h) do { _Pragma("unroll") for (int m = 0; m < 4; ++m) _Pragma("unroll") for (int k = 0; k < 2; ++k) dst[m][k] = *(const PG8_LAS bf16x8*)(lds + PG8_SA(b, h) + aoff + m * 2048 + k * 1024); } while (0)
; #define PG8_LDB(dst, b, h) do { _Pragma("unroll") for (int n = 0; n < 2; ++n) _Pragma("unroll") for (int k = 0; k < 2; ++k) dst[n][k] = *(const PG8_LAS bf16x8*)(lds + PG8_SB(b, h) + boff + n * 2048 + k * 1024); } while (0)
; #define PG8_MMA(ai, bj, At, Bt) do { __builtin_amdgcn_s_setprio(1); _Pragma("unroll") for (int m = 0; m < 4; ++m) _Pragma("unroll") for (int n = 0; n < 2; ++n) _Pragma("unroll") for (int k = 0; k < 2; ++k) \
;         acc[ai][bj][m][n] = __builtin_amdgcn_mfma_f32_16x16x32_bf16(Bt[n][k], At[m][k], acc[ai][bj][m][n], 0, 0, 0); __builtin_amdgcn_s_setprio(0); } while (0)
; #define PG8_WAIT_V(n) asm volatile("s_waitcnt vmcnt(" #n ")" ::: "memory")
; #define PG8_WAIT_L(n) asm volatile("s_waitcnt lgkmcnt(" #n ")" ::: "memory")
; #define PG8_BAR __builtin_amdgcn_s_barrier()
; #define PG8_SCHED __builtin_amdgcn_sched_barrier(0)
; template <class Epi, class Sched, bool ALIGN_EPI = false, bool SP2 = false, bool MIDHOOK = false>
; __device__ __forceinline__ void gemm_phase(PG8_LAS unsigned char* lds, const Gemm g, const Sched& S, const Epi& E) {
;     ...
;             PG8_WAIT_V(8); PG8_WAIT_L(0); PG8_BAR; PG8_MMA(1, 0, At, B0); PG8_MMA(1, 1, At, B1); PG8_BAR; PG8_SCHED;
;             PG8_LDB(B0, 1, 0); PG8_LDB(B1, 1, 1); PG8_SCHED; PG8_LDA(At, 1, 0); PG8_STAGE(PG8_SA(0, 1), a2 + hstep, voffA);
;             PG8_WAIT_V(8); PG8_WAIT_L(0); PG8_BAR; PG8_MMA(0, 0, At, B0); PG8_MMA(0, 1, At, B1); PG8_BAR; PG8_SCHED;
;             PG8_LDA(At, 1, 1); PG8_STAGE(PG8_SB(1, 0), b3, voffB); PG8_STAGE(PG8_SB(1, 1), b3 + hstep, voffB); PG8_STAGE(PG8_SA(1, 0), a3, voffA);
;             PG8_WAIT_V(8); PG8_WAIT_L(0); PG8_BAR; PG8_MMA(1, 0, At, B0); PG8_MMA(1, 1, At, B1); PG8_BAR; PG8_SCHED;
	s_waitcnt lgkmcnt(0)
	v_mfma_f32_16x16x32_bf16 v[64:67], v[132:135], v[164:167], v[64:67]
	v_mfma_f32_16x16x32_bf16 v[60:63], v[140:143], v[164:167], v[60:63]
	v_mfma_f32_16x16x32_bf16 v[48:51], v[132:135], v[172:175], v[48:51]
	v_mfma_f32_16x16x32_bf16 v[44:47], v[140:143], v[172:175], v[44:47]
	v_mfma_f32_16x16x32_bf16 v[32:35], v[132:135], v[180:183], v[32:35]
	v_mfma_f32_16x16x32_bf16 v[28:31], v[140:143], v[180:183], v[28:31]
	v_mfma_f32_16x16x32_bf16 v[16:19], v[132:135], v[212:215], v[16:19]
	v_mfma_f32_16x16x32_bf16 v[12:15], v[140:143], v[212:215], v[12:15]
	v_mfma_f32_16x16x32_bf16 v[64:67], v[136:139], v[168:171], v[64:67]
	v_mfma_f32_16x16x32_bf16 v[60:63], v[144:147], v[168:171], v[60:63]
	v_mfma_f32_16x16x32_bf16 v[48:51], v[136:139], v[176:179], v[48:51]
	v_mfma_f32_16x16x32_bf16 v[44:47], v[144:147], v[176:179], v[44:47]
	v_mfma_f32_16x16x32_bf16 v[32:35], v[136:139], v[184:187], v[32:35]
	v_mfma_f32_16x16x32_bf16 v[28:31], v[144:147], v[184:187], v[28:31]
	v_mfma_f32_16x16x32_bf16 v[16:19], v[136:139], v[216:219], v[16:19]
	v_mfma_f32_16x16x32_bf16 v[12:15], v[144:147], v[216:219], v[12:15]
	v_mfma_f32_16x16x32_bf16 v[56:59], v[148:151], v[164:167], v[56:59]
	v_mfma_f32_16x16x32_bf16 v[52:55], v[156:159], v[164:167], v[52:55]
	v_mfma_f32_16x16x32_bf16 v[40:43], v[148:151], v[172:175], v[40:43]
	v_mfma_f32_16x16x32_bf16 v[36:39], v[156:159], v[172:175], v[36:39]
	v_mfma_f32_16x16x32_bf16 v[24:27], v[148:151], v[180:183], v[24:27]
	v_mfma_f32_16x16x32_bf16 v[20:23], v[156:159], v[180:183], v[20:23]
	v_mfma_f32_16x16x32_bf16 v[8:11], v[148:151], v[212:215], v[8:11]
	v_mfma_f32_16x16x32_bf16 v[2:5], v[156:159], v[212:215], v[4:7]
	v_mfma_f32_16x16x32_bf16 v[56:59], v[152:155], v[168:171], v[56:59]
	v_mfma_f32_16x16x32_bf16 v[52:55], v[160:163], v[168:171], v[52:55]
	v_mfma_f32_16x16x32_bf16 v[40:43], v[152:155], v[176:179], v[40:43]
	v_mfma_f32_16x16x32_bf16 v[36:39], v[160:163], v[176:179], v[36:39]
	v_mfma_f32_16x16x32_bf16 v[24:27], v[152:155], v[184:187], v[24:27]
	v_mfma_f32_16x16x32_bf16 v[20:23], v[160:163], v[184:187], v[20:23]
	v_mfma_f32_16x16x32_bf16 v[8:11], v[152:155], v[216:219], v[8:11]
	v_mfma_f32_16x16x32_bf16 v[2:5], v[160:163], v[216:219], v[2:5]
	s_barrier
	s_add_i32 s51, 0, 0x18000
	v_add_u32_e32 v1, s51, v224
	s_add_i32 s52, 0, 0x1c000
	ds_read_b128 v[132:135], v1
	ds_read_b128 v[136:139], v1 offset:1024
	ds_read_b128 v[140:143], v1 offset:2048
	ds_read_b128 v[144:147], v1 offset:3072
	v_add_u32_e32 v1, s52, v224
	ds_read_b128 v[148:151], v1
	ds_read_b128 v[152:155], v1 offset:1024
	ds_read_b128 v[156:159], v1 offset:2048
	ds_read_b128 v[160:163], v1 offset:3072
	s_add_u32 s30, s30, 0x40000
	s_addc_u32 s31, s31, 0
	s_mov_b32 m0, s37
	v_lshl_add_u64 v[6:7], s[30:31], 0, v[188:189]
	ds_read_b128 v[164:167], v226 offset:32768
	ds_read_b128 v[168:171], v226 offset:33792
	ds_read_b128 v[172:175], v226 offset:34816
	ds_read_b128 v[176:179], v226 offset:35840
	ds_read_b128 v[180:183], v226 offset:36864
	ds_read_b128 v[184:187], v226 offset:37888
	ds_read_b128 v[212:215], v226 offset:38912
	ds_read_b128 v[216:219], v226 offset:39936
	global_load_lds_dwordx4 v[6:7], off
	v_lshl_add_u64 v[6:7], s[30:31], 0, v[192:193]
	s_mov_b32 m0, s38
	s_nop 0
	global_load_lds_dwordx4 v[6:7], off
	s_waitcnt vmcnt(8)
	s_waitcnt lgkmcnt(0)
	s_barrier
	s_waitcnt lgkmcnt(0)
	v_mfma_f32_16x16x32_bf16 v[128:131], v[132:135], v[164:167], v[128:131]
	v_mfma_f32_16x16x32_bf16 v[124:127], v[140:143], v[164:167], v[124:127]
	v_mfma_f32_16x16x32_bf16 v[112:115], v[132:135], v[172:175], v[112:115]
	v_mfma_f32_16x16x32_bf16 v[108:111], v[140:143], v[172:175], v[108:111]
	v_mfma_f32_16x16x32_bf16 v[96:99], v[132:135], v[180:183], v[96:99]
	v_mfma_f32_16x16x32_bf16 v[92:95], v[140:143], v[180:183], v[92:95]
	v_mfma_f32_16x16x32_bf16 v[80:83], v[132:135], v[212:215], v[80:83]
	v_mfma_f32_16x16x32_bf16 v[76:79], v[140:143], v[212:215], v[76:79]
	v_mfma_f32_16x16x32_bf16 v[128:131], v[136:139], v[168:171], v[128:131]
	v_mfma_f32_16x16x32_bf16 v[124:127], v[144:147], v[168:171], v[124:127]
	v_mfma_f32_16x16x32_bf16 v[112:115], v[136:139], v[176:179], v[112:115]
	v_mfma_f32_16x16x32_bf16 v[108:111], v[144:147], v[176:179], v[108:111]
	v_mfma_f32_16x16x32_bf16 v[96:99], v[136:139], v[184:187], v[96:99]
	v_mfma_f32_16x16x32_bf16 v[92:95], v[144:147], v[184:187], v[92:95]
	v_mfma_f32_16x16x32_bf16 v[80:83], v[136:139], v[216:219], v[80:83]
	v_mfma_f32_16x16x32_bf16 v[76:79], v[144:147], v[216:219], v[76:79]
	v_mfma_f32_16x16x32_bf16 v[120:123], v[148:151], v[164:167], v[120:123]
	v_mfma_f32_16x16x32_bf16 v[116:119], v[156:159], v[164:167], v[116:119]
	v_mfma_f32_16x16x32_bf16 v[104:107], v[148:151], v[172:175], v[104:107]
	v_mfma_f32_16x16x32_bf16 v[100:103], v[156:159], v[172:175], v[100:103]
	v_mfma_f32_16x16x32_bf16 v[88:91], v[148:151], v[180:183], v[88:91]
	v_mfma_f32_16x16x32_bf16 v[84:87], v[156:159], v[180:183], v[84:87]
	v_mfma_f32_16x16x32_bf16 v[72:75], v[148:151], v[212:215], v[72:75]
	v_mfma_f32_16x16x32_bf16 v[68:71], v[156:159], v[212:215], v[68:71]
	v_mfma_f32_16x16x32_bf16 v[120:123], v[152:155], v[168:171], v[120:123]
	v_mfma_f32_16x16x32_bf16 v[116:119], v[160:163], v[168:171], v[116:119]
	v_mfma_f32_16x16x32_bf16 v[104:107], v[152:155], v[176:179], v[104:107]
	v_mfma_f32_16x16x32_bf16 v[100:103], v[160:163], v[176:179], v[100:103]
	v_mfma_f32_16x16x32_bf16 v[88:91], v[152:155], v[184:187], v[88:91]
	v_mfma_f32_16x16x32_bf16 v[84:87], v[160:163], v[184:187], v[84:87]
	v_mfma_f32_16x16x32_bf16 v[72:75], v[152:155], v[216:219], v[72:75]
	v_mfma_f32_16x16x32_bf16 v[68:71], v[160:163], v[216:219], v[68:71]
	s_barrier
; #define PG8_STAGE(bufoff, gbase, voff) do { _Pragma("unroll") for (int _i = 0; _i < 2; ++_i) \
;         __builtin_amdgcn_global_load_lds((const unsigned*)((const char*)(gbase) + (voff)[_i]), (PG8_LAS unsigned*)(lds + (bufoff) + ldsw + _i * 8192), 16, 0, 0); } while (0)
; #define PG8_LDA(dst, b, h) do { _Pragma("unroll") for (int m = 0; m < 4; ++m) _Pragma("unroll") for (int k = 0; k < 2; ++k) dst[m][k] = *(const PG8_LAS bf16x8*)(lds + PG8_SA(b, h) + aoff + m * 2048 + k * 1024); } while (0)
; #define PG8_MMA(ai, bj, At, Bt) do { __builtin_amdgcn_s_setprio(1); _Pragma("unroll") for (int m = 0; m < 4; ++m) _Pragma("unroll") for (int n = 0; n < 2; ++n) _Pragma("unroll") for (int k = 0; k < 2; ++k) \
;         acc[ai][bj][m][n] = __builtin_amdgcn_mfma_f32_16x16x32_bf16(Bt[n][k], At[m][k], acc[ai][bj][m][n], 0, 0, 0); __builtin_amdgcn_s_setprio(0); } while (0)
; #define PG8_WAIT_V(n) asm volatile("s_waitcnt vmcnt(" #n ")" ::: "memory")
; #define PG8_WAIT_L(n) asm volatile("s_waitcnt lgkmcnt(" #n ")" ::: "memory")
; #define PG8_BAR __builtin_amdgcn_s_barrier()
; #define PG8_SCHED __builtin_amdgcn_sched_barrier(0)
; template <class Epi, class Sched, bool ALIGN_EPI = false, bool SP2 = false, bool MIDHOOK = false>
; __device__ __forceinline__ void gemm_phase(PG8_LAS unsigned char* lds, const Gemm g, const Sched& S, const Epi& E) {
;     ...
;         for (int t = 0; t < nt; t += 2) {
;             if constexpr (MIDHOOK) { if (t == nt / 2) E.mid(acc, cur, wr, wc, fr, fq); }
;     ...
;             PG8_LDA(At, 1, 1); PG8_STAGE(PG8_SB(1, 0), b3, voffB); PG8_STAGE(PG8_SB(1, 1), b3 + hstep, voffB); PG8_STAGE(PG8_SA(1, 0), a3, voffA);
;             PG8_WAIT_V(8); PG8_WAIT_L(0); PG8_BAR; PG8_MMA(1, 0, At, B0); PG8_MMA(1, 1, At, B1); PG8_BAR; PG8_SCHED;
	s_add_i32 s30, s51, s34
	v_lshl_add_u64 v[6:7], v[228:229], 0, s[10:11]
	s_mov_b32 m0, s30
	ds_read_b128 v[164:167], v226 offset:49152
	ds_read_b128 v[168:171], v226 offset:50176
	ds_read_b128 v[172:175], v226 offset:51200
	ds_read_b128 v[176:179], v226 offset:52224
	ds_read_b128 v[180:183], v226 offset:53248
	ds_read_b128 v[184:187], v226 offset:54272
	ds_read_b128 v[212:215], v226 offset:55296
	ds_read_b128 v[216:219], v226 offset:56320
	global_load_lds_dwordx4 v[6:7], off
	s_add_i32 m0, s30, 0x2000
	s_add_u32 s28, s28, 0x40080
	v_lshl_add_u64 v[6:7], v[230:231], 0, s[10:11]
	s_addc_u32 s29, s29, 0
	s_add_i32 s30, s52, s34
	global_load_lds_dwordx4 v[6:7], off
	v_lshl_add_u64 v[6:7], s[28:29], 0, v[190:191]
	s_mov_b32 m0, s30
	s_nop 0
	global_load_lds_dwordx4 v[6:7], off
	v_lshl_add_u64 v[6:7], s[28:29], 0, v[194:195]
	s_add_i32 m0, s30, 0x2000
	s_nop 0
	global_load_lds_dwordx4 v[6:7], off
	v_lshl_add_u64 v[6:7], v[232:233], 0, s[10:11]
	s_mov_b32 m0, s40
	s_nop 0
	global_load_lds_dwordx4 v[6:7], off
	v_lshl_add_u64 v[6:7], v[234:235], 0, s[10:11]
	s_mov_b32 m0, s41
	s_nop 0
	global_load_lds_dwordx4 v[6:7], off
	s_waitcnt vmcnt(8)
	s_waitcnt lgkmcnt(0)
	s_barrier
	s_waitcnt lgkmcnt(0)
	v_mfma_f32_16x16x32_bf16 v[64:67], v[132:135], v[164:167], v[64:67]
	v_mfma_f32_16x16x32_bf16 v[60:63], v[140:143], v[164:167], v[60:63]
	v_mfma_f32_16x16x32_bf16 v[48:51], v[132:135], v[172:175], v[48:51]
	v_mfma_f32_16x16x32_bf16 v[44:47], v[140:143], v[172:175], v[44:47]
	v_mfma_f32_16x16x32_bf16 v[32:35], v[132:135], v[180:183], v[32:35]
	v_mfma_f32_16x16x32_bf16 v[28:31], v[140:143], v[180:183], v[28:31]
	v_mfma_f32_16x16x32_bf16 v[16:19], v[132:135], v[212:215], v[16:19]
	v_mfma_f32_16x16x32_bf16 v[12:15], v[140:143], v[212:215], v[12:15]
	v_mfma_f32_16x16x32_bf16 v[64:67], v[136:139], v[168:171], v[64:67]
	v_mfma_f32_16x16x32_bf16 v[60:63], v[144:147], v[168:171], v[60:63]
	v_mfma_f32_16x16x32_bf16 v[48:51], v[136:139], v[176:179], v[48:51]
	v_mfma_f32_16x16x32_bf16 v[44:47], v[144:147], v[176:179], v[44:47]
	v_mfma_f32_16x16x32_bf16 v[32:35], v[136:139], v[184:187], v[32:35]
	v_mfma_f32_16x16x32_bf16 v[28:31], v[144:147], v[184:187], v[28:31]
	v_mfma_f32_16x16x32_bf16 v[16:19], v[136:139], v[216:219], v[16:19]
	v_mfma_f32_16x16x32_bf16 v[12:15], v[144:147], v[216:219], v[12:15]
	v_mfma_f32_16x16x32_bf16 v[56:59], v[148:151], v[164:167], v[56:59]
	v_mfma_f32_16x16x32_bf16 v[52:55], v[156:159], v[164:167], v[52:55]
	v_mfma_f32_16x16x32_bf16 v[40:43], v[148:151], v[172:175], v[40:43]
	v_mfma_f32_16x16x32_bf16 v[36:39], v[156:159], v[172:175], v[36:39]
	v_mfma_f32_16x16x32_bf16 v[24:27], v[148:151], v[180:183], v[24:27]
	v_mfma_f32_16x16x32_bf16 v[20:23], v[156:159], v[180:183], v[20:23]
	v_mfma_f32_16x16x32_bf16 v[6:9], v[148:151], v[212:215], v[8:11]
	v_mfma_f32_16x16x32_bf16 v[2:5], v[156:159], v[212:215], v[2:5]
	v_mfma_f32_16x16x32_bf16 v[56:59], v[152:155], v[168:171], v[56:59]
	v_mfma_f32_16x16x32_bf16 v[52:55], v[160:163], v[168:171], v[52:55]
	v_mfma_f32_16x16x32_bf16 v[40:43], v[152:155], v[176:179], v[40:43]
	v_mfma_f32_16x16x32_bf16 v[36:39], v[160:163], v[176:179], v[36:39]
	v_mfma_f32_16x16x32_bf16 v[24:27], v[152:155], v[184:187], v[24:27]
	v_mfma_f32_16x16x32_bf16 v[20:23], v[160:163], v[184:187], v[20:23]
	v_mfma_f32_16x16x32_bf16 v[8:11], v[152:155], v[216:219], v[6:9]
	v_mfma_f32_16x16x32_bf16 v[4:7], v[160:163], v[216:219], v[2:5]
	s_barrier
	s_add_i32 s50, s50, 2
	s_add_u32 s26, s26, 0x100
	s_addc_u32 s27, s27, 0
	s_cmp_gt_u32 s50, 13
	s_cbranch_scc1 .LBB0_3844

; #define PG8_STAGE(bufoff, gbase, voff) do { _Pragma("unroll") for (int _i = 0; _i < 2; ++_i) \
;         __builtin_amdgcn_global_load_lds((const unsigned*)((const char*)(gbase) + (voff)[_i]), (PG8_LAS unsigned*)(lds + (bufoff) + ldsw + _i * 8192), 16, 0, 0); } while (0)
; #define PG8_LDA(dst, b, h) do { _Pragma("unroll") for (int m = 0; m < 4; ++m) _Pragma("unroll") for (int k = 0; k < 2; ++k) dst[m][k] = *(const PG8_LAS bf16x8*)(lds + PG8_SA(b, h) + aoff + m * 2048 + k * 1024); } while (0)
; #define PG8_LDB(dst, b, h) do { _Pragma("unroll") for (int n = 0; n < 2; ++n) _Pragma("unroll") for (int k = 0; k < 2; ++k) dst[n][k] = *(const PG8_LAS bf16x8*)(lds + PG8_SB(b, h) + boff + n * 2048 + k * 1024); } while (0)
; #define PG8_MMA(ai, bj, At, Bt) do { __builtin_amdgcn_s_setprio(1); _Pragma("unroll") for (int m = 0; m < 4; ++m) _Pragma("unroll") for (int n = 0; n < 2; ++n) _Pragma("unroll") for (int k = 0; k < 2; ++k) \
;         acc[ai][bj][m][n] = __builtin_amdgcn_mfma_f32_16x16x32_bf16(Bt[n][k], At[m][k], acc[ai][bj][m][n], 0, 0, 0); __builtin_amdgcn_s_setprio(0); } while (0)
; template <class Epi, class Sched, bool ALIGN_EPI = false, bool SP2 = false, bool MIDHOOK = false>
; __device__ __forceinline__ void gemm_phase(PG8_LAS unsigned char* lds, const Gemm g, const Sched& S, const Epi& E) {
;     ...
;         for (int t = 0; t < nt; t += 2) {
;             if constexpr (MIDHOOK) { if (t == nt / 2) E.mid(acc, cur, wr, wc, fr, fq); }
;             const bool last = (t == nt - 2);
;             const char* a1 = cA + (size_t)(t + 1) * kstep;
;             const char* a2 = last ? nA : cA + (size_t)(t + 2) * kstep; const char* b2 = last ? nB : cB + (size_t)(t + 2) * kstep;
;             const char* a3 = a2 + kstep; const char* b3 = b2 + kstep;
;             if (last && has_next) S.a_ready(nxt);
;             if constexpr (SP2) {
;             PG8_LDB(B0, 0, 0); PG8_LDB(B1, 0, 1); PG8_SCHED; PG8_LDA(At, 0, 0); PG8_STAGE(PG8_SA(1, 1), a1 + hstep, voffA);
;             PG8_WAIT_V(8); PG8_WAIT_L(0); PG8_BAR; PG8_MMA(0, 0, At, B0); PG8_MMA(0, 1, At, B1); PG8_BAR; PG8_SCHED;
;             PG8_LDA(At, 0, 1); PG8_STAGE(PG8_SB(0, 0), b2, voffB); PG8_STAGE(PG8_SB(0, 1), b2 + hstep, voffB); PG8_STAGE(PG8_SA(0, 0), a2, voffA);
;             PG8_WAIT_V(8); PG8_WAIT_L(0); PG8_BAR; PG8_MMA(1, 0, At, B0); PG8_MMA(1, 1, At, B1); PG8_BAR; PG8_SCHED;
.LBB0_3912:
	ds_read_b128 v[148:151], v141
	ds_read_b128 v[158:161], v141 offset:1024
	ds_read_b128 v[162:165], v141 offset:2048
	ds_read_b128 v[166:169], v141 offset:3072
	ds_read_b128 v[170:173], v142
	ds_read_b128 v[174:177], v142 offset:1024
	ds_read_b128 v[178:181], v142 offset:2048
	ds_read_b128 v[182:185], v142 offset:3072
	s_add_u32 s22, s8, s16
	s_addc_u32 s23, s9, s17
	s_add_u32 s22, s22, 0x100
	s_addc_u32 s23, s23, 0
	s_add_u32 s47, s34, s16
	s_addc_u32 s48, s35, s17
	s_cmpk_eq_i32 s16, 0x700
	s_cselect_b32 s25, s9, s23
	s_cselect_b32 s24, s8, s22
	s_cselect_b32 s23, s7, s48
	s_cselect_b32 s22, s6, s47
	s_mov_b32 m0, s37
	v_lshl_add_u64 v[152:153], v[136:137], 0, s[16:17]
	ds_read_b128 v[186:189], v143
	ds_read_b128 v[190:193], v143 offset:1024
	ds_read_b128 v[194:197], v143 offset:2048
	ds_read_b128 v[198:201], v143 offset:3072
	ds_read_b128 v[202:205], v143 offset:4096
	ds_read_b128 v[206:209], v143 offset:5120
	ds_read_b128 v[210:213], v143 offset:6144
	ds_read_b128 v[214:217], v143 offset:7168
	global_load_lds_dwordx4 v[152:153], off
	v_lshl_add_u64 v[152:153], v[138:139], 0, s[16:17]
	s_mov_b32 m0, s38
	s_nop 0
	global_load_lds_dwordx4 v[152:153], off
	s_waitcnt vmcnt(8)
	s_waitcnt lgkmcnt(0)
	s_barrier
	s_waitcnt lgkmcnt(0)
	v_mfma_f32_16x16x32_bf16 v[52:55], v[148:151], v[186:189], v[52:55]
	v_mfma_f32_16x16x32_bf16 v[48:51], v[162:165], v[186:189], v[48:51]
	v_mfma_f32_16x16x32_bf16 v[68:71], v[148:151], v[194:197], v[68:71]
	v_mfma_f32_16x16x32_bf16 v[64:67], v[162:165], v[194:197], v[64:67]
	v_mfma_f32_16x16x32_bf16 v[84:87], v[148:151], v[202:205], v[84:87]
	v_mfma_f32_16x16x32_bf16 v[80:83], v[162:165], v[202:205], v[80:83]
	v_mfma_f32_16x16x32_bf16 v[92:95], v[148:151], v[210:213], v[92:95]
	v_mfma_f32_16x16x32_bf16 v[88:91], v[162:165], v[210:213], v[88:91]
	v_mfma_f32_16x16x32_bf16 v[52:55], v[158:161], v[190:193], v[52:55]
	v_mfma_f32_16x16x32_bf16 v[48:51], v[166:169], v[190:193], v[48:51]
	v_mfma_f32_16x16x32_bf16 v[68:71], v[158:161], v[198:201], v[68:71]
	v_mfma_f32_16x16x32_bf16 v[64:67], v[166:169], v[198:201], v[64:67]
	v_mfma_f32_16x16x32_bf16 v[84:87], v[158:161], v[206:209], v[84:87]
	v_mfma_f32_16x16x32_bf16 v[80:83], v[166:169], v[206:209], v[80:83]
	v_mfma_f32_16x16x32_bf16 v[92:95], v[158:161], v[214:217], v[92:95]
	v_mfma_f32_16x16x32_bf16 v[88:91], v[166:169], v[214:217], v[88:91]
	v_mfma_f32_16x16x32_bf16 v[4:7], v[170:173], v[186:189], v[4:7]
	v_mfma_f32_16x16x32_bf16 v[0:3], v[178:181], v[186:189], v[0:3]
	v_mfma_f32_16x16x32_bf16 v[12:15], v[170:173], v[194:197], v[12:15]
	v_mfma_f32_16x16x32_bf16 v[8:11], v[178:181], v[194:197], v[8:11]
	v_mfma_f32_16x16x32_bf16 v[20:23], v[170:173], v[202:205], v[20:23]
	v_mfma_f32_16x16x32_bf16 v[16:19], v[178:181], v[202:205], v[16:19]
	v_mfma_f32_16x16x32_bf16 v[28:31], v[170:173], v[210:213], v[28:31]
	v_mfma_f32_16x16x32_bf16 v[24:27], v[178:181], v[210:213], v[24:27]
	v_mfma_f32_16x16x32_bf16 v[4:7], v[174:177], v[190:193], v[4:7]
	v_mfma_f32_16x16x32_bf16 v[0:3], v[182:185], v[190:193], v[0:3]
	v_mfma_f32_16x16x32_bf16 v[12:15], v[174:177], v[198:201], v[12:15]
	v_mfma_f32_16x16x32_bf16 v[8:11], v[182:185], v[198:201], v[8:11]
	v_mfma_f32_16x16x32_bf16 v[20:23], v[174:177], v[206:209], v[20:23]
	v_mfma_f32_16x16x32_bf16 v[16:19], v[182:185], v[206:209], v[16:19]
	v_mfma_f32_16x16x32_bf16 v[28:31], v[174:177], v[214:217], v[28:31]
	v_mfma_f32_16x16x32_bf16 v[24:27], v[182:185], v[214:217], v[24:27]
	s_barrier
	s_mov_b32 m0, s39
	v_lshl_add_u64 v[152:153], s[22:23], 0, v[130:131]
	s_add_u32 s48, s22, 0x40000
	ds_read_b128 v[186:189], v143 offset:16384
	ds_read_b128 v[190:193], v143 offset:17408
	ds_read_b128 v[194:197], v143 offset:18432
	ds_read_b128 v[198:201], v143 offset:19456
	ds_read_b128 v[202:205], v143 offset:20480
	ds_read_b128 v[206:209], v143 offset:21504
	ds_read_b128 v[210:213], v143 offset:22528
	ds_read_b128 v[214:217], v143 offset:23552
	global_load_lds_dwordx4 v[152:153], off
	v_lshl_add_u64 v[218:219], s[22:23], 0, v[134:135]
	s_mov_b32 m0, s40
	s_addc_u32 s49, s23, 0
	global_load_lds_dwordx4 v[218:219], off
	v_lshl_add_u64 v[222:223], s[48:49], 0, v[130:131]
	s_mov_b32 m0, s41
	v_lshl_add_u64 v[224:225], s[24:25], 0, v[132:133]
	global_load_lds_dwordx4 v[222:223], off
	v_lshl_add_u64 v[222:223], s[48:49], 0, v[134:135]
	s_mov_b32 m0, s42
	s_nop 0
	global_load_lds_dwordx4 v[222:223], off
	v_lshl_add_u64 v[222:223], s[24:25], 0, v[128:129]
	s_mov_b32 m0, s26
	s_nop 0
	global_load_lds_dwordx4 v[222:223], off
	s_mov_b32 m0, s27
	s_nop 0
	global_load_lds_dwordx4 v[224:225], off
	s_waitcnt vmcnt(8)
	s_waitcnt lgkmcnt(0)
	s_barrier
; #define PG8_STAGE(bufoff, gbase, voff) do { _Pragma("unroll") for (int _i = 0; _i < 2; ++_i) \
;         __builtin_amdgcn_global_load_lds((const unsigned*)((const char*)(gbase) + (voff)[_i]), (PG8_LAS unsigned*)(lds + (bufoff) + ldsw + _i * 8192), 16, 0, 0); } while (0)
; #define PG8_LDA(dst, b, h) do { _Pragma("unroll") for (int m = 0; m < 4; ++m) _Pragma("unroll") for (int k = 0; k < 2; ++k) dst[m][k] = *(const PG8_LAS bf16x8*)(lds + PG8_SA(b, h) + aoff + m * 2048 + k * 1024); } while (0)
; #define PG8_LDB(dst, b, h) do { _Pragma("unroll") for (int n = 0; n < 2; ++n) _Pragma("unroll") for (int k = 0; k < 2; ++k) dst[n][k] = *(const PG8_LAS bf16x8*)(lds + PG8_SB(b, h) + boff + n * 2048 + k * 1024); } while (0)
; #define PG8_MMA(ai, bj, At, Bt) do { __builtin_amdgcn_s_setprio(1); _Pragma("unroll") for (int m = 0; m < 4; ++m) _Pragma("unroll") for (int n = 0; n < 2; ++n) _Pragma("unroll") for (int k = 0; k < 2; ++k) \
;         acc[ai][bj][m][n] = __builtin_amdgcn_mfma_f32_16x16x32_bf16(Bt[n][k], At[m][k], acc[ai][bj][m][n], 0, 0, 0); __builtin_amdgcn_s_setprio(0); } while (0)
; #define PG8_WAIT_V(n) asm volatile("s_waitcnt vmcnt(" #n ")" ::: "memory")
; #define PG8_WAIT_L(n) asm volatile("s_waitcnt lgkmcnt(" #n ")" ::: "memory")
; #define PG8_BAR __builtin_amdgcn_s_barrier()
; #define PG8_SCHED __builtin_amdgcn_sched_barrier(0)
; template <class Epi, class Sched, bool ALIGN_EPI = false, bool SP2 = false, bool MIDHOOK = false>
; __device__ __forceinline__ void gemm_phase(PG8_LAS unsigned char* lds, const Gemm g, const Sched& S, const Epi& E) {
;     ...
;             PG8_WAIT_V(8); PG8_WAIT_L(0); PG8_BAR; PG8_MMA(1, 0, At, B0); PG8_MMA(1, 1, At, B1); PG8_BAR; PG8_SCHED;
;             PG8_LDB(B0, 1, 0); PG8_LDB(B1, 1, 1); PG8_SCHED; PG8_LDA(At, 1, 0); PG8_STAGE(PG8_SA(0, 1), a2 + hstep, voffA);
;             PG8_WAIT_V(8); PG8_WAIT_L(0); PG8_BAR; PG8_MMA(0, 0, At, B0); PG8_MMA(0, 1, At, B1); PG8_BAR; PG8_SCHED;
;             PG8_LDA(At, 1, 1); PG8_STAGE(PG8_SB(1, 0), b3, voffB); PG8_STAGE(PG8_SB(1, 1), b3 + hstep, voffB); PG8_STAGE(PG8_SA(1, 0), a3, voffA);
;             PG8_WAIT_V(8); PG8_WAIT_L(0); PG8_BAR; PG8_MMA(1, 0, At, B0); PG8_MMA(1, 1, At, B1); PG8_BAR; PG8_SCHED;
	s_waitcnt lgkmcnt(0)
	v_mfma_f32_16x16x32_bf16 v[100:103], v[148:151], v[186:189], v[100:103]
	v_mfma_f32_16x16x32_bf16 v[96:99], v[162:165], v[186:189], v[96:99]
	v_mfma_f32_16x16x32_bf16 v[108:111], v[148:151], v[194:197], v[108:111]
	v_mfma_f32_16x16x32_bf16 v[104:107], v[162:165], v[194:197], v[104:107]
	v_mfma_f32_16x16x32_bf16 v[124:127], v[148:151], v[202:205], v[124:127]
	v_mfma_f32_16x16x32_bf16 v[120:123], v[162:165], v[202:205], v[120:123]
	v_mfma_f32_16x16x32_bf16 v[116:119], v[148:151], v[210:213], v[116:119]
	v_mfma_f32_16x16x32_bf16 v[112:115], v[162:165], v[210:213], v[112:115]
	v_mfma_f32_16x16x32_bf16 v[100:103], v[158:161], v[190:193], v[100:103]
	v_mfma_f32_16x16x32_bf16 v[96:99], v[166:169], v[190:193], v[96:99]
	v_mfma_f32_16x16x32_bf16 v[108:111], v[158:161], v[198:201], v[108:111]
	v_mfma_f32_16x16x32_bf16 v[104:107], v[166:169], v[198:201], v[104:107]
	v_mfma_f32_16x16x32_bf16 v[124:127], v[158:161], v[206:209], v[124:127]
	v_mfma_f32_16x16x32_bf16 v[120:123], v[166:169], v[206:209], v[120:123]
	v_mfma_f32_16x16x32_bf16 v[116:119], v[158:161], v[214:217], v[116:119]
	v_mfma_f32_16x16x32_bf16 v[112:115], v[166:169], v[214:217], v[112:115]
	v_mfma_f32_16x16x32_bf16 v[36:39], v[170:173], v[186:189], v[36:39]
	v_mfma_f32_16x16x32_bf16 v[32:35], v[178:181], v[186:189], v[32:35]
	v_mfma_f32_16x16x32_bf16 v[44:47], v[170:173], v[194:197], v[44:47]
	v_mfma_f32_16x16x32_bf16 v[40:43], v[178:181], v[194:197], v[40:43]
	v_mfma_f32_16x16x32_bf16 v[60:63], v[170:173], v[202:205], v[60:63]
	v_mfma_f32_16x16x32_bf16 v[56:59], v[178:181], v[202:205], v[56:59]
	v_mfma_f32_16x16x32_bf16 v[76:79], v[170:173], v[210:213], v[76:79]
	v_mfma_f32_16x16x32_bf16 v[72:75], v[178:181], v[210:213], v[72:75]
	v_mfma_f32_16x16x32_bf16 v[36:39], v[174:177], v[190:193], v[36:39]
	v_mfma_f32_16x16x32_bf16 v[32:35], v[182:185], v[190:193], v[32:35]
	v_mfma_f32_16x16x32_bf16 v[44:47], v[174:177], v[198:201], v[44:47]
	v_mfma_f32_16x16x32_bf16 v[40:43], v[182:185], v[198:201], v[40:43]
	v_mfma_f32_16x16x32_bf16 v[60:63], v[174:177], v[206:209], v[60:63]
	v_mfma_f32_16x16x32_bf16 v[56:59], v[182:185], v[206:209], v[56:59]
	v_mfma_f32_16x16x32_bf16 v[76:79], v[174:177], v[214:217], v[76:79]
	v_mfma_f32_16x16x32_bf16 v[72:75], v[182:185], v[214:217], v[72:75]
	s_barrier
	ds_read_b128 v[148:151], v144
	ds_read_b128 v[158:161], v144 offset:1024
	ds_read_b128 v[162:165], v144 offset:2048
	ds_read_b128 v[166:169], v144 offset:3072
	ds_read_b128 v[170:173], v145
	ds_read_b128 v[174:177], v145 offset:1024
	ds_read_b128 v[178:181], v145 offset:2048
	ds_read_b128 v[182:185], v145 offset:3072
	s_add_u32 s24, s24, 0x40000
	s_addc_u32 s25, s25, 0
	s_mov_b32 m0, s28
	v_lshl_add_u64 v[226:227], s[24:25], 0, v[128:129]
	ds_read_b128 v[186:189], v143 offset:32768
	ds_read_b128 v[190:193], v143 offset:33792
	ds_read_b128 v[194:197], v143 offset:34816
	ds_read_b128 v[198:201], v143 offset:35840
	ds_read_b128 v[202:205], v143 offset:36864
	ds_read_b128 v[206:209], v143 offset:37888
	ds_read_b128 v[210:213], v143 offset:38912
	ds_read_b128 v[214:217], v143 offset:39936
	global_load_lds_dwordx4 v[226:227], off
	v_lshl_add_u64 v[226:227], s[24:25], 0, v[132:133]
	s_mov_b32 m0, s29
	s_nop 0
	global_load_lds_dwordx4 v[226:227], off
	s_waitcnt vmcnt(8)
	s_waitcnt lgkmcnt(0)
	s_barrier
	s_waitcnt lgkmcnt(0)
	v_mfma_f32_16x16x32_bf16 v[52:55], v[148:151], v[186:189], v[52:55]
	v_mfma_f32_16x16x32_bf16 v[48:51], v[162:165], v[186:189], v[48:51]
	v_mfma_f32_16x16x32_bf16 v[68:71], v[148:151], v[194:197], v[68:71]
	v_mfma_f32_16x16x32_bf16 v[64:67], v[162:165], v[194:197], v[64:67]
	v_mfma_f32_16x16x32_bf16 v[84:87], v[148:151], v[202:205], v[84:87]
	v_mfma_f32_16x16x32_bf16 v[80:83], v[162:165], v[202:205], v[80:83]
	v_mfma_f32_16x16x32_bf16 v[92:95], v[148:151], v[210:213], v[92:95]
	v_mfma_f32_16x16x32_bf16 v[88:91], v[162:165], v[210:213], v[88:91]
	v_mfma_f32_16x16x32_bf16 v[52:55], v[158:161], v[190:193], v[52:55]
	v_mfma_f32_16x16x32_bf16 v[48:51], v[166:169], v[190:193], v[48:51]
	v_mfma_f32_16x16x32_bf16 v[68:71], v[158:161], v[198:201], v[68:71]
	v_mfma_f32_16x16x32_bf16 v[64:67], v[166:169], v[198:201], v[64:67]
	v_mfma_f32_16x16x32_bf16 v[84:87], v[158:161], v[206:209], v[84:87]
	v_mfma_f32_16x16x32_bf16 v[80:83], v[166:169], v[206:209], v[80:83]
	v_mfma_f32_16x16x32_bf16 v[92:95], v[158:161], v[214:217], v[92:95]
	v_mfma_f32_16x16x32_bf16 v[88:91], v[166:169], v[214:217], v[88:91]
	v_mfma_f32_16x16x32_bf16 v[4:7], v[170:173], v[186:189], v[4:7]
	v_mfma_f32_16x16x32_bf16 v[0:3], v[178:181], v[186:189], v[0:3]
	v_mfma_f32_16x16x32_bf16 v[12:15], v[170:173], v[194:197], v[12:15]
	v_mfma_f32_16x16x32_bf16 v[8:11], v[178:181], v[194:197], v[8:11]
	v_mfma_f32_16x16x32_bf16 v[20:23], v[170:173], v[202:205], v[20:23]
	v_mfma_f32_16x16x32_bf16 v[16:19], v[178:181], v[202:205], v[16:19]
	v_mfma_f32_16x16x32_bf16 v[28:31], v[170:173], v[210:213], v[28:31]
	v_mfma_f32_16x16x32_bf16 v[24:27], v[178:181], v[210:213], v[24:27]
	v_mfma_f32_16x16x32_bf16 v[4:7], v[174:177], v[190:193], v[4:7]
	v_mfma_f32_16x16x32_bf16 v[0:3], v[182:185], v[190:193], v[0:3]
	v_mfma_f32_16x16x32_bf16 v[12:15], v[174:177], v[198:201], v[12:15]
	v_mfma_f32_16x16x32_bf16 v[8:11], v[182:185], v[198:201], v[8:11]
	v_mfma_f32_16x16x32_bf16 v[20:23], v[174:177], v[206:209], v[20:23]
	v_mfma_f32_16x16x32_bf16 v[16:19], v[182:185], v[206:209], v[16:19]
	v_mfma_f32_16x16x32_bf16 v[28:31], v[174:177], v[214:217], v[28:31]
	v_mfma_f32_16x16x32_bf16 v[24:27], v[182:185], v[214:217], v[24:27]
	s_barrier
; #define PG8_STAGE(bufoff, gbase, voff) do { _Pragma("unroll") for (int _i = 0; _i < 2; ++_i) \
;         __builtin_amdgcn_global_load_lds((const unsigned*)((const char*)(gbase) + (voff)[_i]), (PG8_LAS unsigned*)(lds + (bufoff) + ldsw + _i * 8192), 16, 0, 0); } while (0)
; #define PG8_LDA(dst, b, h) do { _Pragma("unroll") for (int m = 0; m < 4; ++m) _Pragma("unroll") for (int k = 0; k < 2; ++k) dst[m][k] = *(const PG8_LAS bf16x8*)(lds + PG8_SA(b, h) + aoff + m * 2048 + k * 1024); } while (0)
; #define PG8_MMA(ai, bj, At, Bt) do { __builtin_amdgcn_s_setprio(1); _Pragma("unroll") for (int m = 0; m < 4; ++m) _Pragma("unroll") for (int n = 0; n < 2; ++n) _Pragma("unroll") for (int k = 0; k < 2; ++k) \
;         acc[ai][bj][m][n] = __builtin_amdgcn_mfma_f32_16x16x32_bf16(Bt[n][k], At[m][k], acc[ai][bj][m][n], 0, 0, 0); __builtin_amdgcn_s_setprio(0); } while (0)
; #define PG8_WAIT_V(n) asm volatile("s_waitcnt vmcnt(" #n ")" ::: "memory")
; #define PG8_WAIT_L(n) asm volatile("s_waitcnt lgkmcnt(" #n ")" ::: "memory")
; #define PG8_BAR __builtin_amdgcn_s_barrier()
; #define PG8_SCHED __builtin_amdgcn_sched_barrier(0)
; template <class Epi, class Sched, bool ALIGN_EPI = false, bool SP2 = false, bool MIDHOOK = false>
; __device__ __forceinline__ void gemm_phase(PG8_LAS unsigned char* lds, const Gemm g, const Sched& S, const Epi& E) {
;     ...
;             PG8_LDA(At, 1, 1); PG8_STAGE(PG8_SB(1, 0), b3, voffB); PG8_STAGE(PG8_SB(1, 1), b3 + hstep, voffB); PG8_STAGE(PG8_SA(1, 0), a3, voffA);
;             PG8_WAIT_V(8); PG8_WAIT_L(0); PG8_BAR; PG8_MMA(1, 0, At, B0); PG8_MMA(1, 1, At, B1); PG8_BAR; PG8_SCHED;
;     ...
;     PG8_WAIT_V(0);
;     if constexpr (!ALIGN_EPI) { if (wr == 0) PG8_BAR; }
	s_mov_b32 m0, s43
	v_lshl_add_u64 v[152:153], v[152:153], 0, s[12:13]
	s_add_u32 s22, s22, 0x40080
	ds_read_b128 v[186:189], v143 offset:49152
	ds_read_b128 v[190:193], v143 offset:50176
	ds_read_b128 v[194:197], v143 offset:51200
	ds_read_b128 v[198:201], v143 offset:52224
	ds_read_b128 v[202:205], v143 offset:53248
	ds_read_b128 v[206:209], v143 offset:54272
	ds_read_b128 v[210:213], v143 offset:55296
	ds_read_b128 v[214:217], v143 offset:56320
	global_load_lds_dwordx4 v[152:153], off
	v_lshl_add_u64 v[152:153], v[218:219], 0, s[12:13]
	s_mov_b32 m0, s44
	s_addc_u32 s23, s23, 0
	global_load_lds_dwordx4 v[152:153], off
	v_lshl_add_u64 v[152:153], s[22:23], 0, v[130:131]
	s_mov_b32 m0, s45
	s_nop 0
	global_load_lds_dwordx4 v[152:153], off
	v_lshl_add_u64 v[152:153], s[22:23], 0, v[134:135]
	s_mov_b32 m0, s46
	s_nop 0
	global_load_lds_dwordx4 v[152:153], off
	v_lshl_add_u64 v[152:153], v[222:223], 0, s[12:13]
	s_mov_b32 m0, s31
	s_nop 0
	global_load_lds_dwordx4 v[152:153], off
	v_lshl_add_u64 v[152:153], v[224:225], 0, s[12:13]
	s_mov_b32 m0, s33
	s_nop 0
	global_load_lds_dwordx4 v[152:153], off
	s_waitcnt vmcnt(8)
	s_waitcnt lgkmcnt(0)
	s_barrier
	s_waitcnt lgkmcnt(0)
	v_mfma_f32_16x16x32_bf16 v[100:103], v[148:151], v[186:189], v[100:103]
	v_mfma_f32_16x16x32_bf16 v[96:99], v[162:165], v[186:189], v[96:99]
	v_mfma_f32_16x16x32_bf16 v[108:111], v[148:151], v[194:197], v[108:111]
	v_mfma_f32_16x16x32_bf16 v[104:107], v[162:165], v[194:197], v[104:107]
	v_mfma_f32_16x16x32_bf16 v[124:127], v[148:151], v[202:205], v[124:127]
	v_mfma_f32_16x16x32_bf16 v[120:123], v[162:165], v[202:205], v[120:123]
	v_mfma_f32_16x16x32_bf16 v[116:119], v[148:151], v[210:213], v[116:119]
	v_mfma_f32_16x16x32_bf16 v[112:115], v[162:165], v[210:213], v[112:115]
	v_mfma_f32_16x16x32_bf16 v[100:103], v[158:161], v[190:193], v[100:103]
	v_mfma_f32_16x16x32_bf16 v[96:99], v[166:169], v[190:193], v[96:99]
	v_mfma_f32_16x16x32_bf16 v[108:111], v[158:161], v[198:201], v[108:111]
	v_mfma_f32_16x16x32_bf16 v[104:107], v[166:169], v[198:201], v[104:107]
	v_mfma_f32_16x16x32_bf16 v[124:127], v[158:161], v[206:209], v[124:127]
	v_mfma_f32_16x16x32_bf16 v[120:123], v[166:169], v[206:209], v[120:123]
	v_mfma_f32_16x16x32_bf16 v[116:119], v[158:161], v[214:217], v[116:119]
	v_mfma_f32_16x16x32_bf16 v[112:115], v[166:169], v[214:217], v[112:115]
	v_mfma_f32_16x16x32_bf16 v[36:39], v[170:173], v[186:189], v[36:39]
	v_mfma_f32_16x16x32_bf16 v[32:35], v[178:181], v[186:189], v[32:35]
	v_mfma_f32_16x16x32_bf16 v[44:47], v[170:173], v[194:197], v[44:47]
	v_mfma_f32_16x16x32_bf16 v[40:43], v[178:181], v[194:197], v[40:43]
	v_mfma_f32_16x16x32_bf16 v[60:63], v[170:173], v[202:205], v[60:63]
	v_mfma_f32_16x16x32_bf16 v[56:59], v[178:181], v[202:205], v[56:59]
	v_mfma_f32_16x16x32_bf16 v[76:79], v[170:173], v[210:213], v[76:79]
	v_mfma_f32_16x16x32_bf16 v[72:75], v[178:181], v[210:213], v[72:75]
	v_mfma_f32_16x16x32_bf16 v[36:39], v[174:177], v[190:193], v[36:39]
	v_mfma_f32_16x16x32_bf16 v[32:35], v[182:185], v[190:193], v[32:35]
	v_mfma_f32_16x16x32_bf16 v[44:47], v[174:177], v[198:201], v[44:47]
	v_mfma_f32_16x16x32_bf16 v[40:43], v[182:185], v[198:201], v[40:43]
	v_mfma_f32_16x16x32_bf16 v[60:63], v[174:177], v[206:209], v[60:63]
	v_mfma_f32_16x16x32_bf16 v[56:59], v[182:185], v[206:209], v[56:59]
	v_mfma_f32_16x16x32_bf16 v[76:79], v[174:177], v[214:217], v[76:79]
	v_mfma_f32_16x16x32_bf16 v[72:75], v[182:185], v[214:217], v[72:75]
	s_barrier
	s_add_i32 s36, s36, 2
	s_add_u32 s16, s16, 0x100
	s_addc_u32 s17, s17, 0
	s_cmp_lt_u32 s36, 14
	s_cbranch_scc1 .LBB0_3912
	s_waitcnt vmcnt(0)
	s_cmp_gt_u32 s84, 3
	s_cbranch_scc1 .LBB0_3915
	s_barrier

; #define PG8_STAGE(bufoff, gbase, voff) do { _Pragma("unroll") for (int _i = 0; _i < 2; ++_i) \
;         __builtin_amdgcn_global_load_lds((const unsigned*)((const char*)(gbase) + (voff)[_i]), (PG8_LAS unsigned*)(lds + (bufoff) + ldsw + _i * 8192), 16, 0, 0); } while (0)
; #define PG8_LDA(dst, b, h) do { _Pragma("unroll") for (int m = 0; m < 4; ++m) _Pragma("unroll") for (int k = 0; k < 2; ++k) dst[m][k] = *(const PG8_LAS bf16x8*)(lds + PG8_SA(b, h) + aoff + m * 2048 + k * 1024); } while (0)
; #define PG8_LDB(dst, b, h) do { _Pragma("unroll") for (int n = 0; n < 2; ++n) _Pragma("unroll") for (int k = 0; k < 2; ++k) dst[n][k] = *(const PG8_LAS bf16x8*)(lds + PG8_SB(b, h) + boff + n * 2048 + k * 1024); } while (0)
; #define PG8_MMA(ai, bj, At, Bt) do { __builtin_amdgcn_s_setprio(1); _Pragma("unroll") for (int m = 0; m < 4; ++m) _Pragma("unroll") for (int n = 0; n < 2; ++n) _Pragma("unroll") for (int k = 0; k < 2; ++k) \
;         acc[ai][bj][m][n] = __builtin_amdgcn_mfma_f32_16x16x32_bf16(Bt[n][k], At[m][k], acc[ai][bj][m][n], 0, 0, 0); __builtin_amdgcn_s_setprio(0); } while (0)
; template <class Epi, class Sched, bool ALIGN_EPI = false, bool SP2 = false, bool MIDHOOK = false>
; __device__ __forceinline__ void gemm_phase(PG8_LAS unsigned char* lds, const Gemm g, const Sched& S, const Epi& E) {
;     ...
;         for (int t = 0; t < nt; t += 2) {
;             if constexpr (MIDHOOK) { if (t == nt / 2) E.mid(acc, cur, wr, wc, fr, fq); }
;             const bool last = (t == nt - 2);
;             const char* a1 = cA + (size_t)(t + 1) * kstep;
;             const char* a2 = last ? nA : cA + (size_t)(t + 2) * kstep; const char* b2 = last ? nB : cB + (size_t)(t + 2) * kstep;
;             const char* a3 = a2 + kstep; const char* b3 = b2 + kstep;
;             if (last && has_next) S.a_ready(nxt);
;             if constexpr (SP2) {
;             PG8_LDB(B0, 0, 0); PG8_LDB(B1, 0, 1); PG8_SCHED; PG8_LDA(At, 0, 0); PG8_STAGE(PG8_SA(1, 1), a1 + hstep, voffA);
;             PG8_WAIT_V(8); PG8_WAIT_L(0); PG8_BAR; PG8_MMA(0, 0, At, B0); PG8_MMA(0, 1, At, B1); PG8_BAR; PG8_SCHED;
;             PG8_LDA(At, 0, 1); PG8_STAGE(PG8_SB(0, 0), b2, voffB); PG8_STAGE(PG8_SB(0, 1), b2 + hstep, voffB); PG8_STAGE(PG8_SA(0, 0), a2, voffA);
;             PG8_WAIT_V(8); PG8_WAIT_L(0); PG8_BAR; PG8_MMA(1, 0, At, B0); PG8_MMA(1, 1, At, B1); PG8_BAR; PG8_SCHED;
.LBB0_3979:
	ds_read_b128 v[148:151], v141
	ds_read_b128 v[158:161], v141 offset:1024
	ds_read_b128 v[162:165], v141 offset:2048
	ds_read_b128 v[166:169], v141 offset:3072
	ds_read_b128 v[170:173], v142
	ds_read_b128 v[174:177], v142 offset:1024
	ds_read_b128 v[178:181], v142 offset:2048
	ds_read_b128 v[182:185], v142 offset:3072
	s_add_u32 s26, s8, s24
	s_addc_u32 s27, s9, s25
	s_add_u32 s26, s26, 0x100
	s_addc_u32 s27, s27, 0
	s_add_u32 s51, s38, s24
	s_addc_u32 s52, s39, s25
	s_cmpk_eq_i32 s24, 0x700
	s_cselect_b32 s29, s9, s27
	s_cselect_b32 s28, s8, s26
	s_cselect_b32 s27, s5, s52
	s_cselect_b32 s26, s4, s51
	s_mov_b32 m0, s41
	v_lshl_add_u64 v[152:153], v[136:137], 0, s[24:25]
	ds_read_b128 v[186:189], v143
	ds_read_b128 v[190:193], v143 offset:1024
	ds_read_b128 v[194:197], v143 offset:2048
	ds_read_b128 v[198:201], v143 offset:3072
	ds_read_b128 v[202:205], v143 offset:4096
	ds_read_b128 v[206:209], v143 offset:5120
	ds_read_b128 v[210:213], v143 offset:6144
	ds_read_b128 v[214:217], v143 offset:7168
	global_load_lds_dwordx4 v[152:153], off
	v_lshl_add_u64 v[152:153], v[138:139], 0, s[24:25]
	s_mov_b32 m0, s42
	s_nop 0
	global_load_lds_dwordx4 v[152:153], off
	s_waitcnt vmcnt(8)
	s_waitcnt lgkmcnt(0)
	s_barrier
	s_waitcnt lgkmcnt(0)
	v_mfma_f32_16x16x32_bf16 v[52:55], v[148:151], v[186:189], v[52:55]
	v_mfma_f32_16x16x32_bf16 v[48:51], v[162:165], v[186:189], v[48:51]
	v_mfma_f32_16x16x32_bf16 v[68:71], v[148:151], v[194:197], v[68:71]
	v_mfma_f32_16x16x32_bf16 v[64:67], v[162:165], v[194:197], v[64:67]
	v_mfma_f32_16x16x32_bf16 v[84:87], v[148:151], v[202:205], v[84:87]
	v_mfma_f32_16x16x32_bf16 v[80:83], v[162:165], v[202:205], v[80:83]
	v_mfma_f32_16x16x32_bf16 v[92:95], v[148:151], v[210:213], v[92:95]
	v_mfma_f32_16x16x32_bf16 v[88:91], v[162:165], v[210:213], v[88:91]
	v_mfma_f32_16x16x32_bf16 v[52:55], v[158:161], v[190:193], v[52:55]
	v_mfma_f32_16x16x32_bf16 v[48:51], v[166:169], v[190:193], v[48:51]
	v_mfma_f32_16x16x32_bf16 v[68:71], v[158:161], v[198:201], v[68:71]
	v_mfma_f32_16x16x32_bf16 v[64:67], v[166:169], v[198:201], v[64:67]
	v_mfma_f32_16x16x32_bf16 v[84:87], v[158:161], v[206:209], v[84:87]
	v_mfma_f32_16x16x32_bf16 v[80:83], v[166:169], v[206:209], v[80:83]
	v_mfma_f32_16x16x32_bf16 v[92:95], v[158:161], v[214:217], v[92:95]
	v_mfma_f32_16x16x32_bf16 v[88:91], v[166:169], v[214:217], v[88:91]
	v_mfma_f32_16x16x32_bf16 v[4:7], v[170:173], v[186:189], v[4:7]
	v_mfma_f32_16x16x32_bf16 v[0:3], v[178:181], v[186:189], v[0:3]
	v_mfma_f32_16x16x32_bf16 v[12:15], v[170:173], v[194:197], v[12:15]
	v_mfma_f32_16x16x32_bf16 v[8:11], v[178:181], v[194:197], v[8:11]
	v_mfma_f32_16x16x32_bf16 v[20:23], v[170:173], v[202:205], v[20:23]
	v_mfma_f32_16x16x32_bf16 v[16:19], v[178:181], v[202:205], v[16:19]
	v_mfma_f32_16x16x32_bf16 v[28:31], v[170:173], v[210:213], v[28:31]
	v_mfma_f32_16x16x32_bf16 v[24:27], v[178:181], v[210:213], v[24:27]
	v_mfma_f32_16x16x32_bf16 v[4:7], v[174:177], v[190:193], v[4:7]
	v_mfma_f32_16x16x32_bf16 v[0:3], v[182:185], v[190:193], v[0:3]
	v_mfma_f32_16x16x32_bf16 v[12:15], v[174:177], v[198:201], v[12:15]
	v_mfma_f32_16x16x32_bf16 v[8:11], v[182:185], v[198:201], v[8:11]
	v_mfma_f32_16x16x32_bf16 v[20:23], v[174:177], v[206:209], v[20:23]
	v_mfma_f32_16x16x32_bf16 v[16:19], v[182:185], v[206:209], v[16:19]
	v_mfma_f32_16x16x32_bf16 v[28:31], v[174:177], v[214:217], v[28:31]
	v_mfma_f32_16x16x32_bf16 v[24:27], v[182:185], v[214:217], v[24:27]
	s_barrier
	s_mov_b32 m0, s43
	v_lshl_add_u64 v[152:153], s[26:27], 0, v[130:131]
	s_add_u32 s52, s26, 0x40000
	ds_read_b128 v[186:189], v143 offset:16384
	ds_read_b128 v[190:193], v143 offset:17408
	ds_read_b128 v[194:197], v143 offset:18432
	ds_read_b128 v[198:201], v143 offset:19456
	ds_read_b128 v[202:205], v143 offset:20480
	ds_read_b128 v[206:209], v143 offset:21504
	ds_read_b128 v[210:213], v143 offset:22528
	ds_read_b128 v[214:217], v143 offset:23552
	global_load_lds_dwordx4 v[152:153], off
	v_lshl_add_u64 v[218:219], s[26:27], 0, v[134:135]
	s_mov_b32 m0, s44
	s_addc_u32 s53, s27, 0
	global_load_lds_dwordx4 v[218:219], off
	v_lshl_add_u64 v[222:223], s[52:53], 0, v[130:131]
	s_mov_b32 m0, s45
	v_lshl_add_u64 v[224:225], s[28:29], 0, v[132:133]
	global_load_lds_dwordx4 v[222:223], off
	v_lshl_add_u64 v[222:223], s[52:53], 0, v[134:135]
	s_mov_b32 m0, s46
	s_nop 0
	global_load_lds_dwordx4 v[222:223], off
	v_lshl_add_u64 v[222:223], s[28:29], 0, v[128:129]
	s_mov_b32 m0, s30
	s_nop 0
	global_load_lds_dwordx4 v[222:223], off
	s_mov_b32 m0, s31
	s_nop 0
	global_load_lds_dwordx4 v[224:225], off
	s_waitcnt vmcnt(8)
	s_waitcnt lgkmcnt(0)
	s_barrier
; #define PG8_STAGE(bufoff, gbase, voff) do { _Pragma("unroll") for (int _i = 0; _i < 2; ++_i) \
;         __builtin_amdgcn_global_load_lds((const unsigned*)((const char*)(gbase) + (voff)[_i]), (PG8_LAS unsigned*)(lds + (bufoff) + ldsw + _i * 8192), 16, 0, 0); } while (0)
; #define PG8_LDA(dst, b, h) do { _Pragma("unroll") for (int m = 0; m < 4; ++m) _Pragma("unroll") for (int k = 0; k < 2; ++k) dst[m][k] = *(const PG8_LAS bf16x8*)(lds + PG8_SA(b, h) + aoff + m * 2048 + k * 1024); } while (0)
; #define PG8_LDB(dst, b, h) do { _Pragma("unroll") for (int n = 0; n < 2; ++n) _Pragma("unroll") for (int k = 0; k < 2; ++k) dst[n][k] = *(const PG8_LAS bf16x8*)(lds + PG8_SB(b, h) + boff + n * 2048 + k * 1024); } while (0)
; #define PG8_MMA(ai, bj, At, Bt) do { __builtin_amdgcn_s_setprio(1); _Pragma("unroll") for (int m = 0; m < 4; ++m) _Pragma("unroll") for (int n = 0; n < 2; ++n) _Pragma("unroll") for (int k = 0; k < 2; ++k) \
;         acc[ai][bj][m][n] = __builtin_amdgcn_mfma_f32_16x16x32_bf16(Bt[n][k], At[m][k], acc[ai][bj][m][n], 0, 0, 0); __builtin_amdgcn_s_setprio(0); } while (0)
; #define PG8_WAIT_V(n) asm volatile("s_waitcnt vmcnt(" #n ")" ::: "memory")
; #define PG8_WAIT_L(n) asm volatile("s_waitcnt lgkmcnt(" #n ")" ::: "memory")
; #define PG8_BAR __builtin_amdgcn_s_barrier()
; #define PG8_SCHED __builtin_amdgcn_sched_barrier(0)
; template <class Epi, class Sched, bool ALIGN_EPI = false, bool SP2 = false, bool MIDHOOK = false>
; __device__ __forceinline__ void gemm_phase(PG8_LAS unsigned char* lds, const Gemm g, const Sched& S, const Epi& E) {
;     ...
;             PG8_WAIT_V(8); PG8_WAIT_L(0); PG8_BAR; PG8_MMA(1, 0, At, B0); PG8_MMA(1, 1, At, B1); PG8_BAR; PG8_SCHED;
;             PG8_LDB(B0, 1, 0); PG8_LDB(B1, 1, 1); PG8_SCHED; PG8_LDA(At, 1, 0); PG8_STAGE(PG8_SA(0, 1), a2 + hstep, voffA);
;             PG8_WAIT_V(8); PG8_WAIT_L(0); PG8_BAR; PG8_MMA(0, 0, At, B0); PG8_MMA(0, 1, At, B1); PG8_BAR; PG8_SCHED;
;             PG8_LDA(At, 1, 1); PG8_STAGE(PG8_SB(1, 0), b3, voffB); PG8_STAGE(PG8_SB(1, 1), b3 + hstep, voffB); PG8_STAGE(PG8_SA(1, 0), a3, voffA);
;             PG8_WAIT_V(8); PG8_WAIT_L(0); PG8_BAR; PG8_MMA(1, 0, At, B0); PG8_MMA(1, 1, At, B1); PG8_BAR; PG8_SCHED;
	s_waitcnt lgkmcnt(0)
	v_mfma_f32_16x16x32_bf16 v[100:103], v[148:151], v[186:189], v[100:103]
	v_mfma_f32_16x16x32_bf16 v[96:99], v[162:165], v[186:189], v[96:99]
	v_mfma_f32_16x16x32_bf16 v[108:111], v[148:151], v[194:197], v[108:111]
	v_mfma_f32_16x16x32_bf16 v[104:107], v[162:165], v[194:197], v[104:107]
	v_mfma_f32_16x16x32_bf16 v[124:127], v[148:151], v[202:205], v[124:127]
	v_mfma_f32_16x16x32_bf16 v[120:123], v[162:165], v[202:205], v[120:123]
	v_mfma_f32_16x16x32_bf16 v[116:119], v[148:151], v[210:213], v[116:119]
	v_mfma_f32_16x16x32_bf16 v[112:115], v[162:165], v[210:213], v[112:115]
	v_mfma_f32_16x16x32_bf16 v[100:103], v[158:161], v[190:193], v[100:103]
	v_mfma_f32_16x16x32_bf16 v[96:99], v[166:169], v[190:193], v[96:99]
	v_mfma_f32_16x16x32_bf16 v[108:111], v[158:161], v[198:201], v[108:111]
	v_mfma_f32_16x16x32_bf16 v[104:107], v[166:169], v[198:201], v[104:107]
	v_mfma_f32_16x16x32_bf16 v[124:127], v[158:161], v[206:209], v[124:127]
	v_mfma_f32_16x16x32_bf16 v[120:123], v[166:169], v[206:209], v[120:123]
	v_mfma_f32_16x16x32_bf16 v[116:119], v[158:161], v[214:217], v[116:119]
	v_mfma_f32_16x16x32_bf16 v[112:115], v[166:169], v[214:217], v[112:115]
	v_mfma_f32_16x16x32_bf16 v[36:39], v[170:173], v[186:189], v[36:39]
	v_mfma_f32_16x16x32_bf16 v[32:35], v[178:181], v[186:189], v[32:35]
	v_mfma_f32_16x16x32_bf16 v[44:47], v[170:173], v[194:197], v[44:47]
	v_mfma_f32_16x16x32_bf16 v[40:43], v[178:181], v[194:197], v[40:43]
	v_mfma_f32_16x16x32_bf16 v[60:63], v[170:173], v[202:205], v[60:63]
	v_mfma_f32_16x16x32_bf16 v[56:59], v[178:181], v[202:205], v[56:59]
	v_mfma_f32_16x16x32_bf16 v[76:79], v[170:173], v[210:213], v[76:79]
	v_mfma_f32_16x16x32_bf16 v[72:75], v[178:181], v[210:213], v[72:75]
	v_mfma_f32_16x16x32_bf16 v[36:39], v[174:177], v[190:193], v[36:39]
	v_mfma_f32_16x16x32_bf16 v[32:35], v[182:185], v[190:193], v[32:35]
	v_mfma_f32_16x16x32_bf16 v[44:47], v[174:177], v[198:201], v[44:47]
	v_mfma_f32_16x16x32_bf16 v[40:43], v[182:185], v[198:201], v[40:43]
	v_mfma_f32_16x16x32_bf16 v[60:63], v[174:177], v[206:209], v[60:63]
	v_mfma_f32_16x16x32_bf16 v[56:59], v[182:185], v[206:209], v[56:59]
	v_mfma_f32_16x16x32_bf16 v[76:79], v[174:177], v[214:217], v[76:79]
	v_mfma_f32_16x16x32_bf16 v[72:75], v[182:185], v[214:217], v[72:75]
	s_barrier
	ds_read_b128 v[148:151], v144
	ds_read_b128 v[158:161], v144 offset:1024
	ds_read_b128 v[162:165], v144 offset:2048
	ds_read_b128 v[166:169], v144 offset:3072
	ds_read_b128 v[170:173], v145
	ds_read_b128 v[174:177], v145 offset:1024
	ds_read_b128 v[178:181], v145 offset:2048
	ds_read_b128 v[182:185], v145 offset:3072
	s_add_u32 s28, s28, 0x40000
	s_addc_u32 s29, s29, 0
	s_mov_b32 m0, s34
	v_lshl_add_u64 v[226:227], s[28:29], 0, v[128:129]
	ds_read_b128 v[186:189], v143 offset:32768
	ds_read_b128 v[190:193], v143 offset:33792
	ds_read_b128 v[194:197], v143 offset:34816
	ds_read_b128 v[198:201], v143 offset:35840
	ds_read_b128 v[202:205], v143 offset:36864
	ds_read_b128 v[206:209], v143 offset:37888
	ds_read_b128 v[210:213], v143 offset:38912
	ds_read_b128 v[214:217], v143 offset:39936
	global_load_lds_dwordx4 v[226:227], off
	v_lshl_add_u64 v[226:227], s[28:29], 0, v[132:133]
	s_mov_b32 m0, s35
	s_nop 0
	global_load_lds_dwordx4 v[226:227], off
	s_waitcnt vmcnt(8)
	s_waitcnt lgkmcnt(0)
	s_barrier
	s_waitcnt lgkmcnt(0)
	v_mfma_f32_16x16x32_bf16 v[52:55], v[148:151], v[186:189], v[52:55]
	v_mfma_f32_16x16x32_bf16 v[48:51], v[162:165], v[186:189], v[48:51]
	v_mfma_f32_16x16x32_bf16 v[68:71], v[148:151], v[194:197], v[68:71]
	v_mfma_f32_16x16x32_bf16 v[64:67], v[162:165], v[194:197], v[64:67]
	v_mfma_f32_16x16x32_bf16 v[84:87], v[148:151], v[202:205], v[84:87]
	v_mfma_f32_16x16x32_bf16 v[80:83], v[162:165], v[202:205], v[80:83]
	v_mfma_f32_16x16x32_bf16 v[92:95], v[148:151], v[210:213], v[92:95]
	v_mfma_f32_16x16x32_bf16 v[88:91], v[162:165], v[210:213], v[88:91]
	v_mfma_f32_16x16x32_bf16 v[52:55], v[158:161], v[190:193], v[52:55]
	v_mfma_f32_16x16x32_bf16 v[48:51], v[166:169], v[190:193], v[48:51]
	v_mfma_f32_16x16x32_bf16 v[68:71], v[158:161], v[198:201], v[68:71]
	v_mfma_f32_16x16x32_bf16 v[64:67], v[166:169], v[198:201], v[64:67]
	v_mfma_f32_16x16x32_bf16 v[84:87], v[158:161], v[206:209], v[84:87]
	v_mfma_f32_16x16x32_bf16 v[80:83], v[166:169], v[206:209], v[80:83]
	v_mfma_f32_16x16x32_bf16 v[92:95], v[158:161], v[214:217], v[92:95]
	v_mfma_f32_16x16x32_bf16 v[88:91], v[166:169], v[214:217], v[88:91]
	v_mfma_f32_16x16x32_bf16 v[4:7], v[170:173], v[186:189], v[4:7]
	v_mfma_f32_16x16x32_bf16 v[0:3], v[178:181], v[186:189], v[0:3]
	v_mfma_f32_16x16x32_bf16 v[12:15], v[170:173], v[194:197], v[12:15]
	v_mfma_f32_16x16x32_bf16 v[8:11], v[178:181], v[194:197], v[8:11]
	v_mfma_f32_16x16x32_bf16 v[20:23], v[170:173], v[202:205], v[20:23]
	v_mfma_f32_16x16x32_bf16 v[16:19], v[178:181], v[202:205], v[16:19]
	v_mfma_f32_16x16x32_bf16 v[28:31], v[170:173], v[210:213], v[28:31]
	v_mfma_f32_16x16x32_bf16 v[24:27], v[178:181], v[210:213], v[24:27]
	v_mfma_f32_16x16x32_bf16 v[4:7], v[174:177], v[190:193], v[4:7]
	v_mfma_f32_16x16x32_bf16 v[0:3], v[182:185], v[190:193], v[0:3]
	v_mfma_f32_16x16x32_bf16 v[12:15], v[174:177], v[198:201], v[12:15]
	v_mfma_f32_16x16x32_bf16 v[8:11], v[182:185], v[198:201], v[8:11]
	v_mfma_f32_16x16x32_bf16 v[20:23], v[174:177], v[206:209], v[20:23]
	v_mfma_f32_16x16x32_bf16 v[16:19], v[182:185], v[206:209], v[16:19]
	v_mfma_f32_16x16x32_bf16 v[28:31], v[174:177], v[214:217], v[28:31]
	v_mfma_f32_16x16x32_bf16 v[24:27], v[182:185], v[214:217], v[24:27]
	s_barrier
; #define PG8_STAGE(bufoff, gbase, voff) do { _Pragma("unroll") for (int _i = 0; _i < 2; ++_i) \
;         __builtin_amdgcn_global_load_lds((const unsigned*)((const char*)(gbase) + (voff)[_i]), (PG8_LAS unsigned*)(lds + (bufoff) + ldsw + _i * 8192), 16, 0, 0); } while (0)
; #define PG8_LDA(dst, b, h) do { _Pragma("unroll") for (int m = 0; m < 4; ++m) _Pragma("unroll") for (int k = 0; k < 2; ++k) dst[m][k] = *(const PG8_LAS bf16x8*)(lds + PG8_SA(b, h) + aoff + m * 2048 + k * 1024); } while (0)
; #define PG8_MMA(ai, bj, At, Bt) do { __builtin_amdgcn_s_setprio(1); _Pragma("unroll") for (int m = 0; m < 4; ++m) _Pragma("unroll") for (int n = 0; n < 2; ++n) _Pragma("unroll") for (int k = 0; k < 2; ++k) \
;         acc[ai][bj][m][n] = __builtin_amdgcn_mfma_f32_16x16x32_bf16(Bt[n][k], At[m][k], acc[ai][bj][m][n], 0, 0, 0); __builtin_amdgcn_s_setprio(0); } while (0)
; #define PG8_WAIT_V(n) asm volatile("s_waitcnt vmcnt(" #n ")" ::: "memory")
; #define PG8_WAIT_L(n) asm volatile("s_waitcnt lgkmcnt(" #n ")" ::: "memory")
; #define PG8_BAR __builtin_amdgcn_s_barrier()
; #define PG8_SCHED __builtin_amdgcn_sched_barrier(0)
; template <class Epi, class Sched, bool ALIGN_EPI = false, bool SP2 = false, bool MIDHOOK = false>
; __device__ __forceinline__ void gemm_phase(PG8_LAS unsigned char* lds, const Gemm g, const Sched& S, const Epi& E) {
;     ...
;             PG8_LDA(At, 1, 1); PG8_STAGE(PG8_SB(1, 0), b3, voffB); PG8_STAGE(PG8_SB(1, 1), b3 + hstep, voffB); PG8_STAGE(PG8_SA(1, 0), a3, voffA);
;             PG8_WAIT_V(8); PG8_WAIT_L(0); PG8_BAR; PG8_MMA(1, 0, At, B0); PG8_MMA(1, 1, At, B1); PG8_BAR; PG8_SCHED;
;     ...
;     PG8_WAIT_V(0);
;     if constexpr (!ALIGN_EPI) { if (wr == 0) PG8_BAR; }
	s_mov_b32 m0, s47
	v_lshl_add_u64 v[152:153], v[152:153], 0, s[22:23]
	s_add_u32 s26, s26, 0x40080
	ds_read_b128 v[186:189], v143 offset:49152
	ds_read_b128 v[190:193], v143 offset:50176
	ds_read_b128 v[194:197], v143 offset:51200
	ds_read_b128 v[198:201], v143 offset:52224
	ds_read_b128 v[202:205], v143 offset:53248
	ds_read_b128 v[206:209], v143 offset:54272
	ds_read_b128 v[210:213], v143 offset:55296
	ds_read_b128 v[214:217], v143 offset:56320
	global_load_lds_dwordx4 v[152:153], off
	v_lshl_add_u64 v[152:153], v[218:219], 0, s[22:23]
	s_mov_b32 m0, s48
	s_addc_u32 s27, s27, 0
	global_load_lds_dwordx4 v[152:153], off
	v_lshl_add_u64 v[152:153], s[26:27], 0, v[130:131]
	s_mov_b32 m0, s49
	s_nop 0
	global_load_lds_dwordx4 v[152:153], off
	v_lshl_add_u64 v[152:153], s[26:27], 0, v[134:135]
	s_mov_b32 m0, s50
	s_nop 0
	global_load_lds_dwordx4 v[152:153], off
	v_lshl_add_u64 v[152:153], v[222:223], 0, s[22:23]
	s_mov_b32 m0, s36
	s_nop 0
	global_load_lds_dwordx4 v[152:153], off
	v_lshl_add_u64 v[152:153], v[224:225], 0, s[22:23]
	s_mov_b32 m0, s37
	s_nop 0
	global_load_lds_dwordx4 v[152:153], off
	s_waitcnt vmcnt(8)
	s_waitcnt lgkmcnt(0)
	s_barrier
	s_waitcnt lgkmcnt(0)
	v_mfma_f32_16x16x32_bf16 v[100:103], v[148:151], v[186:189], v[100:103]
	v_mfma_f32_16x16x32_bf16 v[96:99], v[162:165], v[186:189], v[96:99]
	v_mfma_f32_16x16x32_bf16 v[108:111], v[148:151], v[194:197], v[108:111]
	v_mfma_f32_16x16x32_bf16 v[104:107], v[162:165], v[194:197], v[104:107]
	v_mfma_f32_16x16x32_bf16 v[124:127], v[148:151], v[202:205], v[124:127]
	v_mfma_f32_16x16x32_bf16 v[120:123], v[162:165], v[202:205], v[120:123]
	v_mfma_f32_16x16x32_bf16 v[116:119], v[148:151], v[210:213], v[116:119]
	v_mfma_f32_16x16x32_bf16 v[112:115], v[162:165], v[210:213], v[112:115]
	v_mfma_f32_16x16x32_bf16 v[100:103], v[158:161], v[190:193], v[100:103]
	v_mfma_f32_16x16x32_bf16 v[96:99], v[166:169], v[190:193], v[96:99]
	v_mfma_f32_16x16x32_bf16 v[108:111], v[158:161], v[198:201], v[108:111]
	v_mfma_f32_16x16x32_bf16 v[104:107], v[166:169], v[198:201], v[104:107]
	v_mfma_f32_16x16x32_bf16 v[124:127], v[158:161], v[206:209], v[124:127]
	v_mfma_f32_16x16x32_bf16 v[120:123], v[166:169], v[206:209], v[120:123]
	v_mfma_f32_16x16x32_bf16 v[116:119], v[158:161], v[214:217], v[116:119]
	v_mfma_f32_16x16x32_bf16 v[112:115], v[166:169], v[214:217], v[112:115]
	v_mfma_f32_16x16x32_bf16 v[36:39], v[170:173], v[186:189], v[36:39]
	v_mfma_f32_16x16x32_bf16 v[32:35], v[178:181], v[186:189], v[32:35]
	v_mfma_f32_16x16x32_bf16 v[44:47], v[170:173], v[194:197], v[44:47]
	v_mfma_f32_16x16x32_bf16 v[40:43], v[178:181], v[194:197], v[40:43]
	v_mfma_f32_16x16x32_bf16 v[60:63], v[170:173], v[202:205], v[60:63]
	v_mfma_f32_16x16x32_bf16 v[56:59], v[178:181], v[202:205], v[56:59]
	v_mfma_f32_16x16x32_bf16 v[76:79], v[170:173], v[210:213], v[76:79]
	v_mfma_f32_16x16x32_bf16 v[72:75], v[178:181], v[210:213], v[72:75]
	v_mfma_f32_16x16x32_bf16 v[36:39], v[174:177], v[190:193], v[36:39]
	v_mfma_f32_16x16x32_bf16 v[32:35], v[182:185], v[190:193], v[32:35]
	v_mfma_f32_16x16x32_bf16 v[44:47], v[174:177], v[198:201], v[44:47]
	v_mfma_f32_16x16x32_bf16 v[40:43], v[182:185], v[198:201], v[40:43]
	v_mfma_f32_16x16x32_bf16 v[60:63], v[174:177], v[206:209], v[60:63]
	v_mfma_f32_16x16x32_bf16 v[56:59], v[182:185], v[206:209], v[56:59]
	v_mfma_f32_16x16x32_bf16 v[76:79], v[174:177], v[214:217], v[76:79]
	v_mfma_f32_16x16x32_bf16 v[72:75], v[182:185], v[214:217], v[72:75]
	s_barrier
	s_add_i32 s40, s40, 2
	s_add_u32 s24, s24, 0x100
	s_addc_u32 s25, s25, 0
	s_cmp_lt_u32 s40, 14
	s_cbranch_scc1 .LBB0_3979
	s_waitcnt vmcnt(0)
	s_cmp_gt_u32 s84, 3
	s_cbranch_scc1 .LBB0_3982
	s_barrier

;     __device__ bool next(int i, Unit& u) const { if (i != 0) return false; return so.next(round, u); }
;     __device__ __forceinline__ bool next(int i, Unit& u) const { if (i > 0 || !on) return false; u.pm = pm; u.pn = 0; return true; }
; #define PG8_STAGE(bufoff, gbase, voff) do { _Pragma("unroll") for (int _i = 0; _i < 2; ++_i) \
;         __builtin_amdgcn_global_load_lds((const unsigned*)((const char*)(gbase) + (voff)[_i]), (PG8_LAS unsigned*)(lds + (bufoff) + ldsw + _i * 8192), 16, 0, 0); } while (0)
; #define PG8_LDA(dst, b, h) do { _Pragma("unroll") for (int m = 0; m < 4; ++m) _Pragma("unroll") for (int k = 0; k < 2; ++k) dst[m][k] = *(const PG8_LAS bf16x8*)(lds + PG8_SA(b, h) + aoff + m * 2048 + k * 1024); } while (0)
; #define PG8_WAIT_V(n) asm volatile("s_waitcnt vmcnt(" #n ")" ::: "memory")
; #define PG8_WAIT_L(n) asm volatile("s_waitcnt lgkmcnt(" #n ")" ::: "memory")
; template <class Epi, class Sched, bool ALIGN_EPI = false, bool SP2 = false, bool MIDHOOK = false>
; __device__ __forceinline__ void gemm_phase(PG8_LAS unsigned char* lds, const Gemm g, const Sched& S, const Epi& E) {
;     ...
;         const bool has_next = S.next(ui + 1, nxt);
;         const char* nA = has_next ? (const char*)g.A + (size_t)nxt.pm * tstep : cA; const char* nB = has_next ? (const char*)g.Bt + (size_t)nxt.pn * tstep : cB;
;         for (int t = 0; t < nt; t += 2) {
;             if constexpr (MIDHOOK) { if (t == nt / 2) E.mid(acc, cur, wr, wc, fr, fq); }
;             const bool last = (t == nt - 2);
;             const char* a1 = cA + (size_t)(t + 1) * kstep;
;             const char* a2 = last ? nA : cA + (size_t)(t + 2) * kstep; const char* b2 = last ? nB : cB + (size_t)(t + 2) * kstep;
;             const char* a3 = a2 + kstep; const char* b3 = b2 + kstep;
;             if (last && has_next) S.a_ready(nxt);
;             if constexpr (SP2) {
;             PG8_LDB(B0, 0, 0); PG8_LDB(B1, 0, 1); PG8_SCHED; PG8_LDA(At, 0, 0); PG8_STAGE(PG8_SA(1, 1), a1 + hstep, voffA);
;             PG8_WAIT_V(8); PG8_WAIT_L(0); PG8_BAR; PG8_MMA(0, 0, At, B0); PG8_MMA(0, 1, At, B1); PG8_BAR; PG8_SCHED;
;             PG8_LDA(At, 0, 1); PG8_STAGE(PG8_SB(0, 0), b2, voffB); PG8_STAGE(PG8_SB(0, 1), b2 + hstep, voffB); PG8_STAGE(PG8_SA(0, 0), a2, voffA);
;             PG8_WAIT_V(8); PG8_WAIT_L(0); PG8_BAR; PG8_MMA(1, 0, At, B0); PG8_MMA(1, 1, At, B1); PG8_BAR; PG8_SCHED;
.LBB0_4106:
	ds_read_b128 v[156:159], v149
	ds_read_b128 v[160:163], v149 offset:1024
	ds_read_b128 v[164:167], v149 offset:2048
	ds_read_b128 v[168:171], v149 offset:3072
	ds_read_b128 v[172:175], v150
	ds_read_b128 v[176:179], v150 offset:1024
	ds_read_b128 v[180:183], v150 offset:2048
	ds_read_b128 v[184:187], v150 offset:3072
	s_add_u32 s42, s40, 0xfffc0080
	s_addc_u32 s43, s41, -1
	s_cmp_eq_u32 s64, 12
	s_cselect_b32 s45, s31, s43
	s_cselect_b32 s44, s60, s42
	s_cselect_b32 s43, s29, s63
	s_cselect_b32 s42, s61, s62
	v_lshl_add_u64 v[144:145], s[40:41], 0, v[136:137]
	s_add_i32 m0, s39, 0xc000
	ds_read_b128 v[188:191], v151
	ds_read_b128 v[192:195], v151 offset:1024
	ds_read_b128 v[196:199], v151 offset:2048
	ds_read_b128 v[200:203], v151 offset:3072
	ds_read_b128 v[204:207], v151 offset:4096
	ds_read_b128 v[208:211], v151 offset:5120
	ds_read_b128 v[212:215], v151 offset:6144
	ds_read_b128 v[216:219], v151 offset:7168
	global_load_lds_dwordx4 v[144:145], off
	v_lshl_add_u64 v[144:145], s[40:41], 0, v[138:139]
	s_add_i32 m0, s39, 0xe000
	s_nop 0
	global_load_lds_dwordx4 v[144:145], off
	s_waitcnt vmcnt(8)
	s_waitcnt lgkmcnt(0)
	s_barrier
	s_waitcnt lgkmcnt(0)
	v_mfma_f32_16x16x32_bf16 v[124:127], v[156:159], v[188:191], v[124:127]
	v_mfma_f32_16x16x32_bf16 v[120:123], v[164:167], v[188:191], v[120:123]
	v_mfma_f32_16x16x32_bf16 v[108:111], v[156:159], v[196:199], v[108:111]
	v_mfma_f32_16x16x32_bf16 v[104:107], v[164:167], v[196:199], v[104:107]
	v_mfma_f32_16x16x32_bf16 v[92:95], v[156:159], v[204:207], v[92:95]
	v_mfma_f32_16x16x32_bf16 v[88:91], v[164:167], v[204:207], v[88:91]
	v_mfma_f32_16x16x32_bf16 v[76:79], v[156:159], v[212:215], v[76:79]
	v_mfma_f32_16x16x32_bf16 v[72:75], v[164:167], v[212:215], v[72:75]
	v_mfma_f32_16x16x32_bf16 v[124:127], v[160:163], v[192:195], v[124:127]
	v_mfma_f32_16x16x32_bf16 v[120:123], v[168:171], v[192:195], v[120:123]
	v_mfma_f32_16x16x32_bf16 v[108:111], v[160:163], v[200:203], v[108:111]
	v_mfma_f32_16x16x32_bf16 v[104:107], v[168:171], v[200:203], v[104:107]
	v_mfma_f32_16x16x32_bf16 v[92:95], v[160:163], v[208:211], v[92:95]
	v_mfma_f32_16x16x32_bf16 v[88:91], v[168:171], v[208:211], v[88:91]
	v_mfma_f32_16x16x32_bf16 v[76:79], v[160:163], v[216:219], v[76:79]
	v_mfma_f32_16x16x32_bf16 v[72:75], v[168:171], v[216:219], v[72:75]
	v_mfma_f32_16x16x32_bf16 v[116:119], v[172:175], v[188:191], v[116:119]
	v_mfma_f32_16x16x32_bf16 v[112:115], v[180:183], v[188:191], v[112:115]
	v_mfma_f32_16x16x32_bf16 v[100:103], v[172:175], v[196:199], v[100:103]
	v_mfma_f32_16x16x32_bf16 v[96:99], v[180:183], v[196:199], v[96:99]
	v_mfma_f32_16x16x32_bf16 v[84:87], v[172:175], v[204:207], v[84:87]
	v_mfma_f32_16x16x32_bf16 v[80:83], v[180:183], v[204:207], v[80:83]
	v_mfma_f32_16x16x32_bf16 v[68:71], v[172:175], v[212:215], v[68:71]
	v_mfma_f32_16x16x32_bf16 v[64:67], v[180:183], v[212:215], v[64:67]
	v_mfma_f32_16x16x32_bf16 v[116:119], v[176:179], v[192:195], v[116:119]
	v_mfma_f32_16x16x32_bf16 v[112:115], v[184:187], v[192:195], v[112:115]
	v_mfma_f32_16x16x32_bf16 v[100:103], v[176:179], v[200:203], v[100:103]
	v_mfma_f32_16x16x32_bf16 v[96:99], v[184:187], v[200:203], v[96:99]
	v_mfma_f32_16x16x32_bf16 v[84:87], v[176:179], v[208:211], v[84:87]
	v_mfma_f32_16x16x32_bf16 v[80:83], v[184:187], v[208:211], v[80:83]
	v_mfma_f32_16x16x32_bf16 v[68:71], v[176:179], v[216:219], v[68:71]
	v_mfma_f32_16x16x32_bf16 v[64:67], v[184:187], v[216:219], v[64:67]
	s_barrier
	s_add_i32 s65, s52, s17
	v_lshl_add_u64 v[144:145], s[42:43], 0, v[130:131]
	s_mov_b32 m0, s65
	ds_read_b128 v[188:191], v151 offset:16384
	ds_read_b128 v[192:195], v151 offset:17408
	ds_read_b128 v[196:199], v151 offset:18432
	ds_read_b128 v[200:203], v151 offset:19456
	ds_read_b128 v[204:207], v151 offset:20480
	ds_read_b128 v[208:211], v151 offset:21504
	ds_read_b128 v[212:215], v151 offset:22528
	ds_read_b128 v[216:219], v151 offset:23552
	global_load_lds_dwordx4 v[144:145], off
	s_add_i32 m0, s65, 0x2000
	s_add_u32 s66, s42, 0x40000
	v_lshl_add_u64 v[152:153], s[42:43], 0, v[134:135]
	s_addc_u32 s67, s43, 0
	s_add_i32 s65, s53, s17
	global_load_lds_dwordx4 v[152:153], off
	v_lshl_add_u64 v[222:223], s[66:67], 0, v[130:131]
	s_mov_b32 m0, s65
	v_lshl_add_u64 v[224:225], s[44:45], 0, v[132:133]
	global_load_lds_dwordx4 v[222:223], off
	v_lshl_add_u64 v[222:223], s[66:67], 0, v[134:135]
	s_add_i32 m0, s65, 0x2000
	s_nop 0
	global_load_lds_dwordx4 v[222:223], off
	v_lshl_add_u64 v[222:223], s[44:45], 0, v[128:129]
	s_mov_b32 m0, s39
	s_nop 0
	global_load_lds_dwordx4 v[222:223], off
	s_mov_b32 m0, s46
	s_nop 0
	global_load_lds_dwordx4 v[224:225], off
	s_waitcnt vmcnt(8)
	s_waitcnt lgkmcnt(0)
	s_barrier
; #define PG8_STAGE(bufoff, gbase, voff) do { _Pragma("unroll") for (int _i = 0; _i < 2; ++_i) \
;         __builtin_amdgcn_global_load_lds((const unsigned*)((const char*)(gbase) + (voff)[_i]), (PG8_LAS unsigned*)(lds + (bufoff) + ldsw + _i * 8192), 16, 0, 0); } while (0)
; #define PG8_LDA(dst, b, h) do { _Pragma("unroll") for (int m = 0; m < 4; ++m) _Pragma("unroll") for (int k = 0; k < 2; ++k) dst[m][k] = *(const PG8_LAS bf16x8*)(lds + PG8_SA(b, h) + aoff + m * 2048 + k * 1024); } while (0)
; #define PG8_LDB(dst, b, h) do { _Pragma("unroll") for (int n = 0; n < 2; ++n) _Pragma("unroll") for (int k = 0; k < 2; ++k) dst[n][k] = *(const PG8_LAS bf16x8*)(lds + PG8_SB(b, h) + boff + n * 2048 + k * 1024); } while (0)
; #define PG8_MMA(ai, bj, At, Bt) do { __builtin_amdgcn_s_setprio(1); _Pragma("unroll") for (int m = 0; m < 4; ++m) _Pragma("unroll") for (int n = 0; n < 2; ++n) _Pragma("unroll") for (int k = 0; k < 2; ++k) \
;         acc[ai][bj][m][n] = __builtin_amdgcn_mfma_f32_16x16x32_bf16(Bt[n][k], At[m][k], acc[ai][bj][m][n], 0, 0, 0); __builtin_amdgcn_s_setprio(0); } while (0)
; #define PG8_WAIT_V(n) asm volatile("s_waitcnt vmcnt(" #n ")" ::: "memory")
; #define PG8_WAIT_L(n) asm volatile("s_waitcnt lgkmcnt(" #n ")" ::: "memory")
; template <class Epi, class Sched, bool ALIGN_EPI = false, bool SP2 = false, bool MIDHOOK = false>
; __device__ __forceinline__ void gemm_phase(PG8_LAS unsigned char* lds, const Gemm g, const Sched& S, const Epi& E) {
;     ...
;             PG8_WAIT_V(8); PG8_WAIT_L(0); PG8_BAR; PG8_MMA(0, 0, At, B0); PG8_MMA(0, 1, At, B1); PG8_BAR; PG8_SCHED;
;             PG8_LDA(At, 0, 1); PG8_STAGE(PG8_SB(0, 0), b2, voffB); PG8_STAGE(PG8_SB(0, 1), b2 + hstep, voffB); PG8_STAGE(PG8_SA(0, 0), a2, voffA);
;             PG8_WAIT_V(8); PG8_WAIT_L(0); PG8_BAR; PG8_MMA(1, 0, At, B0); PG8_MMA(1, 1, At, B1); PG8_BAR; PG8_SCHED;
;             PG8_LDB(B0, 1, 0); PG8_LDB(B1, 1, 1); PG8_SCHED; PG8_LDA(At, 1, 0); PG8_STAGE(PG8_SA(0, 1), a2 + hstep, voffA);
;             PG8_WAIT_V(8); PG8_WAIT_L(0); PG8_BAR; PG8_MMA(0, 0, At, B0); PG8_MMA(0, 1, At, B1); PG8_BAR; PG8_SCHED;
;             PG8_LDA(At, 1, 1); PG8_STAGE(PG8_SB(1, 0), b3, voffB); PG8_STAGE(PG8_SB(1, 1), b3 + hstep, voffB); PG8_STAGE(PG8_SA(1, 0), a3, voffA);
;             PG8_WAIT_V(8); PG8_WAIT_L(0); PG8_BAR; PG8_MMA(1, 0, At, B0); PG8_MMA(1, 1, At, B1); PG8_BAR; PG8_SCHED;
	s_waitcnt lgkmcnt(0)
	v_mfma_f32_16x16x32_bf16 v[60:63], v[156:159], v[188:191], v[60:63]
	v_mfma_f32_16x16x32_bf16 v[56:59], v[164:167], v[188:191], v[56:59]
	v_mfma_f32_16x16x32_bf16 v[44:47], v[156:159], v[196:199], v[44:47]
	v_mfma_f32_16x16x32_bf16 v[40:43], v[164:167], v[196:199], v[40:43]
	v_mfma_f32_16x16x32_bf16 v[28:31], v[156:159], v[204:207], v[28:31]
	v_mfma_f32_16x16x32_bf16 v[24:27], v[164:167], v[204:207], v[24:27]
	v_mfma_f32_16x16x32_bf16 v[12:15], v[156:159], v[212:215], v[12:15]
	v_mfma_f32_16x16x32_bf16 v[8:11], v[164:167], v[212:215], v[8:11]
	v_mfma_f32_16x16x32_bf16 v[60:63], v[160:163], v[192:195], v[60:63]
	v_mfma_f32_16x16x32_bf16 v[56:59], v[168:171], v[192:195], v[56:59]
	v_mfma_f32_16x16x32_bf16 v[44:47], v[160:163], v[200:203], v[44:47]
	v_mfma_f32_16x16x32_bf16 v[40:43], v[168:171], v[200:203], v[40:43]
	v_mfma_f32_16x16x32_bf16 v[28:31], v[160:163], v[208:211], v[28:31]
	v_mfma_f32_16x16x32_bf16 v[24:27], v[168:171], v[208:211], v[24:27]
	v_mfma_f32_16x16x32_bf16 v[12:15], v[160:163], v[216:219], v[12:15]
	v_mfma_f32_16x16x32_bf16 v[8:11], v[168:171], v[216:219], v[8:11]
	v_mfma_f32_16x16x32_bf16 v[52:55], v[172:175], v[188:191], v[52:55]
	v_mfma_f32_16x16x32_bf16 v[48:51], v[180:183], v[188:191], v[48:51]
	v_mfma_f32_16x16x32_bf16 v[36:39], v[172:175], v[196:199], v[36:39]
	v_mfma_f32_16x16x32_bf16 v[32:35], v[180:183], v[196:199], v[32:35]
	v_mfma_f32_16x16x32_bf16 v[20:23], v[172:175], v[204:207], v[20:23]
	v_mfma_f32_16x16x32_bf16 v[16:19], v[180:183], v[204:207], v[16:19]
	v_mfma_f32_16x16x32_bf16 v[4:7], v[172:175], v[212:215], v[4:7]
	v_mfma_f32_16x16x32_bf16 v[0:3], v[180:183], v[212:215], v[0:3]
	v_mfma_f32_16x16x32_bf16 v[52:55], v[176:179], v[192:195], v[52:55]
	v_mfma_f32_16x16x32_bf16 v[48:51], v[184:187], v[192:195], v[48:51]
	v_mfma_f32_16x16x32_bf16 v[36:39], v[176:179], v[200:203], v[36:39]
	v_mfma_f32_16x16x32_bf16 v[32:35], v[184:187], v[200:203], v[32:35]
	v_mfma_f32_16x16x32_bf16 v[20:23], v[176:179], v[208:211], v[20:23]
	v_mfma_f32_16x16x32_bf16 v[16:19], v[184:187], v[208:211], v[16:19]
	v_mfma_f32_16x16x32_bf16 v[4:7], v[176:179], v[216:219], v[4:7]
	v_mfma_f32_16x16x32_bf16 v[0:3], v[184:187], v[216:219], v[0:3]
	s_barrier
	s_add_i32 s65, 0, 0x18000
	s_add_i32 s66, 0, 0x1c000
	v_add_u32_e32 v168, s65, v147
	v_add_u32_e32 v184, s66, v147
	ds_read_b128 v[156:159], v168
	ds_read_b128 v[160:163], v168 offset:1024
	ds_read_b128 v[164:167], v168 offset:2048
	ds_read_b128 v[168:171], v168 offset:3072
	ds_read_b128 v[172:175], v184
	ds_read_b128 v[176:179], v184 offset:1024
	ds_read_b128 v[180:183], v184 offset:2048
	ds_read_b128 v[184:187], v184 offset:3072
	s_add_u32 s44, s44, 0x40000
	s_addc_u32 s45, s45, 0
	s_mov_b32 m0, s47
	v_lshl_add_u64 v[226:227], s[44:45], 0, v[128:129]
	ds_read_b128 v[188:191], v151 offset:32768
	ds_read_b128 v[192:195], v151 offset:33792
	ds_read_b128 v[196:199], v151 offset:34816
	ds_read_b128 v[200:203], v151 offset:35840
	ds_read_b128 v[204:207], v151 offset:36864
	ds_read_b128 v[208:211], v151 offset:37888
	ds_read_b128 v[212:215], v151 offset:38912
	ds_read_b128 v[216:219], v151 offset:39936
	global_load_lds_dwordx4 v[226:227], off
	v_lshl_add_u64 v[226:227], s[44:45], 0, v[132:133]
	s_mov_b32 m0, s48
	s_nop 0
	global_load_lds_dwordx4 v[226:227], off
	s_waitcnt vmcnt(8)
	s_waitcnt lgkmcnt(0)
	s_barrier
	s_waitcnt lgkmcnt(0)
	v_mfma_f32_16x16x32_bf16 v[124:127], v[156:159], v[188:191], v[124:127]
	v_mfma_f32_16x16x32_bf16 v[120:123], v[164:167], v[188:191], v[120:123]
	v_mfma_f32_16x16x32_bf16 v[108:111], v[156:159], v[196:199], v[108:111]
	v_mfma_f32_16x16x32_bf16 v[104:107], v[164:167], v[196:199], v[104:107]
	v_mfma_f32_16x16x32_bf16 v[92:95], v[156:159], v[204:207], v[92:95]
	v_mfma_f32_16x16x32_bf16 v[88:91], v[164:167], v[204:207], v[88:91]
	v_mfma_f32_16x16x32_bf16 v[76:79], v[156:159], v[212:215], v[76:79]
	v_mfma_f32_16x16x32_bf16 v[72:75], v[164:167], v[212:215], v[72:75]
	v_mfma_f32_16x16x32_bf16 v[124:127], v[160:163], v[192:195], v[124:127]
	v_mfma_f32_16x16x32_bf16 v[120:123], v[168:171], v[192:195], v[120:123]
	v_mfma_f32_16x16x32_bf16 v[108:111], v[160:163], v[200:203], v[108:111]
	v_mfma_f32_16x16x32_bf16 v[104:107], v[168:171], v[200:203], v[104:107]
	v_mfma_f32_16x16x32_bf16 v[92:95], v[160:163], v[208:211], v[92:95]
	v_mfma_f32_16x16x32_bf16 v[88:91], v[168:171], v[208:211], v[88:91]
	v_mfma_f32_16x16x32_bf16 v[76:79], v[160:163], v[216:219], v[76:79]
	v_mfma_f32_16x16x32_bf16 v[72:75], v[168:171], v[216:219], v[72:75]
	v_mfma_f32_16x16x32_bf16 v[116:119], v[172:175], v[188:191], v[116:119]
	v_mfma_f32_16x16x32_bf16 v[112:115], v[180:183], v[188:191], v[112:115]
	v_mfma_f32_16x16x32_bf16 v[100:103], v[172:175], v[196:199], v[100:103]
	v_mfma_f32_16x16x32_bf16 v[96:99], v[180:183], v[196:199], v[96:99]
	v_mfma_f32_16x16x32_bf16 v[84:87], v[172:175], v[204:207], v[84:87]
	v_mfma_f32_16x16x32_bf16 v[80:83], v[180:183], v[204:207], v[80:83]
	v_mfma_f32_16x16x32_bf16 v[68:71], v[172:175], v[212:215], v[68:71]
	v_mfma_f32_16x16x32_bf16 v[64:67], v[180:183], v[212:215], v[64:67]
	v_mfma_f32_16x16x32_bf16 v[116:119], v[176:179], v[192:195], v[116:119]
	v_mfma_f32_16x16x32_bf16 v[112:115], v[184:187], v[192:195], v[112:115]
	v_mfma_f32_16x16x32_bf16 v[100:103], v[176:179], v[200:203], v[100:103]
	v_mfma_f32_16x16x32_bf16 v[96:99], v[184:187], v[200:203], v[96:99]
	v_mfma_f32_16x16x32_bf16 v[84:87], v[176:179], v[208:211], v[84:87]
	v_mfma_f32_16x16x32_bf16 v[80:83], v[184:187], v[208:211], v[80:83]
	v_mfma_f32_16x16x32_bf16 v[68:71], v[176:179], v[216:219], v[68:71]
	v_mfma_f32_16x16x32_bf16 v[64:67], v[184:187], v[216:219], v[64:67]
	s_barrier
; #define PG8_STAGE(bufoff, gbase, voff) do { _Pragma("unroll") for (int _i = 0; _i < 2; ++_i) \
;         __builtin_amdgcn_global_load_lds((const unsigned*)((const char*)(gbase) + (voff)[_i]), (PG8_LAS unsigned*)(lds + (bufoff) + ldsw + _i * 8192), 16, 0, 0); } while (0)
; #define PG8_LDA(dst, b, h) do { _Pragma("unroll") for (int m = 0; m < 4; ++m) _Pragma("unroll") for (int k = 0; k < 2; ++k) dst[m][k] = *(const PG8_LAS bf16x8*)(lds + PG8_SA(b, h) + aoff + m * 2048 + k * 1024); } while (0)
; #define PG8_MMA(ai, bj, At, Bt) do { __builtin_amdgcn_s_setprio(1); _Pragma("unroll") for (int m = 0; m < 4; ++m) _Pragma("unroll") for (int n = 0; n < 2; ++n) _Pragma("unroll") for (int k = 0; k < 2; ++k) \
;         acc[ai][bj][m][n] = __builtin_amdgcn_mfma_f32_16x16x32_bf16(Bt[n][k], At[m][k], acc[ai][bj][m][n], 0, 0, 0); __builtin_amdgcn_s_setprio(0); } while (0)
; #define PG8_WAIT_V(n) asm volatile("s_waitcnt vmcnt(" #n ")" ::: "memory")
; #define PG8_WAIT_L(n) asm volatile("s_waitcnt lgkmcnt(" #n ")" ::: "memory")
; #define PG8_BAR __builtin_amdgcn_s_barrier()
; #define PG8_SCHED __builtin_amdgcn_sched_barrier(0)
; template <class Epi, class Sched, bool ALIGN_EPI = false, bool SP2 = false, bool MIDHOOK = false>
; __device__ __forceinline__ void gemm_phase(PG8_LAS unsigned char* lds, const Gemm g, const Sched& S, const Epi& E) {
;     ...
;             PG8_LDA(At, 1, 1); PG8_STAGE(PG8_SB(1, 0), b3, voffB); PG8_STAGE(PG8_SB(1, 1), b3 + hstep, voffB); PG8_STAGE(PG8_SA(1, 0), a3, voffA);
;             PG8_WAIT_V(8); PG8_WAIT_L(0); PG8_BAR; PG8_MMA(1, 0, At, B0); PG8_MMA(1, 1, At, B1); PG8_BAR; PG8_SCHED;
;     ...
;         if constexpr (ALIGN_EPI) { if (wr == 0) PG8_BAR; }
;         if constexpr (!Epi::AFTER_DRAIN) { E(acc, cur, wr, wc, fr, fq); S.done(cur); }
;         if (!has_next) break;
	s_add_i32 s44, s65, s17
	v_lshl_add_u64 v[144:145], v[144:145], 0, s[8:9]
	s_mov_b32 m0, s44
	ds_read_b128 v[188:191], v151 offset:49152
	ds_read_b128 v[192:195], v151 offset:50176
	ds_read_b128 v[196:199], v151 offset:51200
	ds_read_b128 v[200:203], v151 offset:52224
	ds_read_b128 v[204:207], v151 offset:53248
	ds_read_b128 v[208:211], v151 offset:54272
	ds_read_b128 v[212:215], v151 offset:55296
	ds_read_b128 v[216:219], v151 offset:56320
	global_load_lds_dwordx4 v[144:145], off
	s_add_i32 m0, s44, 0x2000
	s_add_u32 s42, s42, 0x40080
	v_lshl_add_u64 v[144:145], v[152:153], 0, s[8:9]
	s_addc_u32 s43, s43, 0
	s_add_i32 s44, s66, s17
	global_load_lds_dwordx4 v[144:145], off
	v_lshl_add_u64 v[144:145], s[42:43], 0, v[130:131]
	s_mov_b32 m0, s44
	s_nop 0
	global_load_lds_dwordx4 v[144:145], off
	v_lshl_add_u64 v[144:145], s[42:43], 0, v[134:135]
	s_add_i32 m0, s44, 0x2000
	s_nop 0
	global_load_lds_dwordx4 v[144:145], off
	v_lshl_add_u64 v[144:145], v[222:223], 0, s[8:9]
	s_mov_b32 m0, s50
	s_nop 0
	global_load_lds_dwordx4 v[144:145], off
	v_lshl_add_u64 v[144:145], v[224:225], 0, s[8:9]
	s_mov_b32 m0, s51
	s_nop 0
	global_load_lds_dwordx4 v[144:145], off
	s_waitcnt vmcnt(8)
	s_waitcnt lgkmcnt(0)
	s_barrier
	s_waitcnt lgkmcnt(0)
	v_mfma_f32_16x16x32_bf16 v[60:63], v[156:159], v[188:191], v[60:63]
	v_mfma_f32_16x16x32_bf16 v[56:59], v[164:167], v[188:191], v[56:59]
	v_mfma_f32_16x16x32_bf16 v[44:47], v[156:159], v[196:199], v[44:47]
	v_mfma_f32_16x16x32_bf16 v[40:43], v[164:167], v[196:199], v[40:43]
	v_mfma_f32_16x16x32_bf16 v[28:31], v[156:159], v[204:207], v[28:31]
	v_mfma_f32_16x16x32_bf16 v[24:27], v[164:167], v[204:207], v[24:27]
	v_mfma_f32_16x16x32_bf16 v[12:15], v[156:159], v[212:215], v[12:15]
	v_mfma_f32_16x16x32_bf16 v[8:11], v[164:167], v[212:215], v[8:11]
	v_mfma_f32_16x16x32_bf16 v[60:63], v[160:163], v[192:195], v[60:63]
	v_mfma_f32_16x16x32_bf16 v[56:59], v[168:171], v[192:195], v[56:59]
	v_mfma_f32_16x16x32_bf16 v[44:47], v[160:163], v[200:203], v[44:47]
	v_mfma_f32_16x16x32_bf16 v[40:43], v[168:171], v[200:203], v[40:43]
	v_mfma_f32_16x16x32_bf16 v[28:31], v[160:163], v[208:211], v[28:31]
	v_mfma_f32_16x16x32_bf16 v[24:27], v[168:171], v[208:211], v[24:27]
	v_mfma_f32_16x16x32_bf16 v[12:15], v[160:163], v[216:219], v[12:15]
	v_mfma_f32_16x16x32_bf16 v[8:11], v[168:171], v[216:219], v[8:11]
	v_mfma_f32_16x16x32_bf16 v[52:55], v[172:175], v[188:191], v[52:55]
	v_mfma_f32_16x16x32_bf16 v[48:51], v[180:183], v[188:191], v[48:51]
	v_mfma_f32_16x16x32_bf16 v[36:39], v[172:175], v[196:199], v[36:39]
	v_mfma_f32_16x16x32_bf16 v[32:35], v[180:183], v[196:199], v[32:35]
	v_mfma_f32_16x16x32_bf16 v[20:23], v[172:175], v[204:207], v[20:23]
	v_mfma_f32_16x16x32_bf16 v[16:19], v[180:183], v[204:207], v[16:19]
	v_mfma_f32_16x16x32_bf16 v[4:7], v[172:175], v[212:215], v[4:7]
	v_mfma_f32_16x16x32_bf16 v[0:3], v[180:183], v[212:215], v[0:3]
	v_mfma_f32_16x16x32_bf16 v[52:55], v[176:179], v[192:195], v[52:55]
	v_mfma_f32_16x16x32_bf16 v[48:51], v[184:187], v[192:195], v[48:51]
	v_mfma_f32_16x16x32_bf16 v[36:39], v[176:179], v[200:203], v[36:39]
	v_mfma_f32_16x16x32_bf16 v[32:35], v[184:187], v[200:203], v[32:35]
	v_mfma_f32_16x16x32_bf16 v[20:23], v[176:179], v[208:211], v[20:23]
	v_mfma_f32_16x16x32_bf16 v[16:19], v[184:187], v[208:211], v[16:19]
	v_mfma_f32_16x16x32_bf16 v[4:7], v[176:179], v[216:219], v[4:7]
	v_mfma_f32_16x16x32_bf16 v[0:3], v[184:187], v[216:219], v[0:3]
	s_barrier
	s_add_i32 s64, s64, 2
	s_add_u32 s40, s40, 0x100
	s_addc_u32 s41, s41, 0
	s_add_u32 s62, s62, 0x100
	s_addc_u32 s63, s63, 0
	s_cmp_gt_u32 s64, 13
	s_cbranch_scc0 .LBB0_4106
	s_and_b64 vcc, exec, s[10:11]
	s_cbranch_vccz .LBB0_4109
	s_barrier

; #define PG8_STAGE(bufoff, gbase, voff) do { _Pragma("unroll") for (int _i = 0; _i < 2; ++_i) \
;         __builtin_amdgcn_global_load_lds((const unsigned*)((const char*)(gbase) + (voff)[_i]), (PG8_LAS unsigned*)(lds + (bufoff) + ldsw + _i * 8192), 16, 0, 0); } while (0)
; #define PG8_LDA(dst, b, h) do { _Pragma("unroll") for (int m = 0; m < 4; ++m) _Pragma("unroll") for (int k = 0; k < 2; ++k) dst[m][k] = *(const PG8_LAS bf16x8*)(lds + PG8_SA(b, h) + aoff + m * 2048 + k * 1024); } while (0)
; #define PG8_LDB(dst, b, h) do { _Pragma("unroll") for (int n = 0; n < 2; ++n) _Pragma("unroll") for (int k = 0; k < 2; ++k) dst[n][k] = *(const PG8_LAS bf16x8*)(lds + PG8_SB(b, h) + boff + n * 2048 + k * 1024); } while (0)
; #define PG8_MMA(ai, bj, At, Bt) do { __builtin_amdgcn_s_setprio(1); _Pragma("unroll") for (int m = 0; m < 4; ++m) _Pragma("unroll") for (int n = 0; n < 2; ++n) _Pragma("unroll") for (int k = 0; k < 2; ++k) \
;         acc[ai][bj][m][n] = __builtin_amdgcn_mfma_f32_16x16x32_bf16(Bt[n][k], At[m][k], acc[ai][bj][m][n], 0, 0, 0); __builtin_amdgcn_s_setprio(0); } while (0)
; template <class Epi, class Sched, bool ALIGN_EPI = false, bool SP2 = false, bool MIDHOOK = false>
; __device__ __forceinline__ void gemm_phase(PG8_LAS unsigned char* lds, const Gemm g, const Sched& S, const Epi& E) {
;     ...
;         for (int t = 0; t < nt; t += 2) {
;             if constexpr (MIDHOOK) { if (t == nt / 2) E.mid(acc, cur, wr, wc, fr, fq); }
;             const bool last = (t == nt - 2);
;             const char* a1 = cA + (size_t)(t + 1) * kstep;
;             const char* a2 = last ? nA : cA + (size_t)(t + 2) * kstep; const char* b2 = last ? nB : cB + (size_t)(t + 2) * kstep;
;             const char* a3 = a2 + kstep; const char* b3 = b2 + kstep;
;             if (last && has_next) S.a_ready(nxt);
;             if constexpr (SP2) {
;             PG8_LDB(B0, 0, 0); PG8_LDB(B1, 0, 1); PG8_SCHED; PG8_LDA(At, 0, 0); PG8_STAGE(PG8_SA(1, 1), a1 + hstep, voffA);
;             PG8_WAIT_V(8); PG8_WAIT_L(0); PG8_BAR; PG8_MMA(0, 0, At, B0); PG8_MMA(0, 1, At, B1); PG8_BAR; PG8_SCHED;
;             PG8_LDA(At, 0, 1); PG8_STAGE(PG8_SB(0, 0), b2, voffB); PG8_STAGE(PG8_SB(0, 1), b2 + hstep, voffB); PG8_STAGE(PG8_SA(0, 0), a2, voffA);
;             PG8_WAIT_V(8); PG8_WAIT_L(0); PG8_BAR; PG8_MMA(1, 0, At, B0); PG8_MMA(1, 1, At, B1); PG8_BAR; PG8_SCHED;
.LBB0_4175:
	ds_read_b128 v[148:151], v141
	ds_read_b128 v[158:161], v141 offset:1024
	ds_read_b128 v[162:165], v141 offset:2048
	ds_read_b128 v[166:169], v141 offset:3072
	ds_read_b128 v[170:173], v142
	ds_read_b128 v[174:177], v142 offset:1024
	ds_read_b128 v[178:181], v142 offset:2048
	ds_read_b128 v[182:185], v142 offset:3072
	s_add_u32 s26, s22, s24
	s_addc_u32 s27, s23, s25
	s_add_u32 s26, s26, 0xe000100
	s_addc_u32 s27, s27, 0
	s_add_u32 s50, s37, s24
	s_addc_u32 s51, s38, s25
	s_cmpk_eq_i32 s24, 0x1f00
	s_cselect_b32 s29, s7, s27
	s_cselect_b32 s28, s6, s26
	s_cselect_b32 s27, s1, s51
	s_cselect_b32 s26, s0, s50
	s_mov_b32 m0, s40
	v_lshl_add_u64 v[152:153], v[136:137], 0, s[24:25]
	ds_read_b128 v[186:189], v143
	ds_read_b128 v[190:193], v143 offset:1024
	ds_read_b128 v[194:197], v143 offset:2048
	ds_read_b128 v[198:201], v143 offset:3072
	ds_read_b128 v[202:205], v143 offset:4096
	ds_read_b128 v[206:209], v143 offset:5120
	ds_read_b128 v[210:213], v143 offset:6144
	ds_read_b128 v[214:217], v143 offset:7168
	global_load_lds_dwordx4 v[152:153], off
	v_lshl_add_u64 v[152:153], v[138:139], 0, s[24:25]
	s_mov_b32 m0, s41
	s_nop 0
	global_load_lds_dwordx4 v[152:153], off
	s_waitcnt vmcnt(8)
	s_waitcnt lgkmcnt(0)
	s_barrier
	s_waitcnt lgkmcnt(0)
	v_mfma_f32_16x16x32_bf16 v[52:55], v[148:151], v[186:189], v[52:55]
	v_mfma_f32_16x16x32_bf16 v[48:51], v[162:165], v[186:189], v[48:51]
	v_mfma_f32_16x16x32_bf16 v[68:71], v[148:151], v[194:197], v[68:71]
	v_mfma_f32_16x16x32_bf16 v[64:67], v[162:165], v[194:197], v[64:67]
	v_mfma_f32_16x16x32_bf16 v[84:87], v[148:151], v[202:205], v[84:87]
	v_mfma_f32_16x16x32_bf16 v[80:83], v[162:165], v[202:205], v[80:83]
	v_mfma_f32_16x16x32_bf16 v[92:95], v[148:151], v[210:213], v[92:95]
	v_mfma_f32_16x16x32_bf16 v[88:91], v[162:165], v[210:213], v[88:91]
	v_mfma_f32_16x16x32_bf16 v[52:55], v[158:161], v[190:193], v[52:55]
	v_mfma_f32_16x16x32_bf16 v[48:51], v[166:169], v[190:193], v[48:51]
	v_mfma_f32_16x16x32_bf16 v[68:71], v[158:161], v[198:201], v[68:71]
	v_mfma_f32_16x16x32_bf16 v[64:67], v[166:169], v[198:201], v[64:67]
	v_mfma_f32_16x16x32_bf16 v[84:87], v[158:161], v[206:209], v[84:87]
	v_mfma_f32_16x16x32_bf16 v[80:83], v[166:169], v[206:209], v[80:83]
	v_mfma_f32_16x16x32_bf16 v[92:95], v[158:161], v[214:217], v[92:95]
	v_mfma_f32_16x16x32_bf16 v[88:91], v[166:169], v[214:217], v[88:91]
	v_mfma_f32_16x16x32_bf16 v[4:7], v[170:173], v[186:189], v[4:7]
	v_mfma_f32_16x16x32_bf16 v[0:3], v[178:181], v[186:189], v[0:3]
	v_mfma_f32_16x16x32_bf16 v[12:15], v[170:173], v[194:197], v[12:15]
	v_mfma_f32_16x16x32_bf16 v[8:11], v[178:181], v[194:197], v[8:11]
	v_mfma_f32_16x16x32_bf16 v[20:23], v[170:173], v[202:205], v[20:23]
	v_mfma_f32_16x16x32_bf16 v[16:19], v[178:181], v[202:205], v[16:19]
	v_mfma_f32_16x16x32_bf16 v[28:31], v[170:173], v[210:213], v[28:31]
	v_mfma_f32_16x16x32_bf16 v[24:27], v[178:181], v[210:213], v[24:27]
	v_mfma_f32_16x16x32_bf16 v[4:7], v[174:177], v[190:193], v[4:7]
	v_mfma_f32_16x16x32_bf16 v[0:3], v[182:185], v[190:193], v[0:3]
	v_mfma_f32_16x16x32_bf16 v[12:15], v[174:177], v[198:201], v[12:15]
	v_mfma_f32_16x16x32_bf16 v[8:11], v[182:185], v[198:201], v[8:11]
	v_mfma_f32_16x16x32_bf16 v[20:23], v[174:177], v[206:209], v[20:23]
	v_mfma_f32_16x16x32_bf16 v[16:19], v[182:185], v[206:209], v[16:19]
	v_mfma_f32_16x16x32_bf16 v[28:31], v[174:177], v[214:217], v[28:31]
	v_mfma_f32_16x16x32_bf16 v[24:27], v[182:185], v[214:217], v[24:27]
	s_barrier
	s_mov_b32 m0, s42
	v_lshl_add_u64 v[152:153], s[26:27], 0, v[130:131]
	s_add_u32 s50, s26, 0x100000
	ds_read_b128 v[186:189], v143 offset:16384
	ds_read_b128 v[190:193], v143 offset:17408
	ds_read_b128 v[194:197], v143 offset:18432
	ds_read_b128 v[198:201], v143 offset:19456
	ds_read_b128 v[202:205], v143 offset:20480
	ds_read_b128 v[206:209], v143 offset:21504
	ds_read_b128 v[210:213], v143 offset:22528
	ds_read_b128 v[214:217], v143 offset:23552
	global_load_lds_dwordx4 v[152:153], off
	v_lshl_add_u64 v[218:219], s[26:27], 0, v[134:135]
	s_mov_b32 m0, s43
	s_addc_u32 s51, s27, 0
	global_load_lds_dwordx4 v[218:219], off
	v_lshl_add_u64 v[222:223], s[50:51], 0, v[130:131]
	s_mov_b32 m0, s44
	v_lshl_add_u64 v[224:225], s[28:29], 0, v[132:133]
	global_load_lds_dwordx4 v[222:223], off
	v_lshl_add_u64 v[222:223], s[50:51], 0, v[134:135]
	s_mov_b32 m0, s45
	s_nop 0
	global_load_lds_dwordx4 v[222:223], off
	v_lshl_add_u64 v[222:223], s[28:29], 0, v[128:129]
	s_mov_b32 m0, s30
	s_nop 0
	global_load_lds_dwordx4 v[222:223], off
	s_mov_b32 m0, s31
	s_nop 0
	global_load_lds_dwordx4 v[224:225], off
	s_waitcnt vmcnt(8)
	s_waitcnt lgkmcnt(0)
	s_barrier
; #define PG8_STAGE(bufoff, gbase, voff) do { _Pragma("unroll") for (int _i = 0; _i < 2; ++_i) \
;         __builtin_amdgcn_global_load_lds((const unsigned*)((const char*)(gbase) + (voff)[_i]), (PG8_LAS unsigned*)(lds + (bufoff) + ldsw + _i * 8192), 16, 0, 0); } while (0)
; #define PG8_LDA(dst, b, h) do { _Pragma("unroll") for (int m = 0; m < 4; ++m) _Pragma("unroll") for (int k = 0; k < 2; ++k) dst[m][k] = *(const PG8_LAS bf16x8*)(lds + PG8_SA(b, h) + aoff + m * 2048 + k * 1024); } while (0)
; #define PG8_LDB(dst, b, h) do { _Pragma("unroll") for (int n = 0; n < 2; ++n) _Pragma("unroll") for (int k = 0; k < 2; ++k) dst[n][k] = *(const PG8_LAS bf16x8*)(lds + PG8_SB(b, h) + boff + n * 2048 + k * 1024); } while (0)
; #define PG8_MMA(ai, bj, At, Bt) do { __builtin_amdgcn_s_setprio(1); _Pragma("unroll") for (int m = 0; m < 4; ++m) _Pragma("unroll") for (int n = 0; n < 2; ++n) _Pragma("unroll") for (int k = 0; k < 2; ++k) \
;         acc[ai][bj][m][n] = __builtin_amdgcn_mfma_f32_16x16x32_bf16(Bt[n][k], At[m][k], acc[ai][bj][m][n], 0, 0, 0); __builtin_amdgcn_s_setprio(0); } while (0)
; #define PG8_WAIT_V(n) asm volatile("s_waitcnt vmcnt(" #n ")" ::: "memory")
; #define PG8_WAIT_L(n) asm volatile("s_waitcnt lgkmcnt(" #n ")" ::: "memory")
; #define PG8_BAR __builtin_amdgcn_s_barrier()
; #define PG8_SCHED __builtin_amdgcn_sched_barrier(0)
; template <class Epi, class Sched, bool ALIGN_EPI = false, bool SP2 = false, bool MIDHOOK = false>
; __device__ __forceinline__ void gemm_phase(PG8_LAS unsigned char* lds, const Gemm g, const Sched& S, const Epi& E) {
;     ...
;             PG8_WAIT_V(8); PG8_WAIT_L(0); PG8_BAR; PG8_MMA(1, 0, At, B0); PG8_MMA(1, 1, At, B1); PG8_BAR; PG8_SCHED;
;             PG8_LDB(B0, 1, 0); PG8_LDB(B1, 1, 1); PG8_SCHED; PG8_LDA(At, 1, 0); PG8_STAGE(PG8_SA(0, 1), a2 + hstep, voffA);
;             PG8_WAIT_V(8); PG8_WAIT_L(0); PG8_BAR; PG8_MMA(0, 0, At, B0); PG8_MMA(0, 1, At, B1); PG8_BAR; PG8_SCHED;
;             PG8_LDA(At, 1, 1); PG8_STAGE(PG8_SB(1, 0), b3, voffB); PG8_STAGE(PG8_SB(1, 1), b3 + hstep, voffB); PG8_STAGE(PG8_SA(1, 0), a3, voffA);
;             PG8_WAIT_V(8); PG8_WAIT_L(0); PG8_BAR; PG8_MMA(1, 0, At, B0); PG8_MMA(1, 1, At, B1); PG8_BAR; PG8_SCHED;
	s_waitcnt lgkmcnt(0)
	v_mfma_f32_16x16x32_bf16 v[100:103], v[148:151], v[186:189], v[100:103]
	v_mfma_f32_16x16x32_bf16 v[96:99], v[162:165], v[186:189], v[96:99]
	v_mfma_f32_16x16x32_bf16 v[108:111], v[148:151], v[194:197], v[108:111]
	v_mfma_f32_16x16x32_bf16 v[104:107], v[162:165], v[194:197], v[104:107]
	v_mfma_f32_16x16x32_bf16 v[124:127], v[148:151], v[202:205], v[124:127]
	v_mfma_f32_16x16x32_bf16 v[112:115], v[162:165], v[202:205], v[112:115]
	v_mfma_f32_16x16x32_bf16 v[120:123], v[148:151], v[210:213], v[120:123]
	v_mfma_f32_16x16x32_bf16 v[116:119], v[162:165], v[210:213], v[116:119]
	v_mfma_f32_16x16x32_bf16 v[100:103], v[158:161], v[190:193], v[100:103]
	v_mfma_f32_16x16x32_bf16 v[96:99], v[166:169], v[190:193], v[96:99]
	v_mfma_f32_16x16x32_bf16 v[108:111], v[158:161], v[198:201], v[108:111]
	v_mfma_f32_16x16x32_bf16 v[104:107], v[166:169], v[198:201], v[104:107]
	v_mfma_f32_16x16x32_bf16 v[124:127], v[158:161], v[206:209], v[124:127]
	v_mfma_f32_16x16x32_bf16 v[112:115], v[166:169], v[206:209], v[112:115]
	v_mfma_f32_16x16x32_bf16 v[120:123], v[158:161], v[214:217], v[120:123]
	v_mfma_f32_16x16x32_bf16 v[116:119], v[166:169], v[214:217], v[116:119]
	v_mfma_f32_16x16x32_bf16 v[36:39], v[170:173], v[186:189], v[36:39]
	v_mfma_f32_16x16x32_bf16 v[32:35], v[178:181], v[186:189], v[32:35]
	v_mfma_f32_16x16x32_bf16 v[44:47], v[170:173], v[194:197], v[44:47]
	v_mfma_f32_16x16x32_bf16 v[40:43], v[178:181], v[194:197], v[40:43]
	v_mfma_f32_16x16x32_bf16 v[60:63], v[170:173], v[202:205], v[60:63]
	v_mfma_f32_16x16x32_bf16 v[56:59], v[178:181], v[202:205], v[56:59]
	v_mfma_f32_16x16x32_bf16 v[76:79], v[170:173], v[210:213], v[76:79]
	v_mfma_f32_16x16x32_bf16 v[72:75], v[178:181], v[210:213], v[72:75]
	v_mfma_f32_16x16x32_bf16 v[36:39], v[174:177], v[190:193], v[36:39]
	v_mfma_f32_16x16x32_bf16 v[32:35], v[182:185], v[190:193], v[32:35]
	v_mfma_f32_16x16x32_bf16 v[44:47], v[174:177], v[198:201], v[44:47]
	v_mfma_f32_16x16x32_bf16 v[40:43], v[182:185], v[198:201], v[40:43]
	v_mfma_f32_16x16x32_bf16 v[60:63], v[174:177], v[206:209], v[60:63]
	v_mfma_f32_16x16x32_bf16 v[56:59], v[182:185], v[206:209], v[56:59]
	v_mfma_f32_16x16x32_bf16 v[76:79], v[174:177], v[214:217], v[76:79]
	v_mfma_f32_16x16x32_bf16 v[72:75], v[182:185], v[214:217], v[72:75]
	s_barrier
	ds_read_b128 v[148:151], v144
	ds_read_b128 v[158:161], v144 offset:1024
	ds_read_b128 v[162:165], v144 offset:2048
	ds_read_b128 v[166:169], v144 offset:3072
	ds_read_b128 v[170:173], v145
	ds_read_b128 v[174:177], v145 offset:1024
	ds_read_b128 v[178:181], v145 offset:2048
	ds_read_b128 v[182:185], v145 offset:3072
	s_add_u32 s28, s28, 0x100000
	s_addc_u32 s29, s29, 0
	s_mov_b32 m0, s33
	v_lshl_add_u64 v[226:227], s[28:29], 0, v[128:129]
	ds_read_b128 v[186:189], v143 offset:32768
	ds_read_b128 v[190:193], v143 offset:33792
	ds_read_b128 v[194:197], v143 offset:34816
	ds_read_b128 v[198:201], v143 offset:35840
	ds_read_b128 v[202:205], v143 offset:36864
	ds_read_b128 v[206:209], v143 offset:37888
	ds_read_b128 v[210:213], v143 offset:38912
	ds_read_b128 v[214:217], v143 offset:39936
	global_load_lds_dwordx4 v[226:227], off
	v_lshl_add_u64 v[226:227], s[28:29], 0, v[132:133]
	s_mov_b32 m0, s34
	s_nop 0
	global_load_lds_dwordx4 v[226:227], off
	s_waitcnt vmcnt(8)
	s_waitcnt lgkmcnt(0)
	s_barrier
	s_waitcnt lgkmcnt(0)
	v_mfma_f32_16x16x32_bf16 v[52:55], v[148:151], v[186:189], v[52:55]
	v_mfma_f32_16x16x32_bf16 v[48:51], v[162:165], v[186:189], v[48:51]
	v_mfma_f32_16x16x32_bf16 v[68:71], v[148:151], v[194:197], v[68:71]
	v_mfma_f32_16x16x32_bf16 v[64:67], v[162:165], v[194:197], v[64:67]
	v_mfma_f32_16x16x32_bf16 v[84:87], v[148:151], v[202:205], v[84:87]
	v_mfma_f32_16x16x32_bf16 v[80:83], v[162:165], v[202:205], v[80:83]
	v_mfma_f32_16x16x32_bf16 v[92:95], v[148:151], v[210:213], v[92:95]
	v_mfma_f32_16x16x32_bf16 v[88:91], v[162:165], v[210:213], v[88:91]
	v_mfma_f32_16x16x32_bf16 v[52:55], v[158:161], v[190:193], v[52:55]
	v_mfma_f32_16x16x32_bf16 v[48:51], v[166:169], v[190:193], v[48:51]
	v_mfma_f32_16x16x32_bf16 v[68:71], v[158:161], v[198:201], v[68:71]
	v_mfma_f32_16x16x32_bf16 v[64:67], v[166:169], v[198:201], v[64:67]
	v_mfma_f32_16x16x32_bf16 v[84:87], v[158:161], v[206:209], v[84:87]
	v_mfma_f32_16x16x32_bf16 v[80:83], v[166:169], v[206:209], v[80:83]
	v_mfma_f32_16x16x32_bf16 v[92:95], v[158:161], v[214:217], v[92:95]
	v_mfma_f32_16x16x32_bf16 v[88:91], v[166:169], v[214:217], v[88:91]
	v_mfma_f32_16x16x32_bf16 v[4:7], v[170:173], v[186:189], v[4:7]
	v_mfma_f32_16x16x32_bf16 v[0:3], v[178:181], v[186:189], v[0:3]
	v_mfma_f32_16x16x32_bf16 v[12:15], v[170:173], v[194:197], v[12:15]
	v_mfma_f32_16x16x32_bf16 v[8:11], v[178:181], v[194:197], v[8:11]
	v_mfma_f32_16x16x32_bf16 v[20:23], v[170:173], v[202:205], v[20:23]
	v_mfma_f32_16x16x32_bf16 v[16:19], v[178:181], v[202:205], v[16:19]
	v_mfma_f32_16x16x32_bf16 v[28:31], v[170:173], v[210:213], v[28:31]
	v_mfma_f32_16x16x32_bf16 v[24:27], v[178:181], v[210:213], v[24:27]
	v_mfma_f32_16x16x32_bf16 v[4:7], v[174:177], v[190:193], v[4:7]
	v_mfma_f32_16x16x32_bf16 v[0:3], v[182:185], v[190:193], v[0:3]
	v_mfma_f32_16x16x32_bf16 v[12:15], v[174:177], v[198:201], v[12:15]
	v_mfma_f32_16x16x32_bf16 v[8:11], v[182:185], v[198:201], v[8:11]
	v_mfma_f32_16x16x32_bf16 v[20:23], v[174:177], v[206:209], v[20:23]
	v_mfma_f32_16x16x32_bf16 v[16:19], v[182:185], v[206:209], v[16:19]
	v_mfma_f32_16x16x32_bf16 v[28:31], v[174:177], v[214:217], v[28:31]
	v_mfma_f32_16x16x32_bf16 v[24:27], v[182:185], v[214:217], v[24:27]
	s_barrier
; #define PG8_STAGE(bufoff, gbase, voff) do { _Pragma("unroll") for (int _i = 0; _i < 2; ++_i) \
;         __builtin_amdgcn_global_load_lds((const unsigned*)((const char*)(gbase) + (voff)[_i]), (PG8_LAS unsigned*)(lds + (bufoff) + ldsw + _i * 8192), 16, 0, 0); } while (0)
; #define PG8_LDA(dst, b, h) do { _Pragma("unroll") for (int m = 0; m < 4; ++m) _Pragma("unroll") for (int k = 0; k < 2; ++k) dst[m][k] = *(const PG8_LAS bf16x8*)(lds + PG8_SA(b, h) + aoff + m * 2048 + k * 1024); } while (0)
; #define PG8_MMA(ai, bj, At, Bt) do { __builtin_amdgcn_s_setprio(1); _Pragma("unroll") for (int m = 0; m < 4; ++m) _Pragma("unroll") for (int n = 0; n < 2; ++n) _Pragma("unroll") for (int k = 0; k < 2; ++k) \
;         acc[ai][bj][m][n] = __builtin_amdgcn_mfma_f32_16x16x32_bf16(Bt[n][k], At[m][k], acc[ai][bj][m][n], 0, 0, 0); __builtin_amdgcn_s_setprio(0); } while (0)
; #define PG8_WAIT_V(n) asm volatile("s_waitcnt vmcnt(" #n ")" ::: "memory")
; #define PG8_WAIT_L(n) asm volatile("s_waitcnt lgkmcnt(" #n ")" ::: "memory")
; #define PG8_BAR __builtin_amdgcn_s_barrier()
; #define PG8_SCHED __builtin_amdgcn_sched_barrier(0)
; template <class Epi, class Sched, bool ALIGN_EPI = false, bool SP2 = false, bool MIDHOOK = false>
; __device__ __forceinline__ void gemm_phase(PG8_LAS unsigned char* lds, const Gemm g, const Sched& S, const Epi& E) {
;     ...
;             PG8_LDA(At, 1, 1); PG8_STAGE(PG8_SB(1, 0), b3, voffB); PG8_STAGE(PG8_SB(1, 1), b3 + hstep, voffB); PG8_STAGE(PG8_SA(1, 0), a3, voffA);
;             PG8_WAIT_V(8); PG8_WAIT_L(0); PG8_BAR; PG8_MMA(1, 0, At, B0); PG8_MMA(1, 1, At, B1); PG8_BAR; PG8_SCHED;
;     ...
;     PG8_WAIT_V(0);
;     if constexpr (!ALIGN_EPI) { if (wr == 0) PG8_BAR; }
	s_mov_b32 m0, s46
	v_lshl_add_u64 v[152:153], v[152:153], 0, s[8:9]
	s_add_u32 s26, s26, 0x100080
	ds_read_b128 v[186:189], v143 offset:49152
	ds_read_b128 v[190:193], v143 offset:50176
	ds_read_b128 v[194:197], v143 offset:51200
	ds_read_b128 v[198:201], v143 offset:52224
	ds_read_b128 v[202:205], v143 offset:53248
	ds_read_b128 v[206:209], v143 offset:54272
	ds_read_b128 v[210:213], v143 offset:55296
	ds_read_b128 v[214:217], v143 offset:56320
	global_load_lds_dwordx4 v[152:153], off
	v_lshl_add_u64 v[152:153], v[218:219], 0, s[8:9]
	s_mov_b32 m0, s47
	s_addc_u32 s27, s27, 0
	global_load_lds_dwordx4 v[152:153], off
	v_lshl_add_u64 v[152:153], s[26:27], 0, v[130:131]
	s_mov_b32 m0, s48
	s_nop 0
	global_load_lds_dwordx4 v[152:153], off
	v_lshl_add_u64 v[152:153], s[26:27], 0, v[134:135]
	s_mov_b32 m0, s49
	s_nop 0
	global_load_lds_dwordx4 v[152:153], off
	v_lshl_add_u64 v[152:153], v[222:223], 0, s[8:9]
	s_mov_b32 m0, s35
	s_nop 0
	global_load_lds_dwordx4 v[152:153], off
	v_lshl_add_u64 v[152:153], v[224:225], 0, s[8:9]
	s_mov_b32 m0, s36
	s_nop 0
	global_load_lds_dwordx4 v[152:153], off
	s_waitcnt vmcnt(8)
	s_waitcnt lgkmcnt(0)
	s_barrier
	s_waitcnt lgkmcnt(0)
	v_mfma_f32_16x16x32_bf16 v[100:103], v[148:151], v[186:189], v[100:103]
	v_mfma_f32_16x16x32_bf16 v[96:99], v[162:165], v[186:189], v[96:99]
	v_mfma_f32_16x16x32_bf16 v[108:111], v[148:151], v[194:197], v[108:111]
	v_mfma_f32_16x16x32_bf16 v[104:107], v[162:165], v[194:197], v[104:107]
	v_mfma_f32_16x16x32_bf16 v[124:127], v[148:151], v[202:205], v[124:127]
	v_mfma_f32_16x16x32_bf16 v[112:115], v[162:165], v[202:205], v[112:115]
	v_mfma_f32_16x16x32_bf16 v[120:123], v[148:151], v[210:213], v[120:123]
	v_mfma_f32_16x16x32_bf16 v[116:119], v[162:165], v[210:213], v[116:119]
	v_mfma_f32_16x16x32_bf16 v[100:103], v[158:161], v[190:193], v[100:103]
	v_mfma_f32_16x16x32_bf16 v[96:99], v[166:169], v[190:193], v[96:99]
	v_mfma_f32_16x16x32_bf16 v[108:111], v[158:161], v[198:201], v[108:111]
	v_mfma_f32_16x16x32_bf16 v[104:107], v[166:169], v[198:201], v[104:107]
	v_mfma_f32_16x16x32_bf16 v[124:127], v[158:161], v[206:209], v[124:127]
	v_mfma_f32_16x16x32_bf16 v[112:115], v[166:169], v[206:209], v[112:115]
	v_mfma_f32_16x16x32_bf16 v[120:123], v[158:161], v[214:217], v[120:123]
	v_mfma_f32_16x16x32_bf16 v[116:119], v[166:169], v[214:217], v[116:119]
	v_mfma_f32_16x16x32_bf16 v[36:39], v[170:173], v[186:189], v[36:39]
	v_mfma_f32_16x16x32_bf16 v[32:35], v[178:181], v[186:189], v[32:35]
	v_mfma_f32_16x16x32_bf16 v[44:47], v[170:173], v[194:197], v[44:47]
	v_mfma_f32_16x16x32_bf16 v[40:43], v[178:181], v[194:197], v[40:43]
	v_mfma_f32_16x16x32_bf16 v[60:63], v[170:173], v[202:205], v[60:63]
	v_mfma_f32_16x16x32_bf16 v[56:59], v[178:181], v[202:205], v[56:59]
	v_mfma_f32_16x16x32_bf16 v[76:79], v[170:173], v[210:213], v[76:79]
	v_mfma_f32_16x16x32_bf16 v[72:75], v[178:181], v[210:213], v[72:75]
	v_mfma_f32_16x16x32_bf16 v[36:39], v[174:177], v[190:193], v[36:39]
	v_mfma_f32_16x16x32_bf16 v[32:35], v[182:185], v[190:193], v[32:35]
	v_mfma_f32_16x16x32_bf16 v[44:47], v[174:177], v[198:201], v[44:47]
	v_mfma_f32_16x16x32_bf16 v[40:43], v[182:185], v[198:201], v[40:43]
	v_mfma_f32_16x16x32_bf16 v[60:63], v[174:177], v[206:209], v[60:63]
	v_mfma_f32_16x16x32_bf16 v[56:59], v[182:185], v[206:209], v[56:59]
	v_mfma_f32_16x16x32_bf16 v[76:79], v[174:177], v[214:217], v[76:79]
	v_mfma_f32_16x16x32_bf16 v[72:75], v[182:185], v[214:217], v[72:75]
	s_barrier
	s_add_i32 s39, s39, 2
	s_add_u32 s24, s24, 0x100
	s_addc_u32 s25, s25, 0
	s_cmp_lt_u32 s39, 62
	s_cbranch_scc1 .LBB0_4175
	s_waitcnt vmcnt(0)
	s_cmp_gt_u32 s84, 3
	s_cbranch_scc1 .LBB0_4178
	s_barrier

; #define PG8_STAGE(bufoff, gbase, voff) do { _Pragma("unroll") for (int _i = 0; _i < 2; ++_i) \
;         __builtin_amdgcn_global_load_lds((const unsigned*)((const char*)(gbase) + (voff)[_i]), (PG8_LAS unsigned*)(lds + (bufoff) + ldsw + _i * 8192), 16, 0, 0); } while (0)
; #define PG8_LDA(dst, b, h) do { _Pragma("unroll") for (int m = 0; m < 4; ++m) _Pragma("unroll") for (int k = 0; k < 2; ++k) dst[m][k] = *(const PG8_LAS bf16x8*)(lds + PG8_SA(b, h) + aoff + m * 2048 + k * 1024); } while (0)
; #define PG8_LDB(dst, b, h) do { _Pragma("unroll") for (int n = 0; n < 2; ++n) _Pragma("unroll") for (int k = 0; k < 2; ++k) dst[n][k] = *(const PG8_LAS bf16x8*)(lds + PG8_SB(b, h) + boff + n * 2048 + k * 1024); } while (0)
; #define PG8_MMA(ai, bj, At, Bt) do { __builtin_amdgcn_s_setprio(1); _Pragma("unroll") for (int m = 0; m < 4; ++m) _Pragma("unroll") for (int n = 0; n < 2; ++n) _Pragma("unroll") for (int k = 0; k < 2; ++k) \
;         acc[ai][bj][m][n] = __builtin_amdgcn_mfma_f32_16x16x32_bf16(Bt[n][k], At[m][k], acc[ai][bj][m][n], 0, 0, 0); __builtin_amdgcn_s_setprio(0); } while (0)
; template <class Epi, class Sched, bool ALIGN_EPI = false, bool SP2 = false, bool MIDHOOK = false>
; __device__ __forceinline__ void gemm_phase(PG8_LAS unsigned char* lds, const Gemm g, const Sched& S, const Epi& E) {
;     ...
;         for (int t = 0; t < nt; t += 2) {
;             if constexpr (MIDHOOK) { if (t == nt / 2) E.mid(acc, cur, wr, wc, fr, fq); }
;             const bool last = (t == nt - 2);
;             const char* a1 = cA + (size_t)(t + 1) * kstep;
;             const char* a2 = last ? nA : cA + (size_t)(t + 2) * kstep; const char* b2 = last ? nB : cB + (size_t)(t + 2) * kstep;
;             const char* a3 = a2 + kstep; const char* b3 = b2 + kstep;
;             if (last && has_next) S.a_ready(nxt);
;             if constexpr (SP2) {
;             PG8_LDB(B0, 0, 0); PG8_LDB(B1, 0, 1); PG8_SCHED; PG8_LDA(At, 0, 0); PG8_STAGE(PG8_SA(1, 1), a1 + hstep, voffA);
;             PG8_WAIT_V(8); PG8_WAIT_L(0); PG8_BAR; PG8_MMA(0, 0, At, B0); PG8_MMA(0, 1, At, B1); PG8_BAR; PG8_SCHED;
;             PG8_LDA(At, 0, 1); PG8_STAGE(PG8_SB(0, 0), b2, voffB); PG8_STAGE(PG8_SB(0, 1), b2 + hstep, voffB); PG8_STAGE(PG8_SA(0, 0), a2, voffA);
;             PG8_WAIT_V(8); PG8_WAIT_L(0); PG8_BAR; PG8_MMA(1, 0, At, B0); PG8_MMA(1, 1, At, B1); PG8_BAR; PG8_SCHED;
.LBB0_4242:
	ds_read_b128 v[148:151], v140
	ds_read_b128 v[158:161], v140 offset:1024
	ds_read_b128 v[162:165], v140 offset:2048
	ds_read_b128 v[166:169], v140 offset:3072
	ds_read_b128 v[170:173], v141
	ds_read_b128 v[174:177], v141 offset:1024
	ds_read_b128 v[178:181], v141 offset:2048
	ds_read_b128 v[182:185], v141 offset:3072
	s_add_u32 s20, s12, s16
	s_addc_u32 s21, s13, s17
	s_add_u32 s20, s20, 0xe000100
	s_addc_u32 s21, s21, 0
	s_add_u32 s45, s31, s16
	s_addc_u32 s46, s33, s17
	s_cmpk_eq_i32 s16, 0x1f00
	s_cselect_b32 s23, s5, s21
	s_cselect_b32 s22, s4, s20
	s_cselect_b32 s21, s1, s46
	s_cselect_b32 s20, s0, s45
	s_mov_b32 m0, s35
	v_lshl_add_u64 v[152:153], v[136:137], 0, s[16:17]
	ds_read_b128 v[186:189], v142
	ds_read_b128 v[190:193], v142 offset:1024
	ds_read_b128 v[194:197], v142 offset:2048
	ds_read_b128 v[198:201], v142 offset:3072
	ds_read_b128 v[202:205], v142 offset:4096
	ds_read_b128 v[206:209], v142 offset:5120
	ds_read_b128 v[210:213], v142 offset:6144
	ds_read_b128 v[214:217], v142 offset:7168
	global_load_lds_dwordx4 v[152:153], off
	v_lshl_add_u64 v[152:153], v[138:139], 0, s[16:17]
	s_mov_b32 m0, s36
	s_nop 0
	global_load_lds_dwordx4 v[152:153], off
	s_waitcnt vmcnt(8)
	s_waitcnt lgkmcnt(0)
	s_barrier
	s_waitcnt lgkmcnt(0)
	v_mfma_f32_16x16x32_bf16 v[52:55], v[148:151], v[186:189], v[52:55]
	v_mfma_f32_16x16x32_bf16 v[48:51], v[162:165], v[186:189], v[48:51]
	v_mfma_f32_16x16x32_bf16 v[68:71], v[148:151], v[194:197], v[68:71]
	v_mfma_f32_16x16x32_bf16 v[64:67], v[162:165], v[194:197], v[64:67]
	v_mfma_f32_16x16x32_bf16 v[84:87], v[148:151], v[202:205], v[84:87]
	v_mfma_f32_16x16x32_bf16 v[80:83], v[162:165], v[202:205], v[80:83]
	v_mfma_f32_16x16x32_bf16 v[92:95], v[148:151], v[210:213], v[92:95]
	v_mfma_f32_16x16x32_bf16 v[88:91], v[162:165], v[210:213], v[88:91]
	v_mfma_f32_16x16x32_bf16 v[52:55], v[158:161], v[190:193], v[52:55]
	v_mfma_f32_16x16x32_bf16 v[48:51], v[166:169], v[190:193], v[48:51]
	v_mfma_f32_16x16x32_bf16 v[68:71], v[158:161], v[198:201], v[68:71]
	v_mfma_f32_16x16x32_bf16 v[64:67], v[166:169], v[198:201], v[64:67]
	v_mfma_f32_16x16x32_bf16 v[84:87], v[158:161], v[206:209], v[84:87]
	v_mfma_f32_16x16x32_bf16 v[80:83], v[166:169], v[206:209], v[80:83]
	v_mfma_f32_16x16x32_bf16 v[92:95], v[158:161], v[214:217], v[92:95]
	v_mfma_f32_16x16x32_bf16 v[88:91], v[166:169], v[214:217], v[88:91]
	v_mfma_f32_16x16x32_bf16 v[4:7], v[170:173], v[186:189], v[4:7]
	v_mfma_f32_16x16x32_bf16 v[0:3], v[178:181], v[186:189], v[0:3]
	v_mfma_f32_16x16x32_bf16 v[12:15], v[170:173], v[194:197], v[12:15]
	v_mfma_f32_16x16x32_bf16 v[8:11], v[178:181], v[194:197], v[8:11]
	v_mfma_f32_16x16x32_bf16 v[20:23], v[170:173], v[202:205], v[20:23]
	v_mfma_f32_16x16x32_bf16 v[16:19], v[178:181], v[202:205], v[16:19]
	v_mfma_f32_16x16x32_bf16 v[28:31], v[170:173], v[210:213], v[28:31]
	v_mfma_f32_16x16x32_bf16 v[24:27], v[178:181], v[210:213], v[24:27]
	v_mfma_f32_16x16x32_bf16 v[4:7], v[174:177], v[190:193], v[4:7]
	v_mfma_f32_16x16x32_bf16 v[0:3], v[182:185], v[190:193], v[0:3]
	v_mfma_f32_16x16x32_bf16 v[12:15], v[174:177], v[198:201], v[12:15]
	v_mfma_f32_16x16x32_bf16 v[8:11], v[182:185], v[198:201], v[8:11]
	v_mfma_f32_16x16x32_bf16 v[20:23], v[174:177], v[206:209], v[20:23]
	v_mfma_f32_16x16x32_bf16 v[16:19], v[182:185], v[206:209], v[16:19]
	v_mfma_f32_16x16x32_bf16 v[28:31], v[174:177], v[214:217], v[28:31]
	v_mfma_f32_16x16x32_bf16 v[24:27], v[182:185], v[214:217], v[24:27]
	s_barrier
	s_mov_b32 m0, s37
	v_lshl_add_u64 v[152:153], s[20:21], 0, v[130:131]
	s_add_u32 s46, s20, 0x100000
	ds_read_b128 v[186:189], v142 offset:16384
	ds_read_b128 v[190:193], v142 offset:17408
	ds_read_b128 v[194:197], v142 offset:18432
	ds_read_b128 v[198:201], v142 offset:19456
	ds_read_b128 v[202:205], v142 offset:20480
	ds_read_b128 v[206:209], v142 offset:21504
	ds_read_b128 v[210:213], v142 offset:22528
	ds_read_b128 v[214:217], v142 offset:23552
	global_load_lds_dwordx4 v[152:153], off
	v_lshl_add_u64 v[218:219], s[20:21], 0, v[134:135]
	s_mov_b32 m0, s38
	s_addc_u32 s47, s21, 0
	global_load_lds_dwordx4 v[218:219], off
	v_lshl_add_u64 v[222:223], s[46:47], 0, v[130:131]
	s_mov_b32 m0, s39
	v_lshl_add_u64 v[224:225], s[22:23], 0, v[132:133]
	global_load_lds_dwordx4 v[222:223], off
	v_lshl_add_u64 v[222:223], s[46:47], 0, v[134:135]
	s_mov_b32 m0, s40
	s_nop 0
	global_load_lds_dwordx4 v[222:223], off
	v_lshl_add_u64 v[222:223], s[22:23], 0, v[128:129]
	s_mov_b32 m0, s25
	s_nop 0
	global_load_lds_dwordx4 v[222:223], off
	s_mov_b32 m0, s26
	s_nop 0
	global_load_lds_dwordx4 v[224:225], off
	s_waitcnt vmcnt(8)
	s_waitcnt lgkmcnt(0)
	s_barrier
; #define PG8_STAGE(bufoff, gbase, voff) do { _Pragma("unroll") for (int _i = 0; _i < 2; ++_i) \
;         __builtin_amdgcn_global_load_lds((const unsigned*)((const char*)(gbase) + (voff)[_i]), (PG8_LAS unsigned*)(lds + (bufoff) + ldsw + _i * 8192), 16, 0, 0); } while (0)
; #define PG8_LDA(dst, b, h) do { _Pragma("unroll") for (int m = 0; m < 4; ++m) _Pragma("unroll") for (int k = 0; k < 2; ++k) dst[m][k] = *(const PG8_LAS bf16x8*)(lds + PG8_SA(b, h) + aoff + m * 2048 + k * 1024); } while (0)
; #define PG8_LDB(dst, b, h) do { _Pragma("unroll") for (int n = 0; n < 2; ++n) _Pragma("unroll") for (int k = 0; k < 2; ++k) dst[n][k] = *(const PG8_LAS bf16x8*)(lds + PG8_SB(b, h) + boff + n * 2048 + k * 1024); } while (0)
; #define PG8_MMA(ai, bj, At, Bt) do { __builtin_amdgcn_s_setprio(1); _Pragma("unroll") for (int m = 0; m < 4; ++m) _Pragma("unroll") for (int n = 0; n < 2; ++n) _Pragma("unroll") for (int k = 0; k < 2; ++k) \
;         acc[ai][bj][m][n] = __builtin_amdgcn_mfma_f32_16x16x32_bf16(Bt[n][k], At[m][k], acc[ai][bj][m][n], 0, 0, 0); __builtin_amdgcn_s_setprio(0); } while (0)
; #define PG8_WAIT_V(n) asm volatile("s_waitcnt vmcnt(" #n ")" ::: "memory")
; #define PG8_WAIT_L(n) asm volatile("s_waitcnt lgkmcnt(" #n ")" ::: "memory")
; #define PG8_BAR __builtin_amdgcn_s_barrier()
; #define PG8_SCHED __builtin_amdgcn_sched_barrier(0)
; template <class Epi, class Sched, bool ALIGN_EPI = false, bool SP2 = false, bool MIDHOOK = false>
; __device__ __forceinline__ void gemm_phase(PG8_LAS unsigned char* lds, const Gemm g, const Sched& S, const Epi& E) {
;     ...
;             PG8_WAIT_V(8); PG8_WAIT_L(0); PG8_BAR; PG8_MMA(1, 0, At, B0); PG8_MMA(1, 1, At, B1); PG8_BAR; PG8_SCHED;
;             PG8_LDB(B0, 1, 0); PG8_LDB(B1, 1, 1); PG8_SCHED; PG8_LDA(At, 1, 0); PG8_STAGE(PG8_SA(0, 1), a2 + hstep, voffA);
;             PG8_WAIT_V(8); PG8_WAIT_L(0); PG8_BAR; PG8_MMA(0, 0, At, B0); PG8_MMA(0, 1, At, B1); PG8_BAR; PG8_SCHED;
;             PG8_LDA(At, 1, 1); PG8_STAGE(PG8_SB(1, 0), b3, voffB); PG8_STAGE(PG8_SB(1, 1), b3 + hstep, voffB); PG8_STAGE(PG8_SA(1, 0), a3, voffA);
;             PG8_WAIT_V(8); PG8_WAIT_L(0); PG8_BAR; PG8_MMA(1, 0, At, B0); PG8_MMA(1, 1, At, B1); PG8_BAR; PG8_SCHED;
	s_waitcnt lgkmcnt(0)
	v_mfma_f32_16x16x32_bf16 v[100:103], v[148:151], v[186:189], v[100:103]
	v_mfma_f32_16x16x32_bf16 v[96:99], v[162:165], v[186:189], v[96:99]
	v_mfma_f32_16x16x32_bf16 v[108:111], v[148:151], v[194:197], v[108:111]
	v_mfma_f32_16x16x32_bf16 v[104:107], v[162:165], v[194:197], v[104:107]
	v_mfma_f32_16x16x32_bf16 v[124:127], v[148:151], v[202:205], v[124:127]
	v_mfma_f32_16x16x32_bf16 v[112:115], v[162:165], v[202:205], v[112:115]
	v_mfma_f32_16x16x32_bf16 v[120:123], v[148:151], v[210:213], v[120:123]
	v_mfma_f32_16x16x32_bf16 v[116:119], v[162:165], v[210:213], v[116:119]
	v_mfma_f32_16x16x32_bf16 v[100:103], v[158:161], v[190:193], v[100:103]
	v_mfma_f32_16x16x32_bf16 v[96:99], v[166:169], v[190:193], v[96:99]
	v_mfma_f32_16x16x32_bf16 v[108:111], v[158:161], v[198:201], v[108:111]
	v_mfma_f32_16x16x32_bf16 v[104:107], v[166:169], v[198:201], v[104:107]
	v_mfma_f32_16x16x32_bf16 v[124:127], v[158:161], v[206:209], v[124:127]
	v_mfma_f32_16x16x32_bf16 v[112:115], v[166:169], v[206:209], v[112:115]
	v_mfma_f32_16x16x32_bf16 v[120:123], v[158:161], v[214:217], v[120:123]
	v_mfma_f32_16x16x32_bf16 v[116:119], v[166:169], v[214:217], v[116:119]
	v_mfma_f32_16x16x32_bf16 v[36:39], v[170:173], v[186:189], v[36:39]
	v_mfma_f32_16x16x32_bf16 v[32:35], v[178:181], v[186:189], v[32:35]
	v_mfma_f32_16x16x32_bf16 v[44:47], v[170:173], v[194:197], v[44:47]
	v_mfma_f32_16x16x32_bf16 v[40:43], v[178:181], v[194:197], v[40:43]
	v_mfma_f32_16x16x32_bf16 v[60:63], v[170:173], v[202:205], v[60:63]
	v_mfma_f32_16x16x32_bf16 v[56:59], v[178:181], v[202:205], v[56:59]
	v_mfma_f32_16x16x32_bf16 v[76:79], v[170:173], v[210:213], v[76:79]
	v_mfma_f32_16x16x32_bf16 v[72:75], v[178:181], v[210:213], v[72:75]
	v_mfma_f32_16x16x32_bf16 v[36:39], v[174:177], v[190:193], v[36:39]
	v_mfma_f32_16x16x32_bf16 v[32:35], v[182:185], v[190:193], v[32:35]
	v_mfma_f32_16x16x32_bf16 v[44:47], v[174:177], v[198:201], v[44:47]
	v_mfma_f32_16x16x32_bf16 v[40:43], v[182:185], v[198:201], v[40:43]
	v_mfma_f32_16x16x32_bf16 v[60:63], v[174:177], v[206:209], v[60:63]
	v_mfma_f32_16x16x32_bf16 v[56:59], v[182:185], v[206:209], v[56:59]
	v_mfma_f32_16x16x32_bf16 v[76:79], v[174:177], v[214:217], v[76:79]
	v_mfma_f32_16x16x32_bf16 v[72:75], v[182:185], v[214:217], v[72:75]
	s_barrier
	ds_read_b128 v[148:151], v143
	ds_read_b128 v[158:161], v143 offset:1024
	ds_read_b128 v[162:165], v143 offset:2048
	ds_read_b128 v[166:169], v143 offset:3072
	ds_read_b128 v[170:173], v144
	ds_read_b128 v[174:177], v144 offset:1024
	ds_read_b128 v[178:181], v144 offset:2048
	ds_read_b128 v[182:185], v144 offset:3072
	s_add_u32 s22, s22, 0x100000
	s_addc_u32 s23, s23, 0
	s_mov_b32 m0, s27
	v_lshl_add_u64 v[226:227], s[22:23], 0, v[128:129]
	ds_read_b128 v[186:189], v142 offset:32768
	ds_read_b128 v[190:193], v142 offset:33792
	ds_read_b128 v[194:197], v142 offset:34816
	ds_read_b128 v[198:201], v142 offset:35840
	ds_read_b128 v[202:205], v142 offset:36864
	ds_read_b128 v[206:209], v142 offset:37888
	ds_read_b128 v[210:213], v142 offset:38912
	ds_read_b128 v[214:217], v142 offset:39936
	global_load_lds_dwordx4 v[226:227], off
	v_lshl_add_u64 v[226:227], s[22:23], 0, v[132:133]
	s_mov_b32 m0, s28
	s_nop 0
	global_load_lds_dwordx4 v[226:227], off
	s_waitcnt vmcnt(8)
	s_waitcnt lgkmcnt(0)
	s_barrier
	s_waitcnt lgkmcnt(0)
	v_mfma_f32_16x16x32_bf16 v[52:55], v[148:151], v[186:189], v[52:55]
	v_mfma_f32_16x16x32_bf16 v[48:51], v[162:165], v[186:189], v[48:51]
	v_mfma_f32_16x16x32_bf16 v[68:71], v[148:151], v[194:197], v[68:71]
	v_mfma_f32_16x16x32_bf16 v[64:67], v[162:165], v[194:197], v[64:67]
	v_mfma_f32_16x16x32_bf16 v[84:87], v[148:151], v[202:205], v[84:87]
	v_mfma_f32_16x16x32_bf16 v[80:83], v[162:165], v[202:205], v[80:83]
	v_mfma_f32_16x16x32_bf16 v[92:95], v[148:151], v[210:213], v[92:95]
	v_mfma_f32_16x16x32_bf16 v[88:91], v[162:165], v[210:213], v[88:91]
	v_mfma_f32_16x16x32_bf16 v[52:55], v[158:161], v[190:193], v[52:55]
	v_mfma_f32_16x16x32_bf16 v[48:51], v[166:169], v[190:193], v[48:51]
	v_mfma_f32_16x16x32_bf16 v[68:71], v[158:161], v[198:201], v[68:71]
	v_mfma_f32_16x16x32_bf16 v[64:67], v[166:169], v[198:201], v[64:67]
	v_mfma_f32_16x16x32_bf16 v[84:87], v[158:161], v[206:209], v[84:87]
	v_mfma_f32_16x16x32_bf16 v[80:83], v[166:169], v[206:209], v[80:83]
	v_mfma_f32_16x16x32_bf16 v[92:95], v[158:161], v[214:217], v[92:95]
	v_mfma_f32_16x16x32_bf16 v[88:91], v[166:169], v[214:217], v[88:91]
	v_mfma_f32_16x16x32_bf16 v[4:7], v[170:173], v[186:189], v[4:7]
	v_mfma_f32_16x16x32_bf16 v[0:3], v[178:181], v[186:189], v[0:3]
	v_mfma_f32_16x16x32_bf16 v[12:15], v[170:173], v[194:197], v[12:15]
	v_mfma_f32_16x16x32_bf16 v[8:11], v[178:181], v[194:197], v[8:11]
	v_mfma_f32_16x16x32_bf16 v[20:23], v[170:173], v[202:205], v[20:23]
	v_mfma_f32_16x16x32_bf16 v[16:19], v[178:181], v[202:205], v[16:19]
	v_mfma_f32_16x16x32_bf16 v[28:31], v[170:173], v[210:213], v[28:31]
	v_mfma_f32_16x16x32_bf16 v[24:27], v[178:181], v[210:213], v[24:27]
	v_mfma_f32_16x16x32_bf16 v[4:7], v[174:177], v[190:193], v[4:7]
	v_mfma_f32_16x16x32_bf16 v[0:3], v[182:185], v[190:193], v[0:3]
	v_mfma_f32_16x16x32_bf16 v[12:15], v[174:177], v[198:201], v[12:15]
	v_mfma_f32_16x16x32_bf16 v[8:11], v[182:185], v[198:201], v[8:11]
	v_mfma_f32_16x16x32_bf16 v[20:23], v[174:177], v[206:209], v[20:23]
	v_mfma_f32_16x16x32_bf16 v[16:19], v[182:185], v[206:209], v[16:19]
	v_mfma_f32_16x16x32_bf16 v[28:31], v[174:177], v[214:217], v[28:31]
	v_mfma_f32_16x16x32_bf16 v[24:27], v[182:185], v[214:217], v[24:27]
	s_barrier
; #define PG8_STAGE(bufoff, gbase, voff) do { _Pragma("unroll") for (int _i = 0; _i < 2; ++_i) \
;         __builtin_amdgcn_global_load_lds((const unsigned*)((const char*)(gbase) + (voff)[_i]), (PG8_LAS unsigned*)(lds + (bufoff) + ldsw + _i * 8192), 16, 0, 0); } while (0)
; #define PG8_LDA(dst, b, h) do { _Pragma("unroll") for (int m = 0; m < 4; ++m) _Pragma("unroll") for (int k = 0; k < 2; ++k) dst[m][k] = *(const PG8_LAS bf16x8*)(lds + PG8_SA(b, h) + aoff + m * 2048 + k * 1024); } while (0)
; #define PG8_MMA(ai, bj, At, Bt) do { __builtin_amdgcn_s_setprio(1); _Pragma("unroll") for (int m = 0; m < 4; ++m) _Pragma("unroll") for (int n = 0; n < 2; ++n) _Pragma("unroll") for (int k = 0; k < 2; ++k) \
;         acc[ai][bj][m][n] = __builtin_amdgcn_mfma_f32_16x16x32_bf16(Bt[n][k], At[m][k], acc[ai][bj][m][n], 0, 0, 0); __builtin_amdgcn_s_setprio(0); } while (0)
; #define PG8_WAIT_V(n) asm volatile("s_waitcnt vmcnt(" #n ")" ::: "memory")
; #define PG8_WAIT_L(n) asm volatile("s_waitcnt lgkmcnt(" #n ")" ::: "memory")
; #define PG8_BAR __builtin_amdgcn_s_barrier()
; #define PG8_SCHED __builtin_amdgcn_sched_barrier(0)
; template <class Epi, class Sched, bool ALIGN_EPI = false, bool SP2 = false, bool MIDHOOK = false>
; __device__ __forceinline__ void gemm_phase(PG8_LAS unsigned char* lds, const Gemm g, const Sched& S, const Epi& E) {
;     ...
;             PG8_LDA(At, 1, 1); PG8_STAGE(PG8_SB(1, 0), b3, voffB); PG8_STAGE(PG8_SB(1, 1), b3 + hstep, voffB); PG8_STAGE(PG8_SA(1, 0), a3, voffA);
;             PG8_WAIT_V(8); PG8_WAIT_L(0); PG8_BAR; PG8_MMA(1, 0, At, B0); PG8_MMA(1, 1, At, B1); PG8_BAR; PG8_SCHED;
;     ...
;     PG8_WAIT_V(0);
;     if constexpr (!ALIGN_EPI) { if (wr == 0) PG8_BAR; }
	s_mov_b32 m0, s41
	v_lshl_add_u64 v[152:153], v[152:153], 0, s[8:9]
	s_add_u32 s20, s20, 0x100080
	ds_read_b128 v[186:189], v142 offset:49152
	ds_read_b128 v[190:193], v142 offset:50176
	ds_read_b128 v[194:197], v142 offset:51200
	ds_read_b128 v[198:201], v142 offset:52224
	ds_read_b128 v[202:205], v142 offset:53248
	ds_read_b128 v[206:209], v142 offset:54272
	ds_read_b128 v[210:213], v142 offset:55296
	ds_read_b128 v[214:217], v142 offset:56320
	global_load_lds_dwordx4 v[152:153], off
	v_lshl_add_u64 v[152:153], v[218:219], 0, s[8:9]
	s_mov_b32 m0, s42
	s_addc_u32 s21, s21, 0
	global_load_lds_dwordx4 v[152:153], off
	v_lshl_add_u64 v[152:153], s[20:21], 0, v[130:131]
	s_mov_b32 m0, s43
	s_nop 0
	global_load_lds_dwordx4 v[152:153], off
	v_lshl_add_u64 v[152:153], s[20:21], 0, v[134:135]
	s_mov_b32 m0, s44
	s_nop 0
	global_load_lds_dwordx4 v[152:153], off
	v_lshl_add_u64 v[152:153], v[222:223], 0, s[8:9]
	s_mov_b32 m0, s29
	s_nop 0
	global_load_lds_dwordx4 v[152:153], off
	v_lshl_add_u64 v[152:153], v[224:225], 0, s[8:9]
	s_mov_b32 m0, s30
	s_nop 0
	global_load_lds_dwordx4 v[152:153], off
	s_waitcnt vmcnt(8)
	s_waitcnt lgkmcnt(0)
	s_barrier
	s_waitcnt lgkmcnt(0)
	v_mfma_f32_16x16x32_bf16 v[100:103], v[148:151], v[186:189], v[100:103]
	v_mfma_f32_16x16x32_bf16 v[96:99], v[162:165], v[186:189], v[96:99]
	v_mfma_f32_16x16x32_bf16 v[108:111], v[148:151], v[194:197], v[108:111]
	v_mfma_f32_16x16x32_bf16 v[104:107], v[162:165], v[194:197], v[104:107]
	v_mfma_f32_16x16x32_bf16 v[124:127], v[148:151], v[202:205], v[124:127]
	v_mfma_f32_16x16x32_bf16 v[112:115], v[162:165], v[202:205], v[112:115]
	v_mfma_f32_16x16x32_bf16 v[120:123], v[148:151], v[210:213], v[120:123]
	v_mfma_f32_16x16x32_bf16 v[116:119], v[162:165], v[210:213], v[116:119]
	v_mfma_f32_16x16x32_bf16 v[100:103], v[158:161], v[190:193], v[100:103]
	v_mfma_f32_16x16x32_bf16 v[96:99], v[166:169], v[190:193], v[96:99]
	v_mfma_f32_16x16x32_bf16 v[108:111], v[158:161], v[198:201], v[108:111]
	v_mfma_f32_16x16x32_bf16 v[104:107], v[166:169], v[198:201], v[104:107]
	v_mfma_f32_16x16x32_bf16 v[124:127], v[158:161], v[206:209], v[124:127]
	v_mfma_f32_16x16x32_bf16 v[112:115], v[166:169], v[206:209], v[112:115]
	v_mfma_f32_16x16x32_bf16 v[120:123], v[158:161], v[214:217], v[120:123]
	v_mfma_f32_16x16x32_bf16 v[116:119], v[166:169], v[214:217], v[116:119]
	v_mfma_f32_16x16x32_bf16 v[36:39], v[170:173], v[186:189], v[36:39]
	v_mfma_f32_16x16x32_bf16 v[32:35], v[178:181], v[186:189], v[32:35]
	v_mfma_f32_16x16x32_bf16 v[44:47], v[170:173], v[194:197], v[44:47]
	v_mfma_f32_16x16x32_bf16 v[40:43], v[178:181], v[194:197], v[40:43]
	v_mfma_f32_16x16x32_bf16 v[60:63], v[170:173], v[202:205], v[60:63]
	v_mfma_f32_16x16x32_bf16 v[56:59], v[178:181], v[202:205], v[56:59]
	v_mfma_f32_16x16x32_bf16 v[76:79], v[170:173], v[210:213], v[76:79]
	v_mfma_f32_16x16x32_bf16 v[72:75], v[178:181], v[210:213], v[72:75]
	v_mfma_f32_16x16x32_bf16 v[36:39], v[174:177], v[190:193], v[36:39]
	v_mfma_f32_16x16x32_bf16 v[32:35], v[182:185], v[190:193], v[32:35]
	v_mfma_f32_16x16x32_bf16 v[44:47], v[174:177], v[198:201], v[44:47]
	v_mfma_f32_16x16x32_bf16 v[40:43], v[182:185], v[198:201], v[40:43]
	v_mfma_f32_16x16x32_bf16 v[60:63], v[174:177], v[206:209], v[60:63]
	v_mfma_f32_16x16x32_bf16 v[56:59], v[182:185], v[206:209], v[56:59]
	v_mfma_f32_16x16x32_bf16 v[76:79], v[174:177], v[214:217], v[76:79]
	v_mfma_f32_16x16x32_bf16 v[72:75], v[182:185], v[214:217], v[72:75]
	s_barrier
	s_add_i32 s34, s34, 2
	s_add_u32 s16, s16, 0x100
	s_addc_u32 s17, s17, 0
	s_cmp_lt_u32 s34, 62
	s_cbranch_scc1 .LBB0_4242
	s_waitcnt vmcnt(0)
	s_cmp_gt_u32 s84, 3
	s_cbranch_scc1 .LBB0_4245
	s_barrier
